# K-loop A-fragment ds_reads address the per-phase LDS base (biased +0x10000 once) through the offset field: 4 VALU adds and 4 scalar constant moves per iteration removed
# speedup vs baseline: 1.0326x; 1.0078x over previous
.LBB0_117:
	s_add_u32 s0, s26, 0x2efe000
	s_addc_u32 s1, s25, 0
	s_add_u32 s10, s26, 0x2f16000
	s_addc_u32 s11, s25, 0
	v_bfe_u32 v163, v11, 4, 2
	s_add_u32 s41, s26, 0x2f58800
	v_and_b32_e32 v162, 15, v11
	v_lshlrev_b32_e32 v15, 4, v163
	v_lshlrev_b32_e32 v11, 2, v11
	s_addc_u32 s42, s25, 0
	s_lshl_b32 s43, s4, 6
	v_lshl_or_b32 v15, v162, 6, v15
	s_lshl_b32 s4, s4, 13
	v_and_b32_e32 v11, 32, v11
	v_bitop3_b32 v16, v15, s4, v11 bitop3:0xde
	s_lshl_b32 s4, s5, 5
	s_and_b32 s44, s4, 0x60
	s_add_i32 m0, s37, 0x18000
	v_lshl_add_u64 v[6:7], v[6:7], 0, s[78:79]
	s_lshl_b32 s4, s44, 7
	s_waitcnt vmcnt(4)
	s_barrier
	global_load_lds_dwordx4 v[6:7], off
	v_lshl_add_u64 v[4:5], v[4:5], 0, s[78:79]
	s_add_i32 m0, s37, 0x1a000
	s_add_i32 s45, s37, 0x8000
	s_add_i32 s46, s37, 0xa000
	v_bitop3_b32 v164, s4, v15, v11 bitop3:0xf6
	v_add_u32_e32 v164, 0x10000, v164
	global_load_lds_dwordx4 v[4:5], off
	v_lshl_add_u64 v[2:3], v[2:3], 0, s[78:79]
	s_mov_b32 m0, s45
	s_add_u32 s4, s2, 0x40080
	global_load_lds_dwordx4 v[2:3], off
	v_lshl_add_u64 v[0:1], v[0:1], 0, s[78:79]
	s_mov_b32 m0, s46
	s_addc_u32 s5, s3, 0
	global_load_lds_dwordx4 v[0:1], off
	s_add_i32 m0, s37, 0x1c000
	v_lshl_add_u64 v[0:1], s[4:5], 0, v[168:169]
	global_load_lds_dwordx4 v[0:1], off
	v_lshl_add_u64 v[0:1], s[4:5], 0, v[148:149]
	s_add_i32 m0, s37, 0x1e000
	s_ashr_i32 s47, s27, 31
	global_load_lds_dwordx4 v[0:1], off
	v_lshlrev_b32_e32 v0, 14, v8
	v_and_b32_e32 v0, 0xffff8000, v0
	v_lshl_add_u32 v0, v9, 11, v0
	v_and_b32_e32 v1, 1, v8
	v_lshl_or_b32 v0, v1, 6, v0
	v_lshl_add_u32 v150, v10, 1, v0
	v_lshlrev_b32_e32 v0, 14, v12
	v_and_b32_e32 v0, 0xffff8000, v0
	s_waitcnt vmcnt(6)
	v_lshl_add_u32 v0, v13, 11, v0
	v_and_b32_e32 v1, 1, v12
	v_lshl_or_b32 v0, v1, 6, v0
	v_mov_b32_e32 v151, v169
	v_lshl_add_u32 v152, v14, 1, v0
	v_mov_b32_e32 v153, v169
	s_mov_b32 s48, 0
	v_add_u32_e32 v165, 0, v16
	s_lshl_b32 s49, s44, 2
	s_barrier
	s_branch .LBB0_120

.LBB0_122:
	v_mov_b64_e32 v[0:1], 0x180
	s_ashr_i32 s15, s14, 31
	v_cmp_lt_i64_e32 vcc, s[16:17], v[0:1]
	s_lshl_b64 s[16:17], s[14:15], 19
	s_add_u32 s16, s30, s16
	s_addc_u32 s17, s31, s17
	s_and_b64 s[18:19], vcc, exec
	s_cselect_b32 s7, s17, s21
	s_cselect_b32 s9, s16, s20
	s_ashr_i32 s13, s12, 31
	s_lshl_b64 s[18:19], s[12:13], 19
	s_add_u32 s18, s34, s18
	s_addc_u32 s19, s35, s19
	s_and_b64 s[22:23], vcc, exec
	s_cselect_b32 s13, s19, s3
	s_cselect_b32 s15, s18, s2
	s_add_u32 s20, s20, 0x40080
	s_addc_u32 s21, s21, 0
	s_add_u32 s50, s2, 0x100
	s_addc_u32 s51, s3, 0
	s_mov_b32 s52, -2
	s_add_u32 s2, s20, 0xfffc0080
	s_addc_u32 s3, s21, -1
	ds_read_b128 v[24:27], v164
	ds_read_b128 v[28:31], v164 offset:1024
	ds_read_b128 v[32:35], v164 offset:2048
	ds_read_b128 v[36:39], v164 offset:3072
	s_cmp_eq_u32 s52, 12
	s_cselect_b32 s23, s7, s3
	s_cselect_b32 s22, s9, s2
	s_cselect_b32 s3, s13, s51
	s_cselect_b32 s2, s15, s50
	s_add_i32 m0, s37, 0xc000
	ds_read_b128 v[154:157], v165
	ds_read_b128 v[158:161], v165 offset:1024
	ds_read_b128 v[180:183], v165 offset:2048
	ds_read_b128 v[184:187], v165 offset:3072
	ds_read_b128 v[188:191], v165 offset:4096
	ds_read_b128 v[192:195], v165 offset:5120
	ds_read_b128 v[196:199], v165 offset:6144
	global_load_lds_dwordx4 v150, s[20:21]
	s_add_i32 m0, s37, 0xe000
	ds_read_b128 v[200:203], v165 offset:7168
	global_load_lds_dwordx4 v152, s[20:21]
	s_waitcnt lgkmcnt(8)
	s_barrier
	s_waitcnt lgkmcnt(0)
	v_mfma_f32_16x16x32_bf16 v[140:143], v[24:27], v[154:157], 0
	v_mfma_f32_16x16x32_bf16 v[136:139], v[32:35], v[154:157], 0
	v_mfma_f32_16x16x32_bf16 v[124:127], v[24:27], v[180:183], 0
	v_mfma_f32_16x16x32_bf16 v[120:123], v[32:35], v[180:183], 0
	v_mfma_f32_16x16x32_bf16 v[108:111], v[24:27], v[188:191], 0
	v_mfma_f32_16x16x32_bf16 v[104:107], v[32:35], v[188:191], 0
	v_mfma_f32_16x16x32_bf16 v[92:95], v[24:27], v[196:199], 0
	v_mfma_f32_16x16x32_bf16 v[88:91], v[32:35], v[196:199], 0
	v_mfma_f32_16x16x32_bf16 v[140:143], v[28:31], v[158:161], v[140:143]
	v_mfma_f32_16x16x32_bf16 v[136:139], v[36:39], v[158:161], v[136:139]
	v_mfma_f32_16x16x32_bf16 v[124:127], v[28:31], v[184:187], v[124:127]
	v_mfma_f32_16x16x32_bf16 v[120:123], v[36:39], v[184:187], v[120:123]
	v_mfma_f32_16x16x32_bf16 v[108:111], v[28:31], v[192:195], v[108:111]
	v_mfma_f32_16x16x32_bf16 v[104:107], v[36:39], v[192:195], v[104:107]
	v_mfma_f32_16x16x32_bf16 v[92:95], v[28:31], v[200:203], v[92:95]
	v_mfma_f32_16x16x32_bf16 v[88:91], v[36:39], v[200:203], v[88:91]
	s_barrier
	s_add_i32 s53, s36, 0x10000
	ds_read_b128 v[204:207], v164 offset:16384
	ds_read_b128 v[208:211], v164 offset:17408
	ds_read_b128 v[212:215], v164 offset:18432
	ds_read_b128 v[216:219], v164 offset:19456
	s_mov_b32 m0, s53
	s_add_u32 s98, s2, 0x80
	s_addc_u32 s99, s3, 0
	global_load_lds_dwordx4 v168, s[2:3]
	s_add_i32 m0, s53, 0x2000
	s_nop 0
	global_load_lds_dwordx4 v148, s[2:3]
	s_barrier
	s_waitcnt lgkmcnt(0)
	v_mfma_f32_16x16x32_bf16 v[132:135], v[204:207], v[154:157], 0
	v_mfma_f32_16x16x32_bf16 v[128:131], v[212:215], v[154:157], 0
	v_mfma_f32_16x16x32_bf16 v[116:119], v[204:207], v[180:183], 0
	v_mfma_f32_16x16x32_bf16 v[112:115], v[212:215], v[180:183], 0
	v_mfma_f32_16x16x32_bf16 v[100:103], v[204:207], v[188:191], 0
	v_mfma_f32_16x16x32_bf16 v[96:99], v[212:215], v[188:191], 0
	v_mfma_f32_16x16x32_bf16 v[84:87], v[204:207], v[196:199], 0
	v_mfma_f32_16x16x32_bf16 v[80:83], v[212:215], v[196:199], 0
	v_mfma_f32_16x16x32_bf16 v[132:135], v[208:211], v[158:161], v[132:135]
	v_mfma_f32_16x16x32_bf16 v[128:131], v[216:219], v[158:161], v[128:131]
	v_mfma_f32_16x16x32_bf16 v[116:119], v[208:211], v[184:187], v[116:119]
	v_mfma_f32_16x16x32_bf16 v[112:115], v[216:219], v[184:187], v[112:115]
	v_mfma_f32_16x16x32_bf16 v[100:103], v[208:211], v[192:195], v[100:103]
	v_mfma_f32_16x16x32_bf16 v[96:99], v[216:219], v[192:195], v[96:99]
	v_mfma_f32_16x16x32_bf16 v[84:87], v[208:211], v[200:203], v[84:87]
	v_mfma_f32_16x16x32_bf16 v[80:83], v[216:219], v[200:203], v[80:83]
	s_mov_b32 m0, s37
	s_add_u32 s100, s22, 0x80
	s_addc_u32 s101, s23, 0
	s_barrier
	ds_read_b128 v[154:157], v165 offset:16384
	ds_read_b128 v[158:161], v165 offset:17408
	ds_read_b128 v[180:183], v165 offset:18432
	ds_read_b128 v[184:187], v165 offset:19456
	ds_read_b128 v[188:191], v165 offset:20480
	ds_read_b128 v[192:195], v165 offset:21504
	ds_read_b128 v[196:199], v165 offset:22528
	global_load_lds_dwordx4 v144, s[22:23]
	s_mov_b32 m0, s38
	ds_read_b128 v[200:203], v165 offset:23552
	global_load_lds_dwordx4 v146, s[22:23]
	s_barrier
	s_waitcnt lgkmcnt(0)
	v_mfma_f32_16x16x32_bf16 v[76:79], v[24:27], v[154:157], 0
	v_mfma_f32_16x16x32_bf16 v[72:75], v[32:35], v[154:157], 0
	v_mfma_f32_16x16x32_bf16 v[60:63], v[24:27], v[180:183], 0
	v_mfma_f32_16x16x32_bf16 v[56:59], v[32:35], v[180:183], 0
	v_mfma_f32_16x16x32_bf16 v[44:47], v[24:27], v[188:191], 0
	v_mfma_f32_16x16x32_bf16 v[40:43], v[32:35], v[188:191], 0
	v_mfma_f32_16x16x32_bf16 v[12:15], v[24:27], v[196:199], 0
	v_mfma_f32_16x16x32_bf16 v[8:11], v[32:35], v[196:199], 0
	v_mfma_f32_16x16x32_bf16 v[76:79], v[28:31], v[158:161], v[76:79]
	v_mfma_f32_16x16x32_bf16 v[72:75], v[36:39], v[158:161], v[72:75]
	v_mfma_f32_16x16x32_bf16 v[60:63], v[28:31], v[184:187], v[60:63]
	v_mfma_f32_16x16x32_bf16 v[56:59], v[36:39], v[184:187], v[56:59]
	v_mfma_f32_16x16x32_bf16 v[44:47], v[28:31], v[192:195], v[44:47]
	v_mfma_f32_16x16x32_bf16 v[40:43], v[36:39], v[192:195], v[40:43]
	v_mfma_f32_16x16x32_bf16 v[12:15], v[28:31], v[200:203], v[12:15]
	v_mfma_f32_16x16x32_bf16 v[8:11], v[36:39], v[200:203], v[8:11]
	s_barrier
	s_add_i32 s53, s36, 0x14000
	s_mov_b32 m0, s53
	s_add_u32 s54, s2, 0x40000
	s_addc_u32 s55, s3, 0
	global_load_lds_dwordx4 v168, s[54:55]
	s_add_i32 m0, s53, 0x2000
	s_nop 0
	global_load_lds_dwordx4 v148, s[54:55]
	s_waitcnt vmcnt(6)
	s_barrier
	v_mfma_f32_16x16x32_bf16 v[20:23], v[204:207], v[188:191], 0
	v_mfma_f32_16x16x32_bf16 v[16:19], v[212:215], v[188:191], 0
	v_mfma_f32_16x16x32_bf16 v[4:7], v[204:207], v[196:199], 0
	v_mfma_f32_16x16x32_bf16 v[0:3], v[212:215], v[196:199], 0
	v_mfma_f32_16x16x32_bf16 v[24:27], v[204:207], v[154:157], 0
	v_mfma_f32_16x16x32_bf16 v[28:31], v[212:215], v[154:157], 0
	v_mfma_f32_16x16x32_bf16 v[32:35], v[204:207], v[180:183], 0
	v_mfma_f32_16x16x32_bf16 v[36:39], v[212:215], v[180:183], 0
	v_mfma_f32_16x16x32_bf16 v[20:23], v[208:211], v[192:195], v[20:23]
	v_mfma_f32_16x16x32_bf16 v[16:19], v[216:219], v[192:195], v[16:19]
	v_mfma_f32_16x16x32_bf16 v[4:7], v[208:211], v[200:203], v[4:7]
	v_mfma_f32_16x16x32_bf16 v[0:3], v[216:219], v[200:203], v[0:3]
	v_mfma_f32_16x16x32_bf16 v[24:27], v[208:211], v[158:161], v[24:27]
	v_mfma_f32_16x16x32_bf16 v[28:31], v[216:219], v[158:161], v[28:31]
	v_mfma_f32_16x16x32_bf16 v[32:35], v[208:211], v[184:187], v[32:35]
	v_mfma_f32_16x16x32_bf16 v[36:39], v[216:219], v[184:187], v[36:39]
	s_barrier
	ds_read_b128 v[48:51], v164 offset:32768
	ds_read_b128 v[52:55], v164 offset:33792
	ds_read_b128 v[64:67], v164 offset:34816
	ds_read_b128 v[68:71], v164 offset:35840
	s_add_u32 s22, s22, 0x40000
	s_addc_u32 s23, s23, 0
	s_mov_b32 m0, s39
	ds_read_b128 v[154:157], v165 offset:32768
	ds_read_b128 v[158:161], v165 offset:33792
	ds_read_b128 v[180:183], v165 offset:34816
	ds_read_b128 v[184:187], v165 offset:35840
	ds_read_b128 v[188:191], v165 offset:36864
	ds_read_b128 v[192:195], v165 offset:37888
	ds_read_b128 v[196:199], v165 offset:38912
	global_load_lds_dwordx4 v144, s[22:23]
	s_mov_b32 m0, s40
	ds_read_b128 v[200:203], v165 offset:39936
	global_load_lds_dwordx4 v146, s[22:23]
	s_waitcnt lgkmcnt(8)
	s_barrier
	s_waitcnt lgkmcnt(0)
	v_mfma_f32_16x16x32_bf16 v[140:143], v[48:51], v[154:157], v[140:143]
	v_mfma_f32_16x16x32_bf16 v[136:139], v[64:67], v[154:157], v[136:139]
	v_mfma_f32_16x16x32_bf16 v[124:127], v[48:51], v[180:183], v[124:127]
	v_mfma_f32_16x16x32_bf16 v[120:123], v[64:67], v[180:183], v[120:123]
	v_mfma_f32_16x16x32_bf16 v[108:111], v[48:51], v[188:191], v[108:111]
	v_mfma_f32_16x16x32_bf16 v[104:107], v[64:67], v[188:191], v[104:107]
	v_mfma_f32_16x16x32_bf16 v[92:95], v[48:51], v[196:199], v[92:95]
	v_mfma_f32_16x16x32_bf16 v[88:91], v[64:67], v[196:199], v[88:91]
	v_mfma_f32_16x16x32_bf16 v[140:143], v[52:55], v[158:161], v[140:143]
	v_mfma_f32_16x16x32_bf16 v[136:139], v[68:71], v[158:161], v[136:139]
	v_mfma_f32_16x16x32_bf16 v[124:127], v[52:55], v[184:187], v[124:127]
	v_mfma_f32_16x16x32_bf16 v[120:123], v[68:71], v[184:187], v[120:123]
	v_mfma_f32_16x16x32_bf16 v[108:111], v[52:55], v[192:195], v[108:111]
	v_mfma_f32_16x16x32_bf16 v[104:107], v[68:71], v[192:195], v[104:107]
	v_mfma_f32_16x16x32_bf16 v[92:95], v[52:55], v[200:203], v[92:95]
	v_mfma_f32_16x16x32_bf16 v[88:91], v[68:71], v[200:203], v[88:91]
	s_barrier
	s_add_i32 s23, s36, 0x18000
	s_mov_b32 m0, s23
	ds_read_b128 v[204:207], v164 offset:49152
	ds_read_b128 v[208:211], v164 offset:50176
	ds_read_b128 v[212:215], v164 offset:51200
	global_load_lds_dwordx4 v168, s[98:99]
	s_add_i32 m0, s23, 0x2000
	ds_read_b128 v[216:219], v164 offset:52224
	global_load_lds_dwordx4 v148, s[98:99]
	s_barrier
	s_waitcnt lgkmcnt(0)
	v_mfma_f32_16x16x32_bf16 v[132:135], v[204:207], v[154:157], v[132:135]
	v_mfma_f32_16x16x32_bf16 v[128:131], v[212:215], v[154:157], v[128:131]
	v_mfma_f32_16x16x32_bf16 v[116:119], v[204:207], v[180:183], v[116:119]
	v_mfma_f32_16x16x32_bf16 v[112:115], v[212:215], v[180:183], v[112:115]
	v_mfma_f32_16x16x32_bf16 v[100:103], v[204:207], v[188:191], v[100:103]
	v_mfma_f32_16x16x32_bf16 v[96:99], v[212:215], v[188:191], v[96:99]
	v_mfma_f32_16x16x32_bf16 v[84:87], v[204:207], v[196:199], v[84:87]
	v_mfma_f32_16x16x32_bf16 v[80:83], v[212:215], v[196:199], v[80:83]
	v_mfma_f32_16x16x32_bf16 v[132:135], v[208:211], v[158:161], v[132:135]
	v_mfma_f32_16x16x32_bf16 v[128:131], v[216:219], v[158:161], v[128:131]
	v_mfma_f32_16x16x32_bf16 v[116:119], v[208:211], v[184:187], v[116:119]
	v_mfma_f32_16x16x32_bf16 v[112:115], v[216:219], v[184:187], v[112:115]
	v_mfma_f32_16x16x32_bf16 v[100:103], v[208:211], v[192:195], v[100:103]
	v_mfma_f32_16x16x32_bf16 v[96:99], v[216:219], v[192:195], v[96:99]
	v_mfma_f32_16x16x32_bf16 v[84:87], v[208:211], v[200:203], v[84:87]
	v_mfma_f32_16x16x32_bf16 v[80:83], v[216:219], v[200:203], v[80:83]
	s_mov_b32 m0, s45
	s_barrier
	ds_read_b128 v[154:157], v165 offset:49152
	ds_read_b128 v[158:161], v165 offset:50176
	ds_read_b128 v[180:183], v165 offset:51200
	ds_read_b128 v[184:187], v165 offset:52224
	ds_read_b128 v[188:191], v165 offset:53248
	ds_read_b128 v[192:195], v165 offset:54272
	ds_read_b128 v[196:199], v165 offset:55296
	global_load_lds_dwordx4 v144, s[100:101]
	s_mov_b32 m0, s46
	ds_read_b128 v[200:203], v165 offset:56320
	global_load_lds_dwordx4 v146, s[100:101]
	s_barrier
	s_waitcnt lgkmcnt(0)
	v_mfma_f32_16x16x32_bf16 v[76:79], v[48:51], v[154:157], v[76:79]
	v_mfma_f32_16x16x32_bf16 v[72:75], v[64:67], v[154:157], v[72:75]
	v_mfma_f32_16x16x32_bf16 v[60:63], v[48:51], v[180:183], v[60:63]
	v_mfma_f32_16x16x32_bf16 v[56:59], v[64:67], v[180:183], v[56:59]
	v_mfma_f32_16x16x32_bf16 v[44:47], v[48:51], v[188:191], v[44:47]
	v_mfma_f32_16x16x32_bf16 v[40:43], v[64:67], v[188:191], v[40:43]
	v_mfma_f32_16x16x32_bf16 v[12:15], v[48:51], v[196:199], v[12:15]
	v_mfma_f32_16x16x32_bf16 v[8:11], v[64:67], v[196:199], v[8:11]
	v_mfma_f32_16x16x32_bf16 v[76:79], v[52:55], v[158:161], v[76:79]
	v_mfma_f32_16x16x32_bf16 v[72:75], v[68:71], v[158:161], v[72:75]
	v_mfma_f32_16x16x32_bf16 v[60:63], v[52:55], v[184:187], v[60:63]
	v_mfma_f32_16x16x32_bf16 v[56:59], v[68:71], v[184:187], v[56:59]
	v_mfma_f32_16x16x32_bf16 v[44:47], v[52:55], v[192:195], v[44:47]
	v_mfma_f32_16x16x32_bf16 v[40:43], v[68:71], v[192:195], v[40:43]
	v_mfma_f32_16x16x32_bf16 v[12:15], v[52:55], v[200:203], v[12:15]
	v_mfma_f32_16x16x32_bf16 v[8:11], v[68:71], v[200:203], v[8:11]
	s_barrier
	s_add_i32 s22, s36, 0x1c000
	s_mov_b32 m0, s22
	s_add_u32 s2, s2, 0x40080
	s_addc_u32 s3, s3, 0
	global_load_lds_dwordx4 v168, s[2:3]
	s_add_i32 m0, s22, 0x2000
	s_nop 0
	global_load_lds_dwordx4 v148, s[2:3]
	s_waitcnt vmcnt(6)
	s_barrier
	v_mfma_f32_16x16x32_bf16 v[24:27], v[204:207], v[154:157], v[24:27]
	v_mfma_f32_16x16x32_bf16 v[68:71], v[208:211], v[158:161], v[24:27]
	v_mfma_f32_16x16x32_bf16 v[24:27], v[212:215], v[154:157], v[28:31]
	v_mfma_f32_16x16x32_bf16 v[64:67], v[216:219], v[158:161], v[24:27]
	v_mfma_f32_16x16x32_bf16 v[24:27], v[204:207], v[180:183], v[32:35]
	v_mfma_f32_16x16x32_bf16 v[52:55], v[208:211], v[184:187], v[24:27]
	v_mfma_f32_16x16x32_bf16 v[24:27], v[212:215], v[180:183], v[36:39]
	v_mfma_f32_16x16x32_bf16 v[20:23], v[204:207], v[188:191], v[20:23]
	v_mfma_f32_16x16x32_bf16 v[16:19], v[212:215], v[188:191], v[16:19]
	v_mfma_f32_16x16x32_bf16 v[4:7], v[204:207], v[196:199], v[4:7]
	v_mfma_f32_16x16x32_bf16 v[0:3], v[212:215], v[196:199], v[0:3]
	v_mfma_f32_16x16x32_bf16 v[48:51], v[216:219], v[184:187], v[24:27]
	v_mfma_f32_16x16x32_bf16 v[20:23], v[208:211], v[192:195], v[20:23]
	v_mfma_f32_16x16x32_bf16 v[16:19], v[216:219], v[192:195], v[16:19]
	v_mfma_f32_16x16x32_bf16 v[4:7], v[208:211], v[200:203], v[4:7]
	v_mfma_f32_16x16x32_bf16 v[0:3], v[216:219], v[200:203], v[0:3]
	s_add_i32 s52, s52, 2
	s_add_u32 s20, s20, 0x100
	s_addc_u32 s21, s21, 0
	s_add_u32 s50, s50, 0x100
	s_addc_u32 s51, s51, 0
	s_cmp_gt_u32 s52, 13
	s_barrier
.LBB0_123:
	s_add_u32 s2, s20, 0xfffc0080
	s_addc_u32 s3, s21, -1
	ds_read_b128 v[24:27], v164
	ds_read_b128 v[28:31], v164 offset:1024
	ds_read_b128 v[32:35], v164 offset:2048
	ds_read_b128 v[36:39], v164 offset:3072
	s_cmp_eq_u32 s52, 12
	s_cselect_b32 s23, s7, s3
	s_cselect_b32 s22, s9, s2
	s_cselect_b32 s3, s13, s51
	s_cselect_b32 s2, s15, s50
	s_add_i32 m0, s37, 0xc000
	ds_read_b128 v[154:157], v165
	ds_read_b128 v[158:161], v165 offset:1024
	ds_read_b128 v[180:183], v165 offset:2048
	ds_read_b128 v[184:187], v165 offset:3072
	ds_read_b128 v[188:191], v165 offset:4096
	ds_read_b128 v[192:195], v165 offset:5120
	ds_read_b128 v[196:199], v165 offset:6144
	global_load_lds_dwordx4 v150, s[20:21]
	s_add_i32 m0, s37, 0xe000
	ds_read_b128 v[200:203], v165 offset:7168
	global_load_lds_dwordx4 v152, s[20:21]
	s_waitcnt lgkmcnt(8)
	s_barrier
	s_waitcnt lgkmcnt(0)
	v_mfma_f32_16x16x32_bf16 v[140:143], v[24:27], v[154:157], v[140:143]
	v_mfma_f32_16x16x32_bf16 v[136:139], v[32:35], v[154:157], v[136:139]
	v_mfma_f32_16x16x32_bf16 v[124:127], v[24:27], v[180:183], v[124:127]
	v_mfma_f32_16x16x32_bf16 v[120:123], v[32:35], v[180:183], v[120:123]
	v_mfma_f32_16x16x32_bf16 v[108:111], v[24:27], v[188:191], v[108:111]
	v_mfma_f32_16x16x32_bf16 v[104:107], v[32:35], v[188:191], v[104:107]
	v_mfma_f32_16x16x32_bf16 v[92:95], v[24:27], v[196:199], v[92:95]
	v_mfma_f32_16x16x32_bf16 v[88:91], v[32:35], v[196:199], v[88:91]
	v_mfma_f32_16x16x32_bf16 v[140:143], v[28:31], v[158:161], v[140:143]
	v_mfma_f32_16x16x32_bf16 v[136:139], v[36:39], v[158:161], v[136:139]
	v_mfma_f32_16x16x32_bf16 v[124:127], v[28:31], v[184:187], v[124:127]
	v_mfma_f32_16x16x32_bf16 v[120:123], v[36:39], v[184:187], v[120:123]
	v_mfma_f32_16x16x32_bf16 v[108:111], v[28:31], v[192:195], v[108:111]
	v_mfma_f32_16x16x32_bf16 v[104:107], v[36:39], v[192:195], v[104:107]
	v_mfma_f32_16x16x32_bf16 v[92:95], v[28:31], v[200:203], v[92:95]
	v_mfma_f32_16x16x32_bf16 v[88:91], v[36:39], v[200:203], v[88:91]
	s_barrier
	s_add_i32 s53, s36, 0x10000
	ds_read_b128 v[204:207], v164 offset:16384
	ds_read_b128 v[208:211], v164 offset:17408
	ds_read_b128 v[212:215], v164 offset:18432
	ds_read_b128 v[216:219], v164 offset:19456
	s_mov_b32 m0, s53
	s_add_u32 s98, s2, 0x80
	s_addc_u32 s99, s3, 0
	global_load_lds_dwordx4 v168, s[2:3]
	s_add_i32 m0, s53, 0x2000
	s_nop 0
	global_load_lds_dwordx4 v148, s[2:3]
	s_barrier
	s_waitcnt lgkmcnt(0)
	v_mfma_f32_16x16x32_bf16 v[132:135], v[204:207], v[154:157], v[132:135]
	v_mfma_f32_16x16x32_bf16 v[128:131], v[212:215], v[154:157], v[128:131]
	v_mfma_f32_16x16x32_bf16 v[116:119], v[204:207], v[180:183], v[116:119]
	v_mfma_f32_16x16x32_bf16 v[112:115], v[212:215], v[180:183], v[112:115]
	v_mfma_f32_16x16x32_bf16 v[100:103], v[204:207], v[188:191], v[100:103]
	v_mfma_f32_16x16x32_bf16 v[96:99], v[212:215], v[188:191], v[96:99]
	v_mfma_f32_16x16x32_bf16 v[84:87], v[204:207], v[196:199], v[84:87]
	v_mfma_f32_16x16x32_bf16 v[80:83], v[212:215], v[196:199], v[80:83]
	v_mfma_f32_16x16x32_bf16 v[132:135], v[208:211], v[158:161], v[132:135]
	v_mfma_f32_16x16x32_bf16 v[128:131], v[216:219], v[158:161], v[128:131]
	v_mfma_f32_16x16x32_bf16 v[116:119], v[208:211], v[184:187], v[116:119]
	v_mfma_f32_16x16x32_bf16 v[112:115], v[216:219], v[184:187], v[112:115]
	v_mfma_f32_16x16x32_bf16 v[100:103], v[208:211], v[192:195], v[100:103]
	v_mfma_f32_16x16x32_bf16 v[96:99], v[216:219], v[192:195], v[96:99]
	v_mfma_f32_16x16x32_bf16 v[84:87], v[208:211], v[200:203], v[84:87]
	v_mfma_f32_16x16x32_bf16 v[80:83], v[216:219], v[200:203], v[80:83]
	s_mov_b32 m0, s37
	s_add_u32 s100, s22, 0x80
	s_addc_u32 s101, s23, 0
	s_barrier
	ds_read_b128 v[154:157], v165 offset:16384
	ds_read_b128 v[158:161], v165 offset:17408
	ds_read_b128 v[180:183], v165 offset:18432
	ds_read_b128 v[184:187], v165 offset:19456
	ds_read_b128 v[188:191], v165 offset:20480
	ds_read_b128 v[192:195], v165 offset:21504
	ds_read_b128 v[196:199], v165 offset:22528
	global_load_lds_dwordx4 v144, s[22:23]
	s_mov_b32 m0, s38
	ds_read_b128 v[200:203], v165 offset:23552
	global_load_lds_dwordx4 v146, s[22:23]
	s_barrier
	s_waitcnt lgkmcnt(0)
	v_mfma_f32_16x16x32_bf16 v[76:79], v[24:27], v[154:157], v[76:79]
	v_mfma_f32_16x16x32_bf16 v[72:75], v[32:35], v[154:157], v[72:75]
	v_mfma_f32_16x16x32_bf16 v[60:63], v[24:27], v[180:183], v[60:63]
	v_mfma_f32_16x16x32_bf16 v[56:59], v[32:35], v[180:183], v[56:59]
	v_mfma_f32_16x16x32_bf16 v[44:47], v[24:27], v[188:191], v[44:47]
	v_mfma_f32_16x16x32_bf16 v[40:43], v[32:35], v[188:191], v[40:43]
	v_mfma_f32_16x16x32_bf16 v[12:15], v[24:27], v[196:199], v[12:15]
	v_mfma_f32_16x16x32_bf16 v[8:11], v[32:35], v[196:199], v[8:11]
	v_mfma_f32_16x16x32_bf16 v[76:79], v[28:31], v[158:161], v[76:79]
	v_mfma_f32_16x16x32_bf16 v[72:75], v[36:39], v[158:161], v[72:75]
	v_mfma_f32_16x16x32_bf16 v[60:63], v[28:31], v[184:187], v[60:63]
	v_mfma_f32_16x16x32_bf16 v[56:59], v[36:39], v[184:187], v[56:59]
	v_mfma_f32_16x16x32_bf16 v[44:47], v[28:31], v[192:195], v[44:47]
	v_mfma_f32_16x16x32_bf16 v[40:43], v[36:39], v[192:195], v[40:43]
	v_mfma_f32_16x16x32_bf16 v[12:15], v[28:31], v[200:203], v[12:15]
	v_mfma_f32_16x16x32_bf16 v[8:11], v[36:39], v[200:203], v[8:11]
	s_barrier
	s_add_i32 s53, s36, 0x14000
	s_mov_b32 m0, s53
	s_add_u32 s54, s2, 0x40000
	s_addc_u32 s55, s3, 0
	global_load_lds_dwordx4 v168, s[54:55]
	s_add_i32 m0, s53, 0x2000
	s_nop 0
	global_load_lds_dwordx4 v148, s[54:55]
	s_waitcnt vmcnt(6)
	s_barrier
	v_mfma_f32_16x16x32_bf16 v[20:23], v[204:207], v[188:191], v[20:23]
	v_mfma_f32_16x16x32_bf16 v[16:19], v[212:215], v[188:191], v[16:19]
	v_mfma_f32_16x16x32_bf16 v[4:7], v[204:207], v[196:199], v[4:7]
	v_mfma_f32_16x16x32_bf16 v[0:3], v[212:215], v[196:199], v[0:3]
	v_mfma_f32_16x16x32_bf16 v[24:27], v[204:207], v[154:157], v[68:71]
	v_mfma_f32_16x16x32_bf16 v[28:31], v[212:215], v[154:157], v[64:67]
	v_mfma_f32_16x16x32_bf16 v[32:35], v[204:207], v[180:183], v[52:55]
	v_mfma_f32_16x16x32_bf16 v[36:39], v[212:215], v[180:183], v[48:51]
	v_mfma_f32_16x16x32_bf16 v[20:23], v[208:211], v[192:195], v[20:23]
	v_mfma_f32_16x16x32_bf16 v[16:19], v[216:219], v[192:195], v[16:19]
	v_mfma_f32_16x16x32_bf16 v[4:7], v[208:211], v[200:203], v[4:7]
	v_mfma_f32_16x16x32_bf16 v[0:3], v[216:219], v[200:203], v[0:3]
	v_mfma_f32_16x16x32_bf16 v[24:27], v[208:211], v[158:161], v[24:27]
	v_mfma_f32_16x16x32_bf16 v[28:31], v[216:219], v[158:161], v[28:31]
	v_mfma_f32_16x16x32_bf16 v[32:35], v[208:211], v[184:187], v[32:35]
	v_mfma_f32_16x16x32_bf16 v[36:39], v[216:219], v[184:187], v[36:39]
	s_barrier
	ds_read_b128 v[48:51], v164 offset:32768
	ds_read_b128 v[52:55], v164 offset:33792
	ds_read_b128 v[64:67], v164 offset:34816
	ds_read_b128 v[68:71], v164 offset:35840
	s_add_u32 s22, s22, 0x40000
	s_addc_u32 s23, s23, 0
	s_mov_b32 m0, s39
	ds_read_b128 v[154:157], v165 offset:32768
	ds_read_b128 v[158:161], v165 offset:33792
	ds_read_b128 v[180:183], v165 offset:34816
	ds_read_b128 v[184:187], v165 offset:35840
	ds_read_b128 v[188:191], v165 offset:36864
	ds_read_b128 v[192:195], v165 offset:37888
	ds_read_b128 v[196:199], v165 offset:38912
	global_load_lds_dwordx4 v144, s[22:23]
	s_mov_b32 m0, s40
	ds_read_b128 v[200:203], v165 offset:39936
	global_load_lds_dwordx4 v146, s[22:23]
	s_waitcnt lgkmcnt(8)
	s_barrier
	s_waitcnt lgkmcnt(0)
	v_mfma_f32_16x16x32_bf16 v[140:143], v[48:51], v[154:157], v[140:143]
	v_mfma_f32_16x16x32_bf16 v[136:139], v[64:67], v[154:157], v[136:139]
	v_mfma_f32_16x16x32_bf16 v[124:127], v[48:51], v[180:183], v[124:127]
	v_mfma_f32_16x16x32_bf16 v[120:123], v[64:67], v[180:183], v[120:123]
	v_mfma_f32_16x16x32_bf16 v[108:111], v[48:51], v[188:191], v[108:111]
	v_mfma_f32_16x16x32_bf16 v[104:107], v[64:67], v[188:191], v[104:107]
	v_mfma_f32_16x16x32_bf16 v[92:95], v[48:51], v[196:199], v[92:95]
	v_mfma_f32_16x16x32_bf16 v[88:91], v[64:67], v[196:199], v[88:91]
	v_mfma_f32_16x16x32_bf16 v[140:143], v[52:55], v[158:161], v[140:143]
	v_mfma_f32_16x16x32_bf16 v[136:139], v[68:71], v[158:161], v[136:139]
	v_mfma_f32_16x16x32_bf16 v[124:127], v[52:55], v[184:187], v[124:127]
	v_mfma_f32_16x16x32_bf16 v[120:123], v[68:71], v[184:187], v[120:123]
	v_mfma_f32_16x16x32_bf16 v[108:111], v[52:55], v[192:195], v[108:111]
	v_mfma_f32_16x16x32_bf16 v[104:107], v[68:71], v[192:195], v[104:107]
	v_mfma_f32_16x16x32_bf16 v[92:95], v[52:55], v[200:203], v[92:95]
	v_mfma_f32_16x16x32_bf16 v[88:91], v[68:71], v[200:203], v[88:91]
	s_barrier
	s_add_i32 s23, s36, 0x18000
	s_mov_b32 m0, s23
	ds_read_b128 v[204:207], v164 offset:49152
	ds_read_b128 v[208:211], v164 offset:50176
	ds_read_b128 v[212:215], v164 offset:51200
	global_load_lds_dwordx4 v168, s[98:99]
	s_add_i32 m0, s23, 0x2000
	ds_read_b128 v[216:219], v164 offset:52224
	global_load_lds_dwordx4 v148, s[98:99]
	s_barrier
	s_waitcnt lgkmcnt(0)
	v_mfma_f32_16x16x32_bf16 v[132:135], v[204:207], v[154:157], v[132:135]
	v_mfma_f32_16x16x32_bf16 v[128:131], v[212:215], v[154:157], v[128:131]
	v_mfma_f32_16x16x32_bf16 v[116:119], v[204:207], v[180:183], v[116:119]
	v_mfma_f32_16x16x32_bf16 v[112:115], v[212:215], v[180:183], v[112:115]
	v_mfma_f32_16x16x32_bf16 v[100:103], v[204:207], v[188:191], v[100:103]
	v_mfma_f32_16x16x32_bf16 v[96:99], v[212:215], v[188:191], v[96:99]
	v_mfma_f32_16x16x32_bf16 v[84:87], v[204:207], v[196:199], v[84:87]
	v_mfma_f32_16x16x32_bf16 v[80:83], v[212:215], v[196:199], v[80:83]
	v_mfma_f32_16x16x32_bf16 v[132:135], v[208:211], v[158:161], v[132:135]
	v_mfma_f32_16x16x32_bf16 v[128:131], v[216:219], v[158:161], v[128:131]
	v_mfma_f32_16x16x32_bf16 v[116:119], v[208:211], v[184:187], v[116:119]
	v_mfma_f32_16x16x32_bf16 v[112:115], v[216:219], v[184:187], v[112:115]
	v_mfma_f32_16x16x32_bf16 v[100:103], v[208:211], v[192:195], v[100:103]
	v_mfma_f32_16x16x32_bf16 v[96:99], v[216:219], v[192:195], v[96:99]
	v_mfma_f32_16x16x32_bf16 v[84:87], v[208:211], v[200:203], v[84:87]
	v_mfma_f32_16x16x32_bf16 v[80:83], v[216:219], v[200:203], v[80:83]
	s_mov_b32 m0, s45
	s_barrier
	ds_read_b128 v[154:157], v165 offset:49152
	ds_read_b128 v[158:161], v165 offset:50176
	ds_read_b128 v[180:183], v165 offset:51200
	ds_read_b128 v[184:187], v165 offset:52224
	ds_read_b128 v[188:191], v165 offset:53248
	ds_read_b128 v[192:195], v165 offset:54272
	ds_read_b128 v[196:199], v165 offset:55296
	global_load_lds_dwordx4 v144, s[100:101]
	s_mov_b32 m0, s46
	ds_read_b128 v[200:203], v165 offset:56320
	global_load_lds_dwordx4 v146, s[100:101]
	s_barrier
	s_waitcnt lgkmcnt(0)
	v_mfma_f32_16x16x32_bf16 v[76:79], v[48:51], v[154:157], v[76:79]
	v_mfma_f32_16x16x32_bf16 v[72:75], v[64:67], v[154:157], v[72:75]
	v_mfma_f32_16x16x32_bf16 v[60:63], v[48:51], v[180:183], v[60:63]
	v_mfma_f32_16x16x32_bf16 v[56:59], v[64:67], v[180:183], v[56:59]
	v_mfma_f32_16x16x32_bf16 v[44:47], v[48:51], v[188:191], v[44:47]
	v_mfma_f32_16x16x32_bf16 v[40:43], v[64:67], v[188:191], v[40:43]
	v_mfma_f32_16x16x32_bf16 v[12:15], v[48:51], v[196:199], v[12:15]
	v_mfma_f32_16x16x32_bf16 v[8:11], v[64:67], v[196:199], v[8:11]
	v_mfma_f32_16x16x32_bf16 v[76:79], v[52:55], v[158:161], v[76:79]
	v_mfma_f32_16x16x32_bf16 v[72:75], v[68:71], v[158:161], v[72:75]
	v_mfma_f32_16x16x32_bf16 v[60:63], v[52:55], v[184:187], v[60:63]
	v_mfma_f32_16x16x32_bf16 v[56:59], v[68:71], v[184:187], v[56:59]
	v_mfma_f32_16x16x32_bf16 v[44:47], v[52:55], v[192:195], v[44:47]
	v_mfma_f32_16x16x32_bf16 v[40:43], v[68:71], v[192:195], v[40:43]
	v_mfma_f32_16x16x32_bf16 v[12:15], v[52:55], v[200:203], v[12:15]
	v_mfma_f32_16x16x32_bf16 v[8:11], v[68:71], v[200:203], v[8:11]
	s_barrier
	s_add_i32 s22, s36, 0x1c000
	s_mov_b32 m0, s22
	s_add_u32 s2, s2, 0x40080
	s_addc_u32 s3, s3, 0
	global_load_lds_dwordx4 v168, s[2:3]
	s_add_i32 m0, s22, 0x2000
	s_nop 0
	global_load_lds_dwordx4 v148, s[2:3]
	s_waitcnt vmcnt(6)
	s_barrier
	v_mfma_f32_16x16x32_bf16 v[24:27], v[204:207], v[154:157], v[24:27]
	v_mfma_f32_16x16x32_bf16 v[68:71], v[208:211], v[158:161], v[24:27]
	v_mfma_f32_16x16x32_bf16 v[24:27], v[212:215], v[154:157], v[28:31]
	v_mfma_f32_16x16x32_bf16 v[64:67], v[216:219], v[158:161], v[24:27]
	v_mfma_f32_16x16x32_bf16 v[24:27], v[204:207], v[180:183], v[32:35]
	v_mfma_f32_16x16x32_bf16 v[52:55], v[208:211], v[184:187], v[24:27]
	v_mfma_f32_16x16x32_bf16 v[24:27], v[212:215], v[180:183], v[36:39]
	v_mfma_f32_16x16x32_bf16 v[20:23], v[204:207], v[188:191], v[20:23]
	v_mfma_f32_16x16x32_bf16 v[16:19], v[212:215], v[188:191], v[16:19]
	v_mfma_f32_16x16x32_bf16 v[4:7], v[204:207], v[196:199], v[4:7]
	v_mfma_f32_16x16x32_bf16 v[0:3], v[212:215], v[196:199], v[0:3]
	v_mfma_f32_16x16x32_bf16 v[48:51], v[216:219], v[184:187], v[24:27]
	v_mfma_f32_16x16x32_bf16 v[20:23], v[208:211], v[192:195], v[20:23]
	v_mfma_f32_16x16x32_bf16 v[16:19], v[216:219], v[192:195], v[16:19]
	v_mfma_f32_16x16x32_bf16 v[4:7], v[208:211], v[200:203], v[4:7]
	v_mfma_f32_16x16x32_bf16 v[0:3], v[216:219], v[200:203], v[0:3]
	s_add_i32 s52, s52, 2
	s_add_u32 s20, s20, 0x100
	s_addc_u32 s21, s21, 0
	s_add_u32 s50, s50, 0x100
	s_addc_u32 s51, s51, 0
	s_cmp_gt_u32 s52, 13
	s_barrier
	s_cbranch_scc0 .LBB0_123
	s_lshl_b32 s2, s6, 8
	s_add_i32 s3, s2, s43
	s_lshl_b32 s2, s8, 8
	s_cmp_gt_i32 s8, 3
	s_cselect_b64 s[20:21], -1, 0
	s_and_b64 s[22:23], s[20:21], exec
	s_mov_b32 s7, 0x8982000
	s_cselect_b32 s7, s7, 0x7182000
	s_add_u32 s22, s26, s7
	s_addc_u32 s23, s25, 0
	s_add_i32 s7, s6, -16
	v_mov_b32_e32 v160, v163
	v_mov_b32_e32 v24, v162
	s_lshr_b32 s7, s7, 3
	s_add_i32 s96, s7, 1
	v_add_u32_e32 v154, s3, v24
	s_lshl_b64 s[50:51], s[96:97], 11
	v_ashrrev_i32_e32 v155, 31, v154
	s_cmp_gt_i32 s6, 15
	v_lshl_add_u64 v[156:157], v[154:155], 2, s[10:11]
	s_cselect_b32 s7, s51, 0
	s_cselect_b32 s6, s50, 0
	global_load_dword v166, v[156:157], off
	global_load_dword v191, v[156:157], off offset:64
	global_load_dword v192, v[156:157], off offset:128
	global_load_dword v193, v[156:157], off offset:192
	global_load_dword v194, v[156:157], off offset:512
	global_load_dword v195, v[156:157], off offset:576
	global_load_dword v196, v[156:157], off offset:640
	global_load_dword v197, v[156:157], off offset:704
	s_lshl_b64 s[6:7], s[6:7], 2
	s_add_u32 s9, s41, s6
	s_addc_u32 s13, s42, s7
	s_ashr_i32 s3, s2, 31
	s_lshl_b64 s[6:7], s[2:3], 2
	s_add_u32 s3, s9, s6
	s_addc_u32 s7, s13, s7
	v_lshlrev_b32_e32 v158, 3, v160
	s_add_u32 s6, s3, s49
	s_addc_u32 s7, s7, 0
	v_ashrrev_i32_e32 v159, 31, v158
	v_lshl_add_u64 v[24:25], v[158:159], 2, s[6:7]
	global_load_dwordx4 v[36:39], v[24:25], off
	global_load_dwordx4 v[32:35], v[24:25], off offset:16
	global_load_dwordx4 v[28:31], v[24:25], off offset:512
	s_nop 0
	global_load_dwordx4 v[24:27], v[24:25], off offset:528
	s_and_b32 s2, s2, 0x300
	s_or_b32 s2, s2, s44
	v_add_u32_e32 v158, s2, v158
	v_cmp_eq_u32_e64 s[6:7], 0, v160
	v_lshlrev_b64 v[160:161], 11, v[154:155]
	s_cmp_lt_i32 s8, 4
	s_waitcnt vmcnt(0)
	v_ashrrev_i32_e32 v159, 31, v158
	v_lshl_add_u64 v[158:159], v[158:159], 1, s[22:23]
	v_lshl_add_u64 v[160:161], v[158:159], 0, v[160:161]
	v_lshl_add_u64 v[156:157], v[154:155], 2, s[0:1]
	s_and_b64 s[6:7], s[6:7], s[20:21]
	s_mov_b64 s[2:3], 0x8000
	s_mov_b64 s[50:51], 0x28000
	v_mov_b32_e32 v180, 0xc0135761
	v_mov_b32_e32 v181, 0xc0135761
	v_mov_b32_e32 v182, 0xbdd2d3e7
	v_mov_b32_e32 v183, 0xbdd2d3e7
	v_fmamk_f32 v166, v166, 0x3a800000, v225
	v_fmamk_f32 v190, v191, 0x3a800000, v225
	v_fmamk_f32 v192, v192, 0x3a800000, v225
	v_fmamk_f32 v188, v193, 0x3a800000, v225
	v_fmamk_f32 v194, v194, 0x3a800000, v225
	v_fmamk_f32 v186, v195, 0x3a800000, v225
	v_fmamk_f32 v196, v196, 0x3a800000, v225
	v_fmamk_f32 v184, v197, 0x3a800000, v225
	v_rsq_f32_e32 v166, v166
	v_rsq_f32_e32 v190, v190
	v_rsq_f32_e32 v192, v192
	v_rsq_f32_e32 v188, v188
	v_rsq_f32_e32 v194, v194
	v_rsq_f32_e32 v186, v186
	v_rsq_f32_e32 v196, v196
	v_rsq_f32_e32 v184, v184
	v_pk_fma_f32 v[140:141], v[140:141], v[166:167], v[36:37] op_sel_hi:[1,0,1]
	v_pk_fma_f32 v[142:143], v[142:143], v[166:167], v[38:39] op_sel_hi:[1,0,1]
	v_pk_fma_f32 v[136:137], v[136:137], v[166:167], v[32:33] op_sel_hi:[1,0,1]
	v_pk_fma_f32 v[138:139], v[138:139], v[166:167], v[34:35] op_sel_hi:[1,0,1]
	v_pk_fma_f32 v[132:133], v[132:133], v[166:167], v[28:29] op_sel_hi:[1,0,1]
	v_pk_fma_f32 v[134:135], v[134:135], v[166:167], v[30:31] op_sel_hi:[1,0,1]
	v_pk_fma_f32 v[128:129], v[128:129], v[166:167], v[24:25] op_sel_hi:[1,0,1]
	v_pk_fma_f32 v[130:131], v[130:131], v[166:167], v[26:27] op_sel_hi:[1,0,1]
	v_pk_fma_f32 v[124:125], v[124:125], v[190:191], v[36:37] op_sel_hi:[1,0,1]
	v_pk_fma_f32 v[126:127], v[126:127], v[190:191], v[38:39] op_sel_hi:[1,0,1]
	v_pk_fma_f32 v[120:121], v[120:121], v[190:191], v[32:33] op_sel_hi:[1,0,1]
	v_pk_fma_f32 v[122:123], v[122:123], v[190:191], v[34:35] op_sel_hi:[1,0,1]
	v_pk_fma_f32 v[116:117], v[116:117], v[190:191], v[28:29] op_sel_hi:[1,0,1]
	v_pk_fma_f32 v[118:119], v[118:119], v[190:191], v[30:31] op_sel_hi:[1,0,1]
	v_pk_fma_f32 v[112:113], v[112:113], v[190:191], v[24:25] op_sel_hi:[1,0,1]
	v_pk_fma_f32 v[114:115], v[114:115], v[190:191], v[26:27] op_sel_hi:[1,0,1]
	v_pk_fma_f32 v[108:109], v[108:109], v[192:193], v[36:37] op_sel_hi:[1,0,1]
	v_pk_fma_f32 v[110:111], v[110:111], v[192:193], v[38:39] op_sel_hi:[1,0,1]
	v_pk_fma_f32 v[104:105], v[104:105], v[192:193], v[32:33] op_sel_hi:[1,0,1]
	v_pk_fma_f32 v[106:107], v[106:107], v[192:193], v[34:35] op_sel_hi:[1,0,1]
	v_pk_fma_f32 v[100:101], v[100:101], v[192:193], v[28:29] op_sel_hi:[1,0,1]
	v_pk_fma_f32 v[102:103], v[102:103], v[192:193], v[30:31] op_sel_hi:[1,0,1]
	v_pk_fma_f32 v[96:97], v[96:97], v[192:193], v[24:25] op_sel_hi:[1,0,1]
	v_pk_fma_f32 v[98:99], v[98:99], v[192:193], v[26:27] op_sel_hi:[1,0,1]
	v_pk_fma_f32 v[92:93], v[92:93], v[188:189], v[36:37] op_sel_hi:[1,0,1]
	v_pk_fma_f32 v[94:95], v[94:95], v[188:189], v[38:39] op_sel_hi:[1,0,1]
	v_pk_fma_f32 v[88:89], v[88:89], v[188:189], v[32:33] op_sel_hi:[1,0,1]
	v_pk_fma_f32 v[90:91], v[90:91], v[188:189], v[34:35] op_sel_hi:[1,0,1]
	v_pk_fma_f32 v[84:85], v[84:85], v[188:189], v[28:29] op_sel_hi:[1,0,1]
	v_pk_fma_f32 v[86:87], v[86:87], v[188:189], v[30:31] op_sel_hi:[1,0,1]
	v_pk_fma_f32 v[80:81], v[80:81], v[188:189], v[24:25] op_sel_hi:[1,0,1]
	v_pk_fma_f32 v[82:83], v[82:83], v[188:189], v[26:27] op_sel_hi:[1,0,1]
	v_pk_fma_f32 v[76:77], v[76:77], v[194:195], v[36:37] op_sel_hi:[1,0,1]
	v_pk_fma_f32 v[78:79], v[78:79], v[194:195], v[38:39] op_sel_hi:[1,0,1]
	v_pk_fma_f32 v[72:73], v[72:73], v[194:195], v[32:33] op_sel_hi:[1,0,1]
	v_pk_fma_f32 v[74:75], v[74:75], v[194:195], v[34:35] op_sel_hi:[1,0,1]
	v_pk_fma_f32 v[68:69], v[68:69], v[194:195], v[28:29] op_sel_hi:[1,0,1]
	v_pk_fma_f32 v[70:71], v[70:71], v[194:195], v[30:31] op_sel_hi:[1,0,1]
	v_pk_fma_f32 v[64:65], v[64:65], v[194:195], v[24:25] op_sel_hi:[1,0,1]
	v_pk_fma_f32 v[66:67], v[66:67], v[194:195], v[26:27] op_sel_hi:[1,0,1]
	v_pk_fma_f32 v[60:61], v[60:61], v[186:187], v[36:37] op_sel_hi:[1,0,1]
	v_pk_fma_f32 v[62:63], v[62:63], v[186:187], v[38:39] op_sel_hi:[1,0,1]
	v_pk_fma_f32 v[56:57], v[56:57], v[186:187], v[32:33] op_sel_hi:[1,0,1]
	v_pk_fma_f32 v[58:59], v[58:59], v[186:187], v[34:35] op_sel_hi:[1,0,1]
	v_pk_fma_f32 v[52:53], v[52:53], v[186:187], v[28:29] op_sel_hi:[1,0,1]
	v_pk_fma_f32 v[54:55], v[54:55], v[186:187], v[30:31] op_sel_hi:[1,0,1]
	v_pk_fma_f32 v[48:49], v[48:49], v[186:187], v[24:25] op_sel_hi:[1,0,1]
	v_pk_fma_f32 v[50:51], v[50:51], v[186:187], v[26:27] op_sel_hi:[1,0,1]
	v_pk_fma_f32 v[44:45], v[44:45], v[196:197], v[36:37] op_sel_hi:[1,0,1]
	v_pk_fma_f32 v[46:47], v[46:47], v[196:197], v[38:39] op_sel_hi:[1,0,1]
	v_pk_fma_f32 v[40:41], v[40:41], v[196:197], v[32:33] op_sel_hi:[1,0,1]
	v_pk_fma_f32 v[42:43], v[42:43], v[196:197], v[34:35] op_sel_hi:[1,0,1]
	v_pk_fma_f32 v[20:21], v[20:21], v[196:197], v[28:29] op_sel_hi:[1,0,1]
	v_pk_fma_f32 v[22:23], v[22:23], v[196:197], v[30:31] op_sel_hi:[1,0,1]
	v_pk_fma_f32 v[16:17], v[16:17], v[196:197], v[24:25] op_sel_hi:[1,0,1]
	v_pk_fma_f32 v[18:19], v[18:19], v[196:197], v[26:27] op_sel_hi:[1,0,1]
	v_pk_fma_f32 v[12:13], v[12:13], v[184:185], v[36:37] op_sel_hi:[1,0,1]
	v_pk_fma_f32 v[14:15], v[14:15], v[184:185], v[38:39] op_sel_hi:[1,0,1]
	v_pk_fma_f32 v[8:9], v[8:9], v[184:185], v[32:33] op_sel_hi:[1,0,1]
	v_pk_fma_f32 v[10:11], v[10:11], v[184:185], v[34:35] op_sel_hi:[1,0,1]
	v_pk_fma_f32 v[4:5], v[4:5], v[184:185], v[28:29] op_sel_hi:[1,0,1]
	v_pk_fma_f32 v[6:7], v[6:7], v[184:185], v[30:31] op_sel_hi:[1,0,1]
	v_pk_fma_f32 v[0:1], v[0:1], v[184:185], v[24:25] op_sel_hi:[1,0,1]
	v_pk_fma_f32 v[2:3], v[2:3], v[184:185], v[26:27] op_sel_hi:[1,0,1]
	v_pk_mul_f32 v[24:25], v[140:141], v[140:141]
	v_pk_mul_f32 v[26:27], v[142:143], v[142:143]
	v_pk_mul_f32 v[28:29], v[136:137], v[136:137]
	v_pk_mul_f32 v[30:31], v[138:139], v[138:139]
	v_pk_mul_f32 v[32:33], v[132:133], v[132:133]
	v_pk_mul_f32 v[34:35], v[134:135], v[134:135]
	v_pk_mul_f32 v[36:37], v[128:129], v[128:129]
	v_pk_mul_f32 v[38:39], v[130:131], v[130:131]
	v_pk_fma_f32 v[24:25], v[24:25], v[182:183], v[180:181]
	v_pk_fma_f32 v[26:27], v[26:27], v[182:183], v[180:181]
	v_pk_fma_f32 v[28:29], v[28:29], v[182:183], v[180:181]
	v_pk_fma_f32 v[30:31], v[30:31], v[182:183], v[180:181]
	v_pk_fma_f32 v[32:33], v[32:33], v[182:183], v[180:181]
	v_pk_fma_f32 v[34:35], v[34:35], v[182:183], v[180:181]
	v_pk_fma_f32 v[36:37], v[36:37], v[182:183], v[180:181]
	v_pk_fma_f32 v[38:39], v[38:39], v[182:183], v[180:181]
	v_pk_mul_f32 v[24:25], v[24:25], v[140:141]
	v_pk_mul_f32 v[26:27], v[26:27], v[142:143]
	v_pk_mul_f32 v[28:29], v[28:29], v[136:137]
	v_pk_mul_f32 v[30:31], v[30:31], v[138:139]
	v_pk_mul_f32 v[32:33], v[32:33], v[132:133]
	v_pk_mul_f32 v[34:35], v[34:35], v[134:135]
	v_pk_mul_f32 v[36:37], v[36:37], v[128:129]
	v_pk_mul_f32 v[38:39], v[38:39], v[130:131]
	v_exp_f32_e32 v24, v24
	v_exp_f32_e32 v25, v25
	v_exp_f32_e32 v26, v26
	v_exp_f32_e32 v27, v27
	v_exp_f32_e32 v28, v28
	v_exp_f32_e32 v29, v29
	v_exp_f32_e32 v30, v30
	v_exp_f32_e32 v31, v31
	v_exp_f32_e32 v32, v32
	v_exp_f32_e32 v33, v33
	v_exp_f32_e32 v34, v34
	v_exp_f32_e32 v35, v35
	v_exp_f32_e32 v36, v36
	v_exp_f32_e32 v37, v37
	v_exp_f32_e32 v38, v38
	v_exp_f32_e32 v39, v39
	v_pk_add_f32 v[24:25], v[24:25], 1.0 op_sel_hi:[1,0]
	v_pk_add_f32 v[26:27], v[26:27], 1.0 op_sel_hi:[1,0]
	v_pk_add_f32 v[28:29], v[28:29], 1.0 op_sel_hi:[1,0]
	v_pk_add_f32 v[30:31], v[30:31], 1.0 op_sel_hi:[1,0]
	v_pk_add_f32 v[32:33], v[32:33], 1.0 op_sel_hi:[1,0]
	v_pk_add_f32 v[34:35], v[34:35], 1.0 op_sel_hi:[1,0]
	v_pk_add_f32 v[36:37], v[36:37], 1.0 op_sel_hi:[1,0]
	v_pk_add_f32 v[38:39], v[38:39], 1.0 op_sel_hi:[1,0]
	v_rcp_f32_e32 v24, v24
	v_rcp_f32_e32 v25, v25
	v_rcp_f32_e32 v26, v26
	v_rcp_f32_e32 v27, v27
	v_rcp_f32_e32 v28, v28
	v_rcp_f32_e32 v29, v29
	v_rcp_f32_e32 v30, v30
	v_rcp_f32_e32 v31, v31
	v_rcp_f32_e32 v32, v32
	v_rcp_f32_e32 v33, v33
	v_rcp_f32_e32 v34, v34
	v_rcp_f32_e32 v35, v35
	v_rcp_f32_e32 v36, v36
	v_rcp_f32_e32 v37, v37
	v_rcp_f32_e32 v38, v38
	v_rcp_f32_e32 v39, v39
	v_pk_mul_f32 v[140:141], v[140:141], v[24:25]
	v_pk_mul_f32 v[142:143], v[142:143], v[26:27]
	v_pk_mul_f32 v[136:137], v[136:137], v[28:29]
	v_pk_mul_f32 v[138:139], v[138:139], v[30:31]
	v_pk_mul_f32 v[132:133], v[132:133], v[32:33]
	v_pk_mul_f32 v[134:135], v[134:135], v[34:35]
	v_pk_mul_f32 v[128:129], v[128:129], v[36:37]
	v_pk_mul_f32 v[130:131], v[130:131], v[38:39]
	v_cvt_pk_bf16_f32 v24, v140, v141
	v_cvt_pk_bf16_f32 v25, v142, v143
	v_cvt_pk_bf16_f32 v26, v136, v137
	v_cvt_pk_bf16_f32 v27, v138, v139
	v_cvt_pk_bf16_f32 v28, v132, v133
	v_cvt_pk_bf16_f32 v29, v134, v135
	v_cvt_pk_bf16_f32 v30, v128, v129
	v_cvt_pk_bf16_f32 v31, v130, v131
	global_store_dwordx4 v[160:161], v[24:27], off
	global_store_dwordx4 v[160:161], v[28:31], off offset:256
	s_and_b64 vcc, exec, s[20:21]
	s_cbranch_vccz .Lio_skip_0
	v_pk_mul_f32 v[32:33], v[140:141], v[140:141]
	v_pk_fma_f32 v[32:33], v[142:143], v[142:143], v[32:33]
	v_pk_fma_f32 v[32:33], v[136:137], v[136:137], v[32:33]
	v_pk_fma_f32 v[32:33], v[138:139], v[138:139], v[32:33]
	v_pk_fma_f32 v[32:33], v[132:133], v[132:133], v[32:33]
	v_pk_fma_f32 v[32:33], v[134:135], v[134:135], v[32:33]
	v_pk_fma_f32 v[32:33], v[128:129], v[128:129], v[32:33]
	v_pk_fma_f32 v[32:33], v[130:131], v[130:131], v[32:33]
	s_nop 0
	v_add_f32_e32 v32, v32, v33
	v_mov_b32_e32 v33, v32
	s_nop 1
	v_permlane16_swap_b32_e32 v32, v33
	v_add_f32_e32 v32, v32, v33
	v_mov_b32_e32 v33, v32
	s_nop 1
	v_permlane32_swap_b32_e32 v32, v33
	s_and_saveexec_b64 vcc, s[6:7]
	v_add_f32_e32 v32, v32, v33
	global_atomic_add_f32 v[156:157], v32, off
	s_mov_b64 exec, vcc

.LBB0_350:
	s_add_u32 s10, s43, 0x7182000
	s_addc_u32 s11, s42, 0
	s_add_u32 s12, s43, 0x7d82000
	s_addc_u32 s13, s42, 0
	s_add_u32 s14, s43, 0x8382000
	s_addc_u32 s15, s42, 0
	s_add_u32 s16, s5, 0x3000000
	s_addc_u32 s17, s4, 0
	s_add_u32 s18, s43, 0x2ec0000
	s_addc_u32 s19, s42, 0
	s_and_b32 s58, s8, 3
	s_add_i32 m0, s21, 0x18000
	v_lshl_add_u64 v[6:7], v[6:7], 0, s[78:79]
	s_lshl_b32 s59, s9, 6
	s_lshl_b32 s1, s9, 13
	s_lshl_b32 s22, s58, 12
	s_waitcnt vmcnt(4)
	s_barrier
	global_load_lds_dwordx4 v[6:7], off
	v_lshl_add_u64 v[4:5], v[4:5], 0, s[78:79]
	s_add_i32 m0, s21, 0x1a000
	s_add_i32 s60, s21, 0x8000
	s_add_i32 s61, s21, 0xa000
	global_load_lds_dwordx4 v[4:5], off
	v_lshl_add_u64 v[2:3], v[2:3], 0, s[78:79]
	s_mov_b32 m0, s60
	s_add_u32 s8, s2, 0x40080
	global_load_lds_dwordx4 v[2:3], off
	v_lshl_add_u64 v[0:1], v[0:1], 0, s[78:79]
	s_mov_b32 m0, s61
	s_addc_u32 s9, s3, 0
	global_load_lds_dwordx4 v[0:1], off
	s_add_i32 m0, s21, 0x1c000
	v_lshl_add_u64 v[0:1], s[8:9], 0, v[160:161]
	global_load_lds_dwordx4 v[0:1], off
	v_lshl_add_u64 v[0:1], s[8:9], 0, v[162:163]
	s_add_i32 m0, s21, 0x1e000
	v_bfe_u32 v207, v8, 4, 2
	global_load_lds_dwordx4 v[0:1], off
	v_and_b32_e32 v206, 15, v8
	v_lshlrev_b32_e32 v0, 4, v207
	v_lshlrev_b32_e32 v1, 2, v8
	v_lshl_or_b32 v0, v206, 6, v0
	v_and_b32_e32 v1, 32, v1
	v_bitop3_b32 v2, v0, s1, v1 bitop3:0xde
	v_bitop3_b32 v208, s22, v0, v1 bitop3:0xf6
	v_add_u32_e32 v208, 0x10000, v208
	v_lshlrev_b32_e32 v0, 14, v9
	s_ashr_i32 s62, s50, 31
	v_and_b32_e32 v0, 0xffff8000, v0
	s_cmp_gt_u32 s58, 1
	v_lshl_add_u32 v0, v10, 11, v0
	v_and_b32_e32 v1, 1, v9
	s_cselect_b64 s[22:23], -1, 0
	s_add_i32 s24, s58, -2
	s_mov_b32 s25, s97
	v_lshl_or_b32 v0, v1, 6, v0
	s_lshl_b64 s[8:9], s[24:25], 8
	s_lshl_b32 s25, s58, 6
	v_lshl_add_u32 v164, v11, 1, v0
	v_lshlrev_b32_e32 v0, 14, v12
	s_add_u32 s1, s5, s8
	v_and_b32_e32 v0, 0xffff8000, v0
	s_waitcnt vmcnt(6)
	s_addc_u32 s4, s4, s9
	v_lshl_add_u32 v0, v13, 11, v0
	v_and_b32_e32 v1, 1, v12
	s_add_u32 s26, s1, 0x3200000
	v_lshl_or_b32 v0, v1, 6, v0
	s_addc_u32 s27, s4, 0
	v_mov_b32_e32 v165, v169
	v_lshl_add_u32 v166, v14, 1, v0
	v_mov_b32_e32 v167, v169
	s_mov_b32 s63, 0
	v_add_u32_e32 v209, 0, v2
	s_barrier
	s_branch .LBB0_352

.Lie_done_b:
.LBB0_354:
	s_ashr_i32 s31, s30, 31
	v_cmp_lt_i64_e32 vcc, s[8:9], v[170:171]
	s_lshl_b64 s[8:9], s[30:31], 19
	s_add_u32 s34, s52, s8
	s_addc_u32 s35, s53, s9
	s_and_b64 s[8:9], vcc, exec
	s_cselect_b32 s1, s35, s7
	s_cselect_b32 s31, s34, s6
	s_ashr_i32 s29, s28, 31
	s_lshl_b64 s[8:9], s[28:29], 19
	s_add_u32 s36, s43, s8
	s_addc_u32 s37, s42, s9
	s_and_b64 s[8:9], vcc, exec
	s_cselect_b32 s29, s37, s3
	s_cselect_b32 s38, s36, s2
	s_add_u32 s6, s6, 0x40080
	s_addc_u32 s7, s7, 0
	s_add_u32 s39, s2, 0x100
	s_addc_u32 s40, s3, 0
	s_mov_b32 s41, -2
	s_add_u32 s2, s6, 0xfffc0080
	s_addc_u32 s3, s7, -1
	ds_read_b128 v[128:131], v208
	ds_read_b128 v[132:135], v208 offset:1024
	ds_read_b128 v[136:139], v208 offset:2048
	ds_read_b128 v[140:143], v208 offset:3072
	s_cmp_eq_u32 s41, 12
	s_cselect_b32 s9, s1, s3
	s_cselect_b32 s8, s31, s2
	s_cselect_b32 s3, s29, s40
	s_cselect_b32 s2, s38, s39
	s_add_i32 m0, s21, 0xc000
	ds_read_b128 v[144:147], v209
	ds_read_b128 v[148:151], v209 offset:1024
	ds_read_b128 v[152:155], v209 offset:2048
	ds_read_b128 v[156:159], v209 offset:3072
	ds_read_b128 v[180:183], v209 offset:4096
	ds_read_b128 v[184:187], v209 offset:5120
	ds_read_b128 v[188:191], v209 offset:6144
	global_load_lds_dwordx4 v164, s[6:7]
	s_add_i32 m0, s21, 0xe000
	ds_read_b128 v[192:195], v209 offset:7168
	global_load_lds_dwordx4 v166, s[6:7]
	s_waitcnt lgkmcnt(8)
	s_barrier
	s_waitcnt lgkmcnt(0)
	v_mfma_f32_16x16x32_bf16 v[124:127], v[128:131], v[144:147], 0
	v_mfma_f32_16x16x32_bf16 v[120:123], v[136:139], v[144:147], 0
	v_mfma_f32_16x16x32_bf16 v[116:119], v[128:131], v[152:155], 0
	v_mfma_f32_16x16x32_bf16 v[112:115], v[136:139], v[152:155], 0
	v_mfma_f32_16x16x32_bf16 v[100:103], v[128:131], v[180:183], 0
	v_mfma_f32_16x16x32_bf16 v[96:99], v[136:139], v[180:183], 0
	v_mfma_f32_16x16x32_bf16 v[84:87], v[128:131], v[188:191], 0
	v_mfma_f32_16x16x32_bf16 v[80:83], v[136:139], v[188:191], 0
	v_mfma_f32_16x16x32_bf16 v[124:127], v[132:135], v[148:151], v[124:127]
	v_mfma_f32_16x16x32_bf16 v[120:123], v[140:143], v[148:151], v[120:123]
	v_mfma_f32_16x16x32_bf16 v[116:119], v[132:135], v[156:159], v[116:119]
	v_mfma_f32_16x16x32_bf16 v[112:115], v[140:143], v[156:159], v[112:115]
	v_mfma_f32_16x16x32_bf16 v[100:103], v[132:135], v[184:187], v[100:103]
	v_mfma_f32_16x16x32_bf16 v[96:99], v[140:143], v[184:187], v[96:99]
	v_mfma_f32_16x16x32_bf16 v[84:87], v[132:135], v[192:195], v[84:87]
	v_mfma_f32_16x16x32_bf16 v[80:83], v[140:143], v[192:195], v[80:83]
	s_barrier
	s_add_i32 s64, s54, 0x10000
	s_add_u32 s98, s2, 0x80
	s_addc_u32 s99, s3, 0
	s_mov_b32 m0, s64
	ds_read_b128 v[196:199], v208 offset:16384
	ds_read_b128 v[200:203], v208 offset:17408
	ds_read_b128 v[210:213], v208 offset:18432
	global_load_lds_dwordx4 v160, s[2:3]
	s_add_i32 m0, s64, 0x2000
	ds_read_b128 v[214:217], v208 offset:19456
	global_load_lds_dwordx4 v162, s[2:3]
	s_barrier
	s_waitcnt lgkmcnt(0)
	v_mfma_f32_16x16x32_bf16 v[108:111], v[196:199], v[144:147], 0
	v_mfma_f32_16x16x32_bf16 v[104:107], v[210:213], v[144:147], 0
	v_mfma_f32_16x16x32_bf16 v[92:95], v[196:199], v[152:155], 0
	v_mfma_f32_16x16x32_bf16 v[88:91], v[210:213], v[152:155], 0
	v_mfma_f32_16x16x32_bf16 v[76:79], v[196:199], v[180:183], 0
	v_mfma_f32_16x16x32_bf16 v[72:75], v[210:213], v[180:183], 0
	v_mfma_f32_16x16x32_bf16 v[68:71], v[196:199], v[188:191], 0
	v_mfma_f32_16x16x32_bf16 v[64:67], v[210:213], v[188:191], 0
	v_mfma_f32_16x16x32_bf16 v[108:111], v[200:203], v[148:151], v[108:111]
	v_mfma_f32_16x16x32_bf16 v[104:107], v[214:217], v[148:151], v[104:107]
	v_mfma_f32_16x16x32_bf16 v[92:95], v[200:203], v[156:159], v[92:95]
	v_mfma_f32_16x16x32_bf16 v[88:91], v[214:217], v[156:159], v[88:91]
	v_mfma_f32_16x16x32_bf16 v[76:79], v[200:203], v[184:187], v[76:79]
	v_mfma_f32_16x16x32_bf16 v[72:75], v[214:217], v[184:187], v[72:75]
	v_mfma_f32_16x16x32_bf16 v[68:71], v[200:203], v[192:195], v[68:71]
	v_mfma_f32_16x16x32_bf16 v[64:67], v[214:217], v[192:195], v[64:67]
	s_mov_b32 m0, s21
	s_add_u32 s100, s8, 0x80
	s_addc_u32 s101, s9, 0
	s_barrier
	ds_read_b128 v[144:147], v209 offset:16384
	ds_read_b128 v[148:151], v209 offset:17408
	ds_read_b128 v[152:155], v209 offset:18432
	ds_read_b128 v[156:159], v209 offset:19456
	ds_read_b128 v[180:183], v209 offset:20480
	ds_read_b128 v[184:187], v209 offset:21504
	ds_read_b128 v[188:191], v209 offset:22528
	global_load_lds_dwordx4 v160, s[8:9]
	s_mov_b32 m0, s55
	ds_read_b128 v[192:195], v209 offset:23552
	global_load_lds_dwordx4 v162, s[8:9]
	s_barrier
	s_waitcnt lgkmcnt(0)
	v_mfma_f32_16x16x32_bf16 v[60:63], v[128:131], v[144:147], 0
	v_mfma_f32_16x16x32_bf16 v[56:59], v[136:139], v[144:147], 0
	v_mfma_f32_16x16x32_bf16 v[52:55], v[128:131], v[152:155], 0
	v_mfma_f32_16x16x32_bf16 v[48:51], v[136:139], v[152:155], 0
	v_mfma_f32_16x16x32_bf16 v[36:39], v[128:131], v[180:183], 0
	v_mfma_f32_16x16x32_bf16 v[32:35], v[136:139], v[180:183], 0
	v_mfma_f32_16x16x32_bf16 v[20:23], v[128:131], v[188:191], 0
	v_mfma_f32_16x16x32_bf16 v[16:19], v[136:139], v[188:191], 0
	v_mfma_f32_16x16x32_bf16 v[60:63], v[132:135], v[148:151], v[60:63]
	v_mfma_f32_16x16x32_bf16 v[56:59], v[140:143], v[148:151], v[56:59]
	v_mfma_f32_16x16x32_bf16 v[52:55], v[132:135], v[156:159], v[52:55]
	v_mfma_f32_16x16x32_bf16 v[48:51], v[140:143], v[156:159], v[48:51]
	v_mfma_f32_16x16x32_bf16 v[36:39], v[132:135], v[184:187], v[36:39]
	v_mfma_f32_16x16x32_bf16 v[32:35], v[140:143], v[184:187], v[32:35]
	v_mfma_f32_16x16x32_bf16 v[20:23], v[132:135], v[192:195], v[20:23]
	v_mfma_f32_16x16x32_bf16 v[16:19], v[140:143], v[192:195], v[16:19]
	s_barrier
	s_add_i32 s66, s54, 0x14000
	s_mov_b32 m0, s66
	s_add_u32 s64, s2, 0x40000
	s_addc_u32 s65, s3, 0
	global_load_lds_dwordx4 v160, s[64:65]
	s_add_i32 m0, s66, 0x2000
	s_nop 0
	global_load_lds_dwordx4 v162, s[64:65]
	s_waitcnt vmcnt(6)
	s_barrier
	v_mfma_f32_16x16x32_bf16 v[44:47], v[196:199], v[144:147], 0
	v_mfma_f32_16x16x32_bf16 v[40:43], v[210:213], v[144:147], 0
	v_mfma_f32_16x16x32_bf16 v[28:31], v[196:199], v[152:155], 0
	v_mfma_f32_16x16x32_bf16 v[24:27], v[210:213], v[152:155], 0
	v_mfma_f32_16x16x32_bf16 v[12:15], v[196:199], v[180:183], 0
	v_mfma_f32_16x16x32_bf16 v[8:11], v[210:213], v[180:183], 0
	v_mfma_f32_16x16x32_bf16 v[4:7], v[196:199], v[188:191], 0
	v_mfma_f32_16x16x32_bf16 v[0:3], v[210:213], v[188:191], 0
	v_mfma_f32_16x16x32_bf16 v[44:47], v[200:203], v[148:151], v[44:47]
	v_mfma_f32_16x16x32_bf16 v[40:43], v[214:217], v[148:151], v[40:43]
	v_mfma_f32_16x16x32_bf16 v[28:31], v[200:203], v[156:159], v[28:31]
	v_mfma_f32_16x16x32_bf16 v[24:27], v[214:217], v[156:159], v[24:27]
	v_mfma_f32_16x16x32_bf16 v[12:15], v[200:203], v[184:187], v[12:15]
	v_mfma_f32_16x16x32_bf16 v[8:11], v[214:217], v[184:187], v[8:11]
	v_mfma_f32_16x16x32_bf16 v[4:7], v[200:203], v[192:195], v[4:7]
	v_mfma_f32_16x16x32_bf16 v[0:3], v[214:217], v[192:195], v[0:3]
	s_barrier
	ds_read_b128 v[128:131], v208 offset:32768
	ds_read_b128 v[132:135], v208 offset:33792
	ds_read_b128 v[136:139], v208 offset:34816
	ds_read_b128 v[140:143], v208 offset:35840
	s_add_u32 s8, s8, 0x40000
	s_addc_u32 s9, s9, 0
	s_mov_b32 m0, s56
	ds_read_b128 v[144:147], v209 offset:32768
	ds_read_b128 v[148:151], v209 offset:33792
	ds_read_b128 v[152:155], v209 offset:34816
	ds_read_b128 v[156:159], v209 offset:35840
	ds_read_b128 v[180:183], v209 offset:36864
	ds_read_b128 v[184:187], v209 offset:37888
	ds_read_b128 v[188:191], v209 offset:38912
	global_load_lds_dwordx4 v160, s[8:9]
	s_mov_b32 m0, s57
	ds_read_b128 v[192:195], v209 offset:39936
	global_load_lds_dwordx4 v162, s[8:9]
	s_waitcnt lgkmcnt(8)
	s_barrier
	s_waitcnt lgkmcnt(0)
	v_mfma_f32_16x16x32_bf16 v[124:127], v[128:131], v[144:147], v[124:127]
	v_mfma_f32_16x16x32_bf16 v[120:123], v[136:139], v[144:147], v[120:123]
	v_mfma_f32_16x16x32_bf16 v[116:119], v[128:131], v[152:155], v[116:119]
	v_mfma_f32_16x16x32_bf16 v[112:115], v[136:139], v[152:155], v[112:115]
	v_mfma_f32_16x16x32_bf16 v[100:103], v[128:131], v[180:183], v[100:103]
	v_mfma_f32_16x16x32_bf16 v[96:99], v[136:139], v[180:183], v[96:99]
	v_mfma_f32_16x16x32_bf16 v[84:87], v[128:131], v[188:191], v[84:87]
	v_mfma_f32_16x16x32_bf16 v[80:83], v[136:139], v[188:191], v[80:83]
	v_mfma_f32_16x16x32_bf16 v[124:127], v[132:135], v[148:151], v[124:127]
	v_mfma_f32_16x16x32_bf16 v[120:123], v[140:143], v[148:151], v[120:123]
	v_mfma_f32_16x16x32_bf16 v[116:119], v[132:135], v[156:159], v[116:119]
	v_mfma_f32_16x16x32_bf16 v[112:115], v[140:143], v[156:159], v[112:115]
	v_mfma_f32_16x16x32_bf16 v[100:103], v[132:135], v[184:187], v[100:103]
	v_mfma_f32_16x16x32_bf16 v[96:99], v[140:143], v[184:187], v[96:99]
	v_mfma_f32_16x16x32_bf16 v[84:87], v[132:135], v[192:195], v[84:87]
	v_mfma_f32_16x16x32_bf16 v[80:83], v[140:143], v[192:195], v[80:83]
	s_barrier
	s_add_i32 s9, s54, 0x18000
	s_mov_b32 m0, s9
	ds_read_b128 v[196:199], v208 offset:49152
	ds_read_b128 v[200:203], v208 offset:50176
	ds_read_b128 v[210:213], v208 offset:51200
	global_load_lds_dwordx4 v160, s[98:99]
	s_add_i32 m0, s9, 0x2000
	ds_read_b128 v[214:217], v208 offset:52224
	global_load_lds_dwordx4 v162, s[98:99]
	s_barrier
	s_waitcnt lgkmcnt(0)
	v_mfma_f32_16x16x32_bf16 v[108:111], v[196:199], v[144:147], v[108:111]
	v_mfma_f32_16x16x32_bf16 v[104:107], v[210:213], v[144:147], v[104:107]
	v_mfma_f32_16x16x32_bf16 v[92:95], v[196:199], v[152:155], v[92:95]
	v_mfma_f32_16x16x32_bf16 v[88:91], v[210:213], v[152:155], v[88:91]
	v_mfma_f32_16x16x32_bf16 v[76:79], v[196:199], v[180:183], v[76:79]
	v_mfma_f32_16x16x32_bf16 v[72:75], v[210:213], v[180:183], v[72:75]
	v_mfma_f32_16x16x32_bf16 v[68:71], v[196:199], v[188:191], v[68:71]
	v_mfma_f32_16x16x32_bf16 v[64:67], v[210:213], v[188:191], v[64:67]
	v_mfma_f32_16x16x32_bf16 v[108:111], v[200:203], v[148:151], v[108:111]
	v_mfma_f32_16x16x32_bf16 v[104:107], v[214:217], v[148:151], v[104:107]
	v_mfma_f32_16x16x32_bf16 v[92:95], v[200:203], v[156:159], v[92:95]
	v_mfma_f32_16x16x32_bf16 v[88:91], v[214:217], v[156:159], v[88:91]
	v_mfma_f32_16x16x32_bf16 v[76:79], v[200:203], v[184:187], v[76:79]
	v_mfma_f32_16x16x32_bf16 v[72:75], v[214:217], v[184:187], v[72:75]
	v_mfma_f32_16x16x32_bf16 v[68:71], v[200:203], v[192:195], v[68:71]
	v_mfma_f32_16x16x32_bf16 v[64:67], v[214:217], v[192:195], v[64:67]
	s_mov_b32 m0, s60
	s_barrier
	ds_read_b128 v[144:147], v209 offset:49152
	ds_read_b128 v[148:151], v209 offset:50176
	ds_read_b128 v[152:155], v209 offset:51200
	ds_read_b128 v[156:159], v209 offset:52224
	ds_read_b128 v[180:183], v209 offset:53248
	ds_read_b128 v[184:187], v209 offset:54272
	ds_read_b128 v[188:191], v209 offset:55296
	global_load_lds_dwordx4 v160, s[100:101]
	s_mov_b32 m0, s61
	ds_read_b128 v[192:195], v209 offset:56320
	global_load_lds_dwordx4 v162, s[100:101]
	s_barrier
	s_waitcnt lgkmcnt(0)
	v_mfma_f32_16x16x32_bf16 v[60:63], v[128:131], v[144:147], v[60:63]
	v_mfma_f32_16x16x32_bf16 v[56:59], v[136:139], v[144:147], v[56:59]
	v_mfma_f32_16x16x32_bf16 v[52:55], v[128:131], v[152:155], v[52:55]
	v_mfma_f32_16x16x32_bf16 v[48:51], v[136:139], v[152:155], v[48:51]
	v_mfma_f32_16x16x32_bf16 v[36:39], v[128:131], v[180:183], v[36:39]
	v_mfma_f32_16x16x32_bf16 v[32:35], v[136:139], v[180:183], v[32:35]
	v_mfma_f32_16x16x32_bf16 v[20:23], v[128:131], v[188:191], v[20:23]
	v_mfma_f32_16x16x32_bf16 v[16:19], v[136:139], v[188:191], v[16:19]
	v_mfma_f32_16x16x32_bf16 v[60:63], v[132:135], v[148:151], v[60:63]
	v_mfma_f32_16x16x32_bf16 v[56:59], v[140:143], v[148:151], v[56:59]
	v_mfma_f32_16x16x32_bf16 v[52:55], v[132:135], v[156:159], v[52:55]
	v_mfma_f32_16x16x32_bf16 v[48:51], v[140:143], v[156:159], v[48:51]
	v_mfma_f32_16x16x32_bf16 v[36:39], v[132:135], v[184:187], v[36:39]
	v_mfma_f32_16x16x32_bf16 v[32:35], v[140:143], v[184:187], v[32:35]
	v_mfma_f32_16x16x32_bf16 v[20:23], v[132:135], v[192:195], v[20:23]
	v_mfma_f32_16x16x32_bf16 v[16:19], v[140:143], v[192:195], v[16:19]
	s_barrier
	s_add_i32 s8, s54, 0x1c000
	s_mov_b32 m0, s8
	s_add_u32 s2, s2, 0x40080
	s_addc_u32 s3, s3, 0
	global_load_lds_dwordx4 v160, s[2:3]
	s_add_i32 m0, s8, 0x2000
	s_nop 0
	global_load_lds_dwordx4 v162, s[2:3]
	s_waitcnt vmcnt(6)
	s_barrier
	v_mfma_f32_16x16x32_bf16 v[44:47], v[196:199], v[144:147], v[44:47]
	v_mfma_f32_16x16x32_bf16 v[40:43], v[210:213], v[144:147], v[40:43]
	v_mfma_f32_16x16x32_bf16 v[28:31], v[196:199], v[152:155], v[28:31]
	v_mfma_f32_16x16x32_bf16 v[24:27], v[210:213], v[152:155], v[24:27]
	v_mfma_f32_16x16x32_bf16 v[12:15], v[196:199], v[180:183], v[12:15]
	v_mfma_f32_16x16x32_bf16 v[8:11], v[210:213], v[180:183], v[8:11]
	v_mfma_f32_16x16x32_bf16 v[4:7], v[196:199], v[188:191], v[4:7]
	v_mfma_f32_16x16x32_bf16 v[0:3], v[210:213], v[188:191], v[0:3]
	v_mfma_f32_16x16x32_bf16 v[44:47], v[200:203], v[148:151], v[44:47]
	v_mfma_f32_16x16x32_bf16 v[40:43], v[214:217], v[148:151], v[40:43]
	v_mfma_f32_16x16x32_bf16 v[28:31], v[200:203], v[156:159], v[28:31]
	v_mfma_f32_16x16x32_bf16 v[24:27], v[214:217], v[156:159], v[24:27]
	v_mfma_f32_16x16x32_bf16 v[12:15], v[200:203], v[184:187], v[12:15]
	v_mfma_f32_16x16x32_bf16 v[8:11], v[214:217], v[184:187], v[8:11]
	v_mfma_f32_16x16x32_bf16 v[4:7], v[200:203], v[192:195], v[4:7]
	v_mfma_f32_16x16x32_bf16 v[0:3], v[214:217], v[192:195], v[0:3]
	s_add_i32 s41, s41, 2
	s_add_u32 s6, s6, 0x100
	s_addc_u32 s7, s7, 0
	s_add_u32 s39, s39, 0x100
	s_addc_u32 s40, s40, 0
	s_cmp_gt_u32 s41, 13
	s_barrier
.LBB0_355:
	s_add_u32 s2, s6, 0xfffc0080
	s_addc_u32 s3, s7, -1
	ds_read_b128 v[128:131], v208
	ds_read_b128 v[132:135], v208 offset:1024
	ds_read_b128 v[136:139], v208 offset:2048
	ds_read_b128 v[140:143], v208 offset:3072
	s_cmp_eq_u32 s41, 12
	s_cselect_b32 s9, s1, s3
	s_cselect_b32 s8, s31, s2
	s_cselect_b32 s3, s29, s40
	s_cselect_b32 s2, s38, s39
	s_add_i32 m0, s21, 0xc000
	ds_read_b128 v[144:147], v209
	ds_read_b128 v[148:151], v209 offset:1024
	ds_read_b128 v[152:155], v209 offset:2048
	ds_read_b128 v[156:159], v209 offset:3072
	ds_read_b128 v[180:183], v209 offset:4096
	ds_read_b128 v[184:187], v209 offset:5120
	ds_read_b128 v[188:191], v209 offset:6144
	global_load_lds_dwordx4 v164, s[6:7]
	s_add_i32 m0, s21, 0xe000
	ds_read_b128 v[192:195], v209 offset:7168
	global_load_lds_dwordx4 v166, s[6:7]
	s_waitcnt lgkmcnt(8)
	s_barrier
	s_waitcnt lgkmcnt(0)
	v_mfma_f32_16x16x32_bf16 v[124:127], v[128:131], v[144:147], v[124:127]
	v_mfma_f32_16x16x32_bf16 v[120:123], v[136:139], v[144:147], v[120:123]
	v_mfma_f32_16x16x32_bf16 v[116:119], v[128:131], v[152:155], v[116:119]
	v_mfma_f32_16x16x32_bf16 v[112:115], v[136:139], v[152:155], v[112:115]
	v_mfma_f32_16x16x32_bf16 v[100:103], v[128:131], v[180:183], v[100:103]
	v_mfma_f32_16x16x32_bf16 v[96:99], v[136:139], v[180:183], v[96:99]
	v_mfma_f32_16x16x32_bf16 v[84:87], v[128:131], v[188:191], v[84:87]
	v_mfma_f32_16x16x32_bf16 v[80:83], v[136:139], v[188:191], v[80:83]
	v_mfma_f32_16x16x32_bf16 v[124:127], v[132:135], v[148:151], v[124:127]
	v_mfma_f32_16x16x32_bf16 v[120:123], v[140:143], v[148:151], v[120:123]
	v_mfma_f32_16x16x32_bf16 v[116:119], v[132:135], v[156:159], v[116:119]
	v_mfma_f32_16x16x32_bf16 v[112:115], v[140:143], v[156:159], v[112:115]
	v_mfma_f32_16x16x32_bf16 v[100:103], v[132:135], v[184:187], v[100:103]
	v_mfma_f32_16x16x32_bf16 v[96:99], v[140:143], v[184:187], v[96:99]
	v_mfma_f32_16x16x32_bf16 v[84:87], v[132:135], v[192:195], v[84:87]
	v_mfma_f32_16x16x32_bf16 v[80:83], v[140:143], v[192:195], v[80:83]
	s_barrier
	s_add_i32 s64, s54, 0x10000
	s_add_u32 s98, s2, 0x80
	s_addc_u32 s99, s3, 0
	s_mov_b32 m0, s64
	ds_read_b128 v[196:199], v208 offset:16384
	ds_read_b128 v[200:203], v208 offset:17408
	ds_read_b128 v[210:213], v208 offset:18432
	global_load_lds_dwordx4 v160, s[2:3]
	s_add_i32 m0, s64, 0x2000
	ds_read_b128 v[214:217], v208 offset:19456
	global_load_lds_dwordx4 v162, s[2:3]
	s_barrier
	s_waitcnt lgkmcnt(0)
	v_mfma_f32_16x16x32_bf16 v[108:111], v[196:199], v[144:147], v[108:111]
	v_mfma_f32_16x16x32_bf16 v[104:107], v[210:213], v[144:147], v[104:107]
	v_mfma_f32_16x16x32_bf16 v[92:95], v[196:199], v[152:155], v[92:95]
	v_mfma_f32_16x16x32_bf16 v[88:91], v[210:213], v[152:155], v[88:91]
	v_mfma_f32_16x16x32_bf16 v[76:79], v[196:199], v[180:183], v[76:79]
	v_mfma_f32_16x16x32_bf16 v[72:75], v[210:213], v[180:183], v[72:75]
	v_mfma_f32_16x16x32_bf16 v[68:71], v[196:199], v[188:191], v[68:71]
	v_mfma_f32_16x16x32_bf16 v[64:67], v[210:213], v[188:191], v[64:67]
	v_mfma_f32_16x16x32_bf16 v[108:111], v[200:203], v[148:151], v[108:111]
	v_mfma_f32_16x16x32_bf16 v[104:107], v[214:217], v[148:151], v[104:107]
	v_mfma_f32_16x16x32_bf16 v[92:95], v[200:203], v[156:159], v[92:95]
	v_mfma_f32_16x16x32_bf16 v[88:91], v[214:217], v[156:159], v[88:91]
	v_mfma_f32_16x16x32_bf16 v[76:79], v[200:203], v[184:187], v[76:79]
	v_mfma_f32_16x16x32_bf16 v[72:75], v[214:217], v[184:187], v[72:75]
	v_mfma_f32_16x16x32_bf16 v[68:71], v[200:203], v[192:195], v[68:71]
	v_mfma_f32_16x16x32_bf16 v[64:67], v[214:217], v[192:195], v[64:67]
	s_mov_b32 m0, s21
	s_add_u32 s100, s8, 0x80
	s_addc_u32 s101, s9, 0
	s_barrier
	ds_read_b128 v[144:147], v209 offset:16384
	ds_read_b128 v[148:151], v209 offset:17408
	ds_read_b128 v[152:155], v209 offset:18432
	ds_read_b128 v[156:159], v209 offset:19456
	ds_read_b128 v[180:183], v209 offset:20480
	ds_read_b128 v[184:187], v209 offset:21504
	ds_read_b128 v[188:191], v209 offset:22528
	global_load_lds_dwordx4 v160, s[8:9]
	s_mov_b32 m0, s55
	ds_read_b128 v[192:195], v209 offset:23552
	global_load_lds_dwordx4 v162, s[8:9]
	s_barrier
	s_waitcnt lgkmcnt(0)
	v_mfma_f32_16x16x32_bf16 v[60:63], v[128:131], v[144:147], v[60:63]
	v_mfma_f32_16x16x32_bf16 v[56:59], v[136:139], v[144:147], v[56:59]
	v_mfma_f32_16x16x32_bf16 v[52:55], v[128:131], v[152:155], v[52:55]
	v_mfma_f32_16x16x32_bf16 v[48:51], v[136:139], v[152:155], v[48:51]
	v_mfma_f32_16x16x32_bf16 v[36:39], v[128:131], v[180:183], v[36:39]
	v_mfma_f32_16x16x32_bf16 v[32:35], v[136:139], v[180:183], v[32:35]
	v_mfma_f32_16x16x32_bf16 v[20:23], v[128:131], v[188:191], v[20:23]
	v_mfma_f32_16x16x32_bf16 v[16:19], v[136:139], v[188:191], v[16:19]
	v_mfma_f32_16x16x32_bf16 v[60:63], v[132:135], v[148:151], v[60:63]
	v_mfma_f32_16x16x32_bf16 v[56:59], v[140:143], v[148:151], v[56:59]
	v_mfma_f32_16x16x32_bf16 v[52:55], v[132:135], v[156:159], v[52:55]
	v_mfma_f32_16x16x32_bf16 v[48:51], v[140:143], v[156:159], v[48:51]
	v_mfma_f32_16x16x32_bf16 v[36:39], v[132:135], v[184:187], v[36:39]
	v_mfma_f32_16x16x32_bf16 v[32:35], v[140:143], v[184:187], v[32:35]
	v_mfma_f32_16x16x32_bf16 v[20:23], v[132:135], v[192:195], v[20:23]
	v_mfma_f32_16x16x32_bf16 v[16:19], v[140:143], v[192:195], v[16:19]
	s_barrier
	s_add_i32 s66, s54, 0x14000
	s_mov_b32 m0, s66
	s_add_u32 s64, s2, 0x40000
	s_addc_u32 s65, s3, 0
	global_load_lds_dwordx4 v160, s[64:65]
	s_add_i32 m0, s66, 0x2000
	s_nop 0
	global_load_lds_dwordx4 v162, s[64:65]
	s_waitcnt vmcnt(6)
	s_barrier
	v_mfma_f32_16x16x32_bf16 v[44:47], v[196:199], v[144:147], v[44:47]
	v_mfma_f32_16x16x32_bf16 v[40:43], v[210:213], v[144:147], v[40:43]
	v_mfma_f32_16x16x32_bf16 v[28:31], v[196:199], v[152:155], v[28:31]
	v_mfma_f32_16x16x32_bf16 v[24:27], v[210:213], v[152:155], v[24:27]
	v_mfma_f32_16x16x32_bf16 v[12:15], v[196:199], v[180:183], v[12:15]
	v_mfma_f32_16x16x32_bf16 v[8:11], v[210:213], v[180:183], v[8:11]
	v_mfma_f32_16x16x32_bf16 v[4:7], v[196:199], v[188:191], v[4:7]
	v_mfma_f32_16x16x32_bf16 v[0:3], v[210:213], v[188:191], v[0:3]
	v_mfma_f32_16x16x32_bf16 v[44:47], v[200:203], v[148:151], v[44:47]
	v_mfma_f32_16x16x32_bf16 v[40:43], v[214:217], v[148:151], v[40:43]
	v_mfma_f32_16x16x32_bf16 v[28:31], v[200:203], v[156:159], v[28:31]
	v_mfma_f32_16x16x32_bf16 v[24:27], v[214:217], v[156:159], v[24:27]
	v_mfma_f32_16x16x32_bf16 v[12:15], v[200:203], v[184:187], v[12:15]
	v_mfma_f32_16x16x32_bf16 v[8:11], v[214:217], v[184:187], v[8:11]
	v_mfma_f32_16x16x32_bf16 v[4:7], v[200:203], v[192:195], v[4:7]
	v_mfma_f32_16x16x32_bf16 v[0:3], v[214:217], v[192:195], v[0:3]
	s_barrier
	ds_read_b128 v[128:131], v208 offset:32768
	ds_read_b128 v[132:135], v208 offset:33792
	ds_read_b128 v[136:139], v208 offset:34816
	ds_read_b128 v[140:143], v208 offset:35840
	s_add_u32 s8, s8, 0x40000
	s_addc_u32 s9, s9, 0
	s_mov_b32 m0, s56
	ds_read_b128 v[144:147], v209 offset:32768
	ds_read_b128 v[148:151], v209 offset:33792
	ds_read_b128 v[152:155], v209 offset:34816
	ds_read_b128 v[156:159], v209 offset:35840
	ds_read_b128 v[180:183], v209 offset:36864
	ds_read_b128 v[184:187], v209 offset:37888
	ds_read_b128 v[188:191], v209 offset:38912
	global_load_lds_dwordx4 v160, s[8:9]
	s_mov_b32 m0, s57
	ds_read_b128 v[192:195], v209 offset:39936
	global_load_lds_dwordx4 v162, s[8:9]
	s_waitcnt lgkmcnt(8)
	s_barrier
	s_waitcnt lgkmcnt(0)
	v_mfma_f32_16x16x32_bf16 v[124:127], v[128:131], v[144:147], v[124:127]
	v_mfma_f32_16x16x32_bf16 v[120:123], v[136:139], v[144:147], v[120:123]
	v_mfma_f32_16x16x32_bf16 v[116:119], v[128:131], v[152:155], v[116:119]
	v_mfma_f32_16x16x32_bf16 v[112:115], v[136:139], v[152:155], v[112:115]
	v_mfma_f32_16x16x32_bf16 v[100:103], v[128:131], v[180:183], v[100:103]
	v_mfma_f32_16x16x32_bf16 v[96:99], v[136:139], v[180:183], v[96:99]
	v_mfma_f32_16x16x32_bf16 v[84:87], v[128:131], v[188:191], v[84:87]
	v_mfma_f32_16x16x32_bf16 v[80:83], v[136:139], v[188:191], v[80:83]
	v_mfma_f32_16x16x32_bf16 v[124:127], v[132:135], v[148:151], v[124:127]
	v_mfma_f32_16x16x32_bf16 v[120:123], v[140:143], v[148:151], v[120:123]
	v_mfma_f32_16x16x32_bf16 v[116:119], v[132:135], v[156:159], v[116:119]
	v_mfma_f32_16x16x32_bf16 v[112:115], v[140:143], v[156:159], v[112:115]
	v_mfma_f32_16x16x32_bf16 v[100:103], v[132:135], v[184:187], v[100:103]
	v_mfma_f32_16x16x32_bf16 v[96:99], v[140:143], v[184:187], v[96:99]
	v_mfma_f32_16x16x32_bf16 v[84:87], v[132:135], v[192:195], v[84:87]
	v_mfma_f32_16x16x32_bf16 v[80:83], v[140:143], v[192:195], v[80:83]
	s_barrier
	s_add_i32 s9, s54, 0x18000
	s_mov_b32 m0, s9
	ds_read_b128 v[196:199], v208 offset:49152
	ds_read_b128 v[200:203], v208 offset:50176
	ds_read_b128 v[210:213], v208 offset:51200
	global_load_lds_dwordx4 v160, s[98:99]
	s_add_i32 m0, s9, 0x2000
	ds_read_b128 v[214:217], v208 offset:52224
	global_load_lds_dwordx4 v162, s[98:99]
	s_barrier
	s_waitcnt lgkmcnt(0)
	v_mfma_f32_16x16x32_bf16 v[108:111], v[196:199], v[144:147], v[108:111]
	v_mfma_f32_16x16x32_bf16 v[104:107], v[210:213], v[144:147], v[104:107]
	v_mfma_f32_16x16x32_bf16 v[92:95], v[196:199], v[152:155], v[92:95]
	v_mfma_f32_16x16x32_bf16 v[88:91], v[210:213], v[152:155], v[88:91]
	v_mfma_f32_16x16x32_bf16 v[76:79], v[196:199], v[180:183], v[76:79]
	v_mfma_f32_16x16x32_bf16 v[72:75], v[210:213], v[180:183], v[72:75]
	v_mfma_f32_16x16x32_bf16 v[68:71], v[196:199], v[188:191], v[68:71]
	v_mfma_f32_16x16x32_bf16 v[64:67], v[210:213], v[188:191], v[64:67]
	v_mfma_f32_16x16x32_bf16 v[108:111], v[200:203], v[148:151], v[108:111]
	v_mfma_f32_16x16x32_bf16 v[104:107], v[214:217], v[148:151], v[104:107]
	v_mfma_f32_16x16x32_bf16 v[92:95], v[200:203], v[156:159], v[92:95]
	v_mfma_f32_16x16x32_bf16 v[88:91], v[214:217], v[156:159], v[88:91]
	v_mfma_f32_16x16x32_bf16 v[76:79], v[200:203], v[184:187], v[76:79]
	v_mfma_f32_16x16x32_bf16 v[72:75], v[214:217], v[184:187], v[72:75]
	v_mfma_f32_16x16x32_bf16 v[68:71], v[200:203], v[192:195], v[68:71]
	v_mfma_f32_16x16x32_bf16 v[64:67], v[214:217], v[192:195], v[64:67]
	s_mov_b32 m0, s60
	s_barrier
	ds_read_b128 v[144:147], v209 offset:49152
	ds_read_b128 v[148:151], v209 offset:50176
	ds_read_b128 v[152:155], v209 offset:51200
	ds_read_b128 v[156:159], v209 offset:52224
	ds_read_b128 v[180:183], v209 offset:53248
	ds_read_b128 v[184:187], v209 offset:54272
	ds_read_b128 v[188:191], v209 offset:55296
	global_load_lds_dwordx4 v160, s[100:101]
	s_mov_b32 m0, s61
	ds_read_b128 v[192:195], v209 offset:56320
	global_load_lds_dwordx4 v162, s[100:101]
	s_barrier
	s_waitcnt lgkmcnt(0)
	v_mfma_f32_16x16x32_bf16 v[60:63], v[128:131], v[144:147], v[60:63]
	v_mfma_f32_16x16x32_bf16 v[56:59], v[136:139], v[144:147], v[56:59]
	v_mfma_f32_16x16x32_bf16 v[52:55], v[128:131], v[152:155], v[52:55]
	v_mfma_f32_16x16x32_bf16 v[48:51], v[136:139], v[152:155], v[48:51]
	v_mfma_f32_16x16x32_bf16 v[36:39], v[128:131], v[180:183], v[36:39]
	v_mfma_f32_16x16x32_bf16 v[32:35], v[136:139], v[180:183], v[32:35]
	v_mfma_f32_16x16x32_bf16 v[20:23], v[128:131], v[188:191], v[20:23]
	v_mfma_f32_16x16x32_bf16 v[16:19], v[136:139], v[188:191], v[16:19]
	v_mfma_f32_16x16x32_bf16 v[60:63], v[132:135], v[148:151], v[60:63]
	v_mfma_f32_16x16x32_bf16 v[56:59], v[140:143], v[148:151], v[56:59]
	v_mfma_f32_16x16x32_bf16 v[52:55], v[132:135], v[156:159], v[52:55]
	v_mfma_f32_16x16x32_bf16 v[48:51], v[140:143], v[156:159], v[48:51]
	v_mfma_f32_16x16x32_bf16 v[36:39], v[132:135], v[184:187], v[36:39]
	v_mfma_f32_16x16x32_bf16 v[32:35], v[140:143], v[184:187], v[32:35]
	v_mfma_f32_16x16x32_bf16 v[20:23], v[132:135], v[192:195], v[20:23]
	v_mfma_f32_16x16x32_bf16 v[16:19], v[140:143], v[192:195], v[16:19]
	s_barrier
	s_add_i32 s8, s54, 0x1c000
	s_mov_b32 m0, s8
	s_add_u32 s2, s2, 0x40080
	s_addc_u32 s3, s3, 0
	global_load_lds_dwordx4 v160, s[2:3]
	s_add_i32 m0, s8, 0x2000
	s_nop 0
	global_load_lds_dwordx4 v162, s[2:3]
	s_waitcnt vmcnt(6)
	s_barrier
	v_mfma_f32_16x16x32_bf16 v[44:47], v[196:199], v[144:147], v[44:47]
	v_mfma_f32_16x16x32_bf16 v[40:43], v[210:213], v[144:147], v[40:43]
	v_mfma_f32_16x16x32_bf16 v[28:31], v[196:199], v[152:155], v[28:31]
	v_mfma_f32_16x16x32_bf16 v[24:27], v[210:213], v[152:155], v[24:27]
	v_mfma_f32_16x16x32_bf16 v[12:15], v[196:199], v[180:183], v[12:15]
	v_mfma_f32_16x16x32_bf16 v[8:11], v[210:213], v[180:183], v[8:11]
	v_mfma_f32_16x16x32_bf16 v[4:7], v[196:199], v[188:191], v[4:7]
	v_mfma_f32_16x16x32_bf16 v[0:3], v[210:213], v[188:191], v[0:3]
	v_mfma_f32_16x16x32_bf16 v[44:47], v[200:203], v[148:151], v[44:47]
	v_mfma_f32_16x16x32_bf16 v[40:43], v[214:217], v[148:151], v[40:43]
	v_mfma_f32_16x16x32_bf16 v[28:31], v[200:203], v[156:159], v[28:31]
	v_mfma_f32_16x16x32_bf16 v[24:27], v[214:217], v[156:159], v[24:27]
	v_mfma_f32_16x16x32_bf16 v[12:15], v[200:203], v[184:187], v[12:15]
	v_mfma_f32_16x16x32_bf16 v[8:11], v[214:217], v[184:187], v[8:11]
	v_mfma_f32_16x16x32_bf16 v[4:7], v[200:203], v[192:195], v[4:7]
	v_mfma_f32_16x16x32_bf16 v[0:3], v[214:217], v[192:195], v[0:3]
	s_add_i32 s41, s41, 2
	s_add_u32 s6, s6, 0x100
	s_addc_u32 s7, s7, 0
	s_add_u32 s39, s39, 0x100
	s_addc_u32 s40, s40, 0
	s_cmp_gt_u32 s41, 13
	s_barrier
	s_cbranch_scc0 .LBB0_355
	s_lshl_b32 s1, s0, 8
	v_mov_b32_e32 v211, v206
	v_mov_b32_e32 v210, v207
	s_add_i32 s1, s1, s59
	s_cmp_lt_i32 s20, 3
	v_add_u32_e32 v180, s1, v211
	s_mov_b64 s[2:3], -1
	s_cbranch_scc0 .LBB0_490
	s_cmp_gt_i32 s0, 15
	s_cselect_b64 s[2:3], -1, 0
	s_cmp_lt_i32 s0, 16
	s_cselect_b64 s[38:39], -1, 0
	s_cmp_eq_u32 s20, 2
	s_cselect_b64 s[8:9], -1, 0
	s_cmp_lg_u32 s20, 2
	s_cselect_b64 s[0:1], -1, 0
	s_and_b64 s[40:41], s[8:9], s[22:23]
	v_lshlrev_b32_e32 v182, 2, v210
	s_mov_b64 s[6:7], -1
	s_and_b64 vcc, exec, s[40:41]
	v_ashrrev_i32_e32 v183, 31, v182
	s_cbranch_vccnz .LBB0_447
	s_and_b64 s[6:7], s[8:9], exec
	s_cselect_b32 s6, s46, s44
	s_cselect_b32 s7, s47, s45
	v_mov_b32_e32 v128, s7
	v_mov_b32_e32 v129, s6
	v_lshl_add_u64 v[128:129], v[182:183], 2, v[128:129]
	global_load_dwordx4 v[140:143], v[128:129], off
	global_load_dwordx4 v[136:139], v[128:129], off offset:64
	global_load_dwordx4 v[132:135], v[128:129], off offset:128
	s_nop 0
	global_load_dwordx4 v[128:131], v[128:129], off offset:192
	v_mul_f32_e32 v144, v125, v125
	v_mul_f32_e32 v145, v127, v127
	v_fmac_f32_e32 v144, v124, v124
	v_fmac_f32_e32 v145, v126, v126
	v_add_f32_e32 v144, v144, v145
	v_mul_f32_e32 v145, v121, v121
	v_mul_f32_e32 v146, v123, v123
	v_fmac_f32_e32 v145, v120, v120
	v_fmac_f32_e32 v146, v122, v122
	v_add_f32_e32 v145, v145, v146
	v_add_f32_e32 v144, v144, v145
	v_mul_f32_e32 v145, v109, v109
	v_mul_f32_e32 v146, v111, v111
	v_fmac_f32_e32 v145, v108, v108
	v_fmac_f32_e32 v146, v110, v110
	v_add_f32_e32 v145, v145, v146
	v_add_f32_e32 v144, v144, v145
	v_mul_f32_e32 v145, v105, v105
	v_mul_f32_e32 v146, v107, v107
	v_fmac_f32_e32 v145, v104, v104
	v_fmac_f32_e32 v146, v106, v106
	v_add_f32_e32 v145, v145, v146
	v_add_f32_e32 v144, v144, v145
	v_mov_b32_e32 v145, v144
	s_nop 1
	v_permlane16_swap_b32_e32 v144, v145
	v_add_f32_e32 v144, v144, v145
	v_mov_b32_e32 v145, v144
	s_nop 1
	v_permlane32_swap_b32_e32 v144, v145
	v_add_f32_e32 v144, v144, v145
	v_fmamk_f32 v144, v144, 0x3c800000, v225
	v_cmp_gt_f32_e32 vcc, s93, v144
	v_mul_f32_e32 v145, 0x4b800000, v144
	v_and_b32_e32 v202, 63, v211
	v_cndmask_b32_e32 v144, v144, v145, vcc
	v_rsq_f32_e32 v144, v144
	v_cndmask_b32_e64 v168, 0, 1, s[2:3]
	v_cmp_ne_u32_e64 s[6:7], 1, v168
	v_lshlrev_b32_e32 v186, 7, v202
	v_mul_f32_e32 v145, 0x45800000, v144
	v_cndmask_b32_e32 v152, v144, v145, vcc
	v_pk_mul_f32 v[144:145], v[124:125], v[152:153] op_sel_hi:[1,0]
	v_pk_mul_f32 v[146:147], v[126:127], v[152:153] op_sel_hi:[1,0]
	v_pk_mul_f32 v[148:149], v[108:109], v[152:153] op_sel_hi:[1,0]
	v_pk_mul_f32 v[150:151], v[110:111], v[152:153] op_sel_hi:[1,0]
	v_pk_mul_f32 v[184:185], v[104:105], v[152:153] op_sel_hi:[1,0]
	s_andn2_b64 vcc, exec, s[2:3]
	s_waitcnt vmcnt(0)
	v_pk_mul_f32 v[158:159], v[142:143], v[146:147]
	v_pk_mul_f32 v[156:157], v[140:141], v[144:145]
	v_pk_mul_f32 v[144:145], v[120:121], v[152:153] op_sel_hi:[1,0]
	v_pk_mul_f32 v[146:147], v[122:123], v[152:153] op_sel_hi:[1,0]
	v_pk_mul_f32 v[152:153], v[106:107], v[152:153] op_sel_hi:[1,0]
	v_pk_mul_f32 v[146:147], v[138:139], v[146:147]
	v_pk_mul_f32 v[144:145], v[136:137], v[144:145]
	v_pk_mul_f32 v[150:151], v[134:135], v[150:151]
	v_pk_mul_f32 v[148:149], v[132:133], v[148:149]
	v_pk_mul_f32 v[154:155], v[130:131], v[152:153]
	v_pk_mul_f32 v[152:153], v[128:129], v[184:185]
	v_lshl_add_u64 v[184:185], v[182:183], 3, s[18:19]
	s_cbranch_vccnz .LBB0_360
	v_lshlrev_b32_e32 v168, 1, v180
	v_and_b32_e32 v168, 0xf80, v168
	v_lshl_add_u64 v[188:189], v[184:185], 0, v[168:169]
	global_load_dwordx4 v[190:193], v[188:189], off offset:16
	global_load_dwordx4 v[194:197], v[188:189], off
	v_mov_b32_e32 v187, v169
	s_waitcnt vmcnt(0)
	v_mul_f32_e32 v198, v158, v190
	v_mov_b32_e32 v188, v194
	v_mov_b32_e32 v189, v196
	v_mov_b32_e32 v196, v195
	v_mul_f32_e32 v200, v146, v191
	v_mul_f32_e32 v204, v146, v190
	v_mul_f32_e32 v212, v158, v191
	v_mov_b32_e32 v146, v159
	v_mov_b32_e32 v158, v147
	v_pk_mul_f32 v[194:195], v[144:145], v[196:197]
	v_pk_mul_f32 v[144:145], v[144:145], v[188:189]
	v_pk_mul_f32 v[190:191], v[146:147], v[192:193]
	v_pk_mul_f32 v[146:147], v[158:159], v[192:193]
	v_lshl_add_u64 v[192:193], v[184:185], 0, v[186:187]
	v_mov_b32_e32 v199, v190
	v_mov_b32_e32 v201, v191
	v_pk_fma_f32 v[190:191], v[156:157], v[188:189], v[194:195] neg_lo:[0,0,1] neg_hi:[0,0,1]
	v_pk_fma_f32 v[144:145], v[156:157], v[196:197], v[144:145]
	global_load_dwordx4 v[156:159], v[192:193], off offset:16
	s_nop 0
	global_load_dwordx4 v[192:195], v[192:193], off
	v_pk_add_f32 v[188:189], v[198:199], v[200:201] neg_lo:[0,1] neg_hi:[0,1]
	v_mov_b32_e32 v213, v147
	v_mov_b32_e32 v205, v146
	v_pk_add_f32 v[146:147], v[212:213], v[204:205]
	s_waitcnt vmcnt(0)
	v_mul_f32_e32 v198, v150, v156
	v_mul_f32_e32 v200, v154, v157
	v_mul_f32_e32 v156, v154, v156
	v_mov_b32_e32 v154, v151
	v_mov_b32_e32 v197, v194
	v_mov_b32_e32 v194, v193
	v_mul_f32_e32 v204, v150, v157
	v_pk_mul_f32 v[212:213], v[154:155], v[158:159]
	v_mov_b32_e32 v150, v155
	v_mov_b32_e32 v196, v192
	v_pk_mul_f32 v[192:193], v[152:153], v[194:195]
	v_mov_b32_e32 v199, v212
	v_mov_b32_e32 v201, v213
	v_pk_mul_f32 v[150:151], v[150:151], v[158:159]
	v_pk_mul_f32 v[152:153], v[152:153], v[196:197]
	v_pk_fma_f32 v[192:193], v[148:149], v[196:197], v[192:193] neg_lo:[0,0,1] neg_hi:[0,0,1]
	v_pk_add_f32 v[196:197], v[198:199], v[200:201] neg_lo:[0,1] neg_hi:[0,1]
	v_mov_b32_e32 v205, v151
	v_mov_b32_e32 v157, v150
	v_pk_fma_f32 v[152:153], v[148:149], v[194:195], v[152:153]
	v_pk_add_f32 v[154:155], v[204:205], v[156:157]
	v_mov_b32_e32 v148, v192
	v_mov_b32_e32 v149, v193
	v_mov_b32_e32 v150, v196
	v_mov_b32_e32 v151, v197
	v_mov_b32_e32 v156, v190
	v_mov_b32_e32 v157, v191
	v_mov_b32_e32 v158, v188
	v_mov_b32_e32 v159, v189

.LBB0_673:
	v_readlane_b32 s1, v254, 53
	s_add_u32 s14, s5, 0xde82000
	s_mul_i32 s96, s1, 0x7800
	s_addc_u32 s15, s4, 0
	s_lshl_b64 s[16:17], s[96:97], 2
	s_add_u32 s1, s5, s16
	s_addc_u32 s7, s4, s17
	s_add_u32 s45, s1, 0x2ec4000
	s_addc_u32 s46, s7, 0
	s_add_u32 s16, s5, 0xc582000
	v_readlane_b32 s22, v254, 56
	s_addc_u32 s17, s4, 0
	v_readlane_b32 s23, v254, 57
	s_and_b64 s[18:19], s[22:23], exec
	s_cselect_b32 s1, 0, 0xa000
	s_add_u32 s1, s5, s1
	s_addc_u32 s7, s4, 0
	s_add_u32 s49, s1, 0x2f2e000
	s_addc_u32 s50, s7, 0
	s_and_b64 s[18:19], s[22:23], exec
	s_mov_b32 s1, 0x24000
	s_cselect_b32 s1, 0xc000, s1
	s_add_u32 s1, s5, s1
	s_addc_u32 s4, s4, 0
	v_bfe_u32 v204, v10, 4, 2
	s_add_u32 s18, s1, 0x2efe000
	v_and_b32_e32 v205, 15, v10
	v_lshlrev_b32_e32 v15, 4, v204
	v_lshlrev_b32_e32 v10, 2, v10
	s_addc_u32 s19, s4, 0
	v_lshl_or_b32 v15, v205, 6, v15
	s_lshl_b32 s1, s20, 13
	v_and_b32_e32 v10, 32, v10
	v_bitop3_b32 v16, v15, s1, v10 bitop3:0xde
	s_lshl_b32 s1, s21, 5
	s_and_b32 s52, s1, 0x60
	s_add_i32 m0, s41, 0x18000
	v_lshl_add_u64 v[6:7], v[6:7], 0, s[78:79]
	s_lshl_b32 s51, s20, 6
	s_lshl_b32 s1, s52, 7
	s_waitcnt vmcnt(4)
	s_barrier
	global_load_lds_dwordx4 v[6:7], off
	v_lshl_add_u64 v[4:5], v[4:5], 0, s[78:79]
	s_add_i32 m0, s41, 0x1a000
	s_add_i32 s53, s41, 0x8000
	s_add_i32 s54, s41, 0xa000
	global_load_lds_dwordx4 v[4:5], off
	v_lshl_add_u64 v[2:3], v[2:3], 0, s[78:79]
	s_mov_b32 m0, s53
	s_add_u32 s4, s2, 0x40080
	global_load_lds_dwordx4 v[2:3], off
	v_lshl_add_u64 v[0:1], v[0:1], 0, s[78:79]
	s_mov_b32 m0, s54
	s_addc_u32 s5, s3, 0
	global_load_lds_dwordx4 v[0:1], off
	s_add_i32 m0, s41, 0x1c000
	v_lshl_add_u64 v[0:1], s[4:5], 0, v[182:183]
	global_load_lds_dwordx4 v[0:1], off
	v_lshl_add_u64 v[0:1], s[4:5], 0, v[186:187]
	s_add_i32 m0, s41, 0x1e000
	s_mov_b32 s47, 0
	global_load_lds_dwordx4 v[0:1], off
	v_lshlrev_b32_e32 v0, 14, v8
	v_and_b32_e32 v0, 0xffff8000, v0
	v_lshl_add_u32 v0, v9, 11, v0
	v_and_b32_e32 v1, 1, v8
	v_lshl_or_b32 v0, v1, 6, v0
	v_lshl_add_u32 v188, v11, 1, v0
	v_lshlrev_b32_e32 v0, 14, v12
	v_and_b32_e32 v0, 0xffff8000, v0
	s_waitcnt vmcnt(6)
	v_lshl_add_u32 v0, v13, 11, v0
	v_and_b32_e32 v1, 1, v12
	v_lshl_or_b32 v0, v1, 6, v0
	v_bitop3_b32 v206, s1, v15, v10 bitop3:0xf6
	v_add_u32_e32 v206, 0x10000, v206
	s_ashr_i32 s55, s34, 31
	v_mov_b32_e32 v189, v169
	v_lshl_add_u32 v190, v14, 1, v0
	v_mov_b32_e32 v191, v169
	v_add_u32_e32 v207, 0, v16
	s_barrier
	s_branch .LBB0_675

.LBB0_677:
	s_ashr_i32 s23, s22, 31
	v_cmp_lt_i64_e32 vcc, s[24:25], v[174:175]
	s_lshl_b64 s[24:25], s[22:23], 19
	s_add_u32 s24, s36, s24
	s_addc_u32 s25, s37, s25
	s_and_b64 s[26:27], vcc, exec
	s_cselect_b32 s1, s25, s9
	s_cselect_b32 s7, s24, s8
	s_ashr_i32 s21, s20, 31
	s_lshl_b64 s[26:27], s[20:21], 19
	s_add_u32 s26, s38, s26
	s_addc_u32 s27, s39, s27
	s_and_b64 s[28:29], vcc, exec
	s_cselect_b32 s21, s27, s3
	s_cselect_b32 s23, s26, s2
	s_add_u32 s8, s8, 0x40080
	s_addc_u32 s9, s9, 0
	s_add_u32 s56, s2, 0x100
	s_addc_u32 s57, s3, 0
	s_mov_b32 s58, -2
	s_add_u32 s2, s8, 0xfffc0080
	s_addc_u32 s3, s9, -1
	ds_read_b128 v[48:51], v206
	ds_read_b128 v[52:55], v206 offset:1024
	ds_read_b128 v[60:63], v206 offset:2048
	ds_read_b128 v[68:71], v206 offset:3072
	s_cmp_eq_u32 s58, 12
	s_cselect_b32 s29, s1, s3
	s_cselect_b32 s28, s7, s2
	s_cselect_b32 s3, s21, s57
	s_cselect_b32 s2, s23, s56
	s_add_i32 m0, s41, 0xc000
	ds_read_b128 v[72:75], v207
	ds_read_b128 v[76:79], v207 offset:1024
	ds_read_b128 v[80:83], v207 offset:2048
	ds_read_b128 v[84:87], v207 offset:3072
	ds_read_b128 v[160:163], v207 offset:4096
	ds_read_b128 v[164:167], v207 offset:5120
	ds_read_b128 v[192:195], v207 offset:6144
	global_load_lds_dwordx4 v188, s[8:9]
	s_add_i32 m0, s41, 0xe000
	ds_read_b128 v[196:199], v207 offset:7168
	global_load_lds_dwordx4 v190, s[8:9]
	s_waitcnt lgkmcnt(8)
	s_barrier
	s_waitcnt lgkmcnt(0)
	v_mfma_f32_16x16x32_bf16 v[156:159], v[48:51], v[72:75], 0
	v_mfma_f32_16x16x32_bf16 v[152:155], v[60:63], v[72:75], 0
	v_mfma_f32_16x16x32_bf16 v[140:143], v[48:51], v[80:83], 0
	v_mfma_f32_16x16x32_bf16 v[136:139], v[60:63], v[80:83], 0
	v_mfma_f32_16x16x32_bf16 v[124:127], v[48:51], v[160:163], 0
	v_mfma_f32_16x16x32_bf16 v[120:123], v[60:63], v[160:163], 0
	v_mfma_f32_16x16x32_bf16 v[108:111], v[48:51], v[192:195], 0
	v_mfma_f32_16x16x32_bf16 v[104:107], v[60:63], v[192:195], 0
	v_mfma_f32_16x16x32_bf16 v[156:159], v[52:55], v[76:79], v[156:159]
	v_mfma_f32_16x16x32_bf16 v[152:155], v[68:71], v[76:79], v[152:155]
	v_mfma_f32_16x16x32_bf16 v[140:143], v[52:55], v[84:87], v[140:143]
	v_mfma_f32_16x16x32_bf16 v[136:139], v[68:71], v[84:87], v[136:139]
	v_mfma_f32_16x16x32_bf16 v[124:127], v[52:55], v[164:167], v[124:127]
	v_mfma_f32_16x16x32_bf16 v[120:123], v[68:71], v[164:167], v[120:123]
	v_mfma_f32_16x16x32_bf16 v[108:111], v[52:55], v[196:199], v[108:111]
	v_mfma_f32_16x16x32_bf16 v[104:107], v[68:71], v[196:199], v[104:107]
	s_barrier
	s_add_i32 s59, s40, 0x10000
	s_add_u32 s98, s2, 0x80
	s_addc_u32 s99, s3, 0
	s_mov_b32 m0, s59
	ds_read_b128 v[200:203], v206 offset:16384
	ds_read_b128 v[208:211], v206 offset:17408
	ds_read_b128 v[212:215], v206 offset:18432
	global_load_lds_dwordx4 v182, s[2:3]
	s_add_i32 m0, s59, 0x2000
	ds_read_b128 v[216:219], v206 offset:19456
	global_load_lds_dwordx4 v186, s[2:3]
	s_barrier
	s_waitcnt lgkmcnt(0)
	v_mfma_f32_16x16x32_bf16 v[148:151], v[200:203], v[72:75], 0
	v_mfma_f32_16x16x32_bf16 v[72:75], v[212:215], v[72:75], 0
	v_mfma_f32_16x16x32_bf16 v[148:151], v[208:211], v[76:79], v[148:151]
	v_mfma_f32_16x16x32_bf16 v[72:75], v[216:219], v[76:79], v[72:75]
	v_mfma_f32_16x16x32_bf16 v[76:79], v[200:203], v[80:83], 0
	v_mfma_f32_16x16x32_bf16 v[80:83], v[212:215], v[80:83], 0
	v_mfma_f32_16x16x32_bf16 v[112:115], v[212:215], v[160:163], 0
	v_mfma_f32_16x16x32_bf16 v[100:103], v[200:203], v[192:195], 0
	v_mfma_f32_16x16x32_bf16 v[96:99], v[212:215], v[192:195], 0
	v_mfma_f32_16x16x32_bf16 v[76:79], v[208:211], v[84:87], v[76:79]
	v_mfma_f32_16x16x32_bf16 v[80:83], v[216:219], v[84:87], v[80:83]
	v_mfma_f32_16x16x32_bf16 v[84:87], v[200:203], v[160:163], 0
	v_mfma_f32_16x16x32_bf16 v[112:115], v[216:219], v[164:167], v[112:115]
	v_mfma_f32_16x16x32_bf16 v[100:103], v[208:211], v[196:199], v[100:103]
	v_mfma_f32_16x16x32_bf16 v[96:99], v[216:219], v[196:199], v[96:99]
	v_mfma_f32_16x16x32_bf16 v[84:87], v[208:211], v[164:167], v[84:87]
	s_mov_b32 m0, s41
	s_add_u32 s100, s28, 0x80
	s_addc_u32 s101, s29, 0
	s_barrier
	ds_read_b128 v[116:119], v207 offset:16384
	ds_read_b128 v[128:131], v207 offset:17408
	ds_read_b128 v[132:135], v207 offset:18432
	ds_read_b128 v[144:147], v207 offset:19456
	ds_read_b128 v[160:163], v207 offset:20480
	ds_read_b128 v[164:167], v207 offset:21504
	ds_read_b128 v[192:195], v207 offset:22528
	global_load_lds_dwordx4 v180, s[28:29]
	s_mov_b32 m0, s42
	ds_read_b128 v[196:199], v207 offset:23552
	global_load_lds_dwordx4 v184, s[28:29]
	s_barrier
	s_waitcnt lgkmcnt(0)
	v_mfma_f32_16x16x32_bf16 v[92:95], v[48:51], v[116:119], 0
	v_mfma_f32_16x16x32_bf16 v[88:91], v[60:63], v[116:119], 0
	v_mfma_f32_16x16x32_bf16 v[44:47], v[48:51], v[132:135], 0
	v_mfma_f32_16x16x32_bf16 v[40:43], v[60:63], v[132:135], 0
	v_mfma_f32_16x16x32_bf16 v[28:31], v[48:51], v[160:163], 0
	v_mfma_f32_16x16x32_bf16 v[24:27], v[60:63], v[160:163], 0
	v_mfma_f32_16x16x32_bf16 v[12:15], v[48:51], v[192:195], 0
	v_mfma_f32_16x16x32_bf16 v[8:11], v[60:63], v[192:195], 0
	v_mfma_f32_16x16x32_bf16 v[92:95], v[52:55], v[128:131], v[92:95]
	v_mfma_f32_16x16x32_bf16 v[88:91], v[68:71], v[128:131], v[88:91]
	v_mfma_f32_16x16x32_bf16 v[44:47], v[52:55], v[144:147], v[44:47]
	v_mfma_f32_16x16x32_bf16 v[40:43], v[68:71], v[144:147], v[40:43]
	v_mfma_f32_16x16x32_bf16 v[28:31], v[52:55], v[164:167], v[28:31]
	v_mfma_f32_16x16x32_bf16 v[24:27], v[68:71], v[164:167], v[24:27]
	v_mfma_f32_16x16x32_bf16 v[12:15], v[52:55], v[196:199], v[12:15]
	v_mfma_f32_16x16x32_bf16 v[8:11], v[68:71], v[196:199], v[8:11]
	s_barrier
	s_add_i32 s59, s40, 0x14000
	s_mov_b32 m0, s59
	s_add_u32 s60, s2, 0x40000
	s_addc_u32 s61, s3, 0
	global_load_lds_dwordx4 v182, s[60:61]
	s_add_i32 m0, s59, 0x2000
	s_nop 0
	global_load_lds_dwordx4 v186, s[60:61]
	s_waitcnt vmcnt(6)
	s_barrier
	v_mfma_f32_16x16x32_bf16 v[36:39], v[200:203], v[132:135], 0
	v_mfma_f32_16x16x32_bf16 v[32:35], v[212:215], v[132:135], 0
	v_mfma_f32_16x16x32_bf16 v[20:23], v[200:203], v[160:163], 0
	v_mfma_f32_16x16x32_bf16 v[16:19], v[212:215], v[160:163], 0
	v_mfma_f32_16x16x32_bf16 v[4:7], v[200:203], v[192:195], 0
	v_mfma_f32_16x16x32_bf16 v[0:3], v[212:215], v[192:195], 0
	v_mfma_f32_16x16x32_bf16 v[48:51], v[200:203], v[116:119], 0
	v_mfma_f32_16x16x32_bf16 v[52:55], v[212:215], v[116:119], 0
	v_mfma_f32_16x16x32_bf16 v[36:39], v[208:211], v[144:147], v[36:39]
	v_mfma_f32_16x16x32_bf16 v[32:35], v[216:219], v[144:147], v[32:35]
	v_mfma_f32_16x16x32_bf16 v[20:23], v[208:211], v[164:167], v[20:23]
	v_mfma_f32_16x16x32_bf16 v[16:19], v[216:219], v[164:167], v[16:19]
	v_mfma_f32_16x16x32_bf16 v[4:7], v[208:211], v[196:199], v[4:7]
	v_mfma_f32_16x16x32_bf16 v[0:3], v[216:219], v[196:199], v[0:3]
	v_mfma_f32_16x16x32_bf16 v[48:51], v[208:211], v[128:131], v[48:51]
	v_mfma_f32_16x16x32_bf16 v[52:55], v[216:219], v[128:131], v[52:55]
	s_barrier
	ds_read_b128 v[56:59], v206 offset:32768
	ds_read_b128 v[60:63], v206 offset:33792
	ds_read_b128 v[64:67], v206 offset:34816
	ds_read_b128 v[68:71], v206 offset:35840
	s_add_u32 s28, s28, 0x40000
	s_addc_u32 s29, s29, 0
	s_mov_b32 m0, s43
	ds_read_b128 v[116:119], v207 offset:32768
	ds_read_b128 v[128:131], v207 offset:33792
	ds_read_b128 v[160:163], v207 offset:34816
	ds_read_b128 v[164:167], v207 offset:35840
	ds_read_b128 v[192:195], v207 offset:36864
	ds_read_b128 v[196:199], v207 offset:37888
	ds_read_b128 v[200:203], v207 offset:38912
	global_load_lds_dwordx4 v180, s[28:29]
	s_mov_b32 m0, s44
	ds_read_b128 v[208:211], v207 offset:39936
	global_load_lds_dwordx4 v184, s[28:29]
	s_waitcnt lgkmcnt(8)
	s_barrier
	s_waitcnt lgkmcnt(0)
	v_mfma_f32_16x16x32_bf16 v[132:135], v[56:59], v[116:119], v[156:159]
	v_mfma_f32_16x16x32_bf16 v[156:159], v[60:63], v[128:131], v[132:135]
	v_mfma_f32_16x16x32_bf16 v[132:135], v[64:67], v[116:119], v[152:155]
	v_mfma_f32_16x16x32_bf16 v[152:155], v[68:71], v[128:131], v[132:135]
	v_mfma_f32_16x16x32_bf16 v[132:135], v[56:59], v[160:163], v[140:143]
	v_mfma_f32_16x16x32_bf16 v[140:143], v[60:63], v[164:167], v[132:135]
	v_mfma_f32_16x16x32_bf16 v[132:135], v[64:67], v[160:163], v[136:139]
	v_mfma_f32_16x16x32_bf16 v[124:127], v[56:59], v[192:195], v[124:127]
	v_mfma_f32_16x16x32_bf16 v[120:123], v[64:67], v[192:195], v[120:123]
	v_mfma_f32_16x16x32_bf16 v[108:111], v[56:59], v[200:203], v[108:111]
	v_mfma_f32_16x16x32_bf16 v[104:107], v[64:67], v[200:203], v[104:107]
	v_mfma_f32_16x16x32_bf16 v[136:139], v[68:71], v[164:167], v[132:135]
	v_mfma_f32_16x16x32_bf16 v[124:127], v[60:63], v[196:199], v[124:127]
	v_mfma_f32_16x16x32_bf16 v[120:123], v[68:71], v[196:199], v[120:123]
	v_mfma_f32_16x16x32_bf16 v[108:111], v[60:63], v[208:211], v[108:111]
	v_mfma_f32_16x16x32_bf16 v[104:107], v[68:71], v[208:211], v[104:107]
	s_barrier
	s_add_i32 s29, s40, 0x18000
	ds_read_b128 v[212:215], v206 offset:49152
	ds_read_b128 v[216:219], v206 offset:50176
	ds_read_b128 v[220:223], v206 offset:51200
	s_mov_b32 m0, s29
	ds_read_b128 v[236:239], v206 offset:52224
	global_load_lds_dwordx4 v182, s[98:99]
	s_add_i32 m0, s29, 0x2000
	s_nop 0
	global_load_lds_dwordx4 v186, s[98:99]
	s_barrier
	s_waitcnt lgkmcnt(0)
	v_mfma_f32_16x16x32_bf16 v[72:75], v[220:223], v[116:119], v[72:75]
	v_mfma_f32_16x16x32_bf16 v[132:135], v[212:215], v[116:119], v[148:151]
	v_mfma_f32_16x16x32_bf16 v[144:147], v[236:239], v[128:131], v[72:75]
	v_mfma_f32_16x16x32_bf16 v[72:75], v[212:215], v[160:163], v[76:79]
	v_mfma_f32_16x16x32_bf16 v[148:151], v[216:219], v[128:131], v[132:135]
	v_mfma_f32_16x16x32_bf16 v[132:135], v[216:219], v[164:167], v[72:75]
	v_mfma_f32_16x16x32_bf16 v[72:75], v[220:223], v[160:163], v[80:83]
	v_mfma_f32_16x16x32_bf16 v[128:131], v[236:239], v[164:167], v[72:75]
	v_mfma_f32_16x16x32_bf16 v[72:75], v[212:215], v[192:195], v[84:87]
	v_mfma_f32_16x16x32_bf16 v[116:119], v[216:219], v[196:199], v[72:75]
	v_mfma_f32_16x16x32_bf16 v[72:75], v[220:223], v[192:195], v[112:115]
	v_mfma_f32_16x16x32_bf16 v[112:115], v[236:239], v[196:199], v[72:75]
	v_mfma_f32_16x16x32_bf16 v[72:75], v[212:215], v[200:203], v[100:103]
	v_mfma_f32_16x16x32_bf16 v[100:103], v[216:219], v[208:211], v[72:75]
	v_mfma_f32_16x16x32_bf16 v[72:75], v[220:223], v[200:203], v[96:99]
	v_mfma_f32_16x16x32_bf16 v[96:99], v[236:239], v[208:211], v[72:75]
	s_mov_b32 m0, s53
	s_barrier
	s_nop 2
	ds_read_b128 v[72:75], v207 offset:49152
	ds_read_b128 v[76:79], v207 offset:50176
	ds_read_b128 v[80:83], v207 offset:51200
	ds_read_b128 v[84:87], v207 offset:52224
	ds_read_b128 v[160:163], v207 offset:53248
	ds_read_b128 v[164:167], v207 offset:54272
	ds_read_b128 v[192:195], v207 offset:55296
	global_load_lds_dwordx4 v180, s[100:101]
	s_mov_b32 m0, s54
	ds_read_b128 v[196:199], v207 offset:56320
	global_load_lds_dwordx4 v184, s[100:101]
	s_barrier
	s_waitcnt lgkmcnt(0)
	v_mfma_f32_16x16x32_bf16 v[92:95], v[56:59], v[72:75], v[92:95]
	v_mfma_f32_16x16x32_bf16 v[88:91], v[64:67], v[72:75], v[88:91]
	v_mfma_f32_16x16x32_bf16 v[44:47], v[56:59], v[80:83], v[44:47]
	v_mfma_f32_16x16x32_bf16 v[40:43], v[64:67], v[80:83], v[40:43]
	v_mfma_f32_16x16x32_bf16 v[28:31], v[56:59], v[160:163], v[28:31]
	v_mfma_f32_16x16x32_bf16 v[24:27], v[64:67], v[160:163], v[24:27]
	v_mfma_f32_16x16x32_bf16 v[12:15], v[56:59], v[192:195], v[12:15]
	v_mfma_f32_16x16x32_bf16 v[8:11], v[64:67], v[192:195], v[8:11]
	v_mfma_f32_16x16x32_bf16 v[92:95], v[60:63], v[76:79], v[92:95]
	v_mfma_f32_16x16x32_bf16 v[88:91], v[68:71], v[76:79], v[88:91]
	v_mfma_f32_16x16x32_bf16 v[44:47], v[60:63], v[84:87], v[44:47]
	v_mfma_f32_16x16x32_bf16 v[40:43], v[68:71], v[84:87], v[40:43]
	v_mfma_f32_16x16x32_bf16 v[28:31], v[60:63], v[164:167], v[28:31]
	v_mfma_f32_16x16x32_bf16 v[24:27], v[68:71], v[164:167], v[24:27]
	v_mfma_f32_16x16x32_bf16 v[12:15], v[60:63], v[196:199], v[12:15]
	v_mfma_f32_16x16x32_bf16 v[8:11], v[68:71], v[196:199], v[8:11]
	s_barrier
	s_add_i32 s28, s40, 0x1c000
	s_mov_b32 m0, s28
	s_add_u32 s2, s2, 0x40080
	s_addc_u32 s3, s3, 0
	global_load_lds_dwordx4 v182, s[2:3]
	s_add_i32 m0, s28, 0x2000
	s_nop 0
	global_load_lds_dwordx4 v186, s[2:3]
	s_waitcnt vmcnt(6)
	s_barrier
	v_mfma_f32_16x16x32_bf16 v[48:51], v[212:215], v[72:75], v[48:51]
	v_mfma_f32_16x16x32_bf16 v[64:67], v[216:219], v[76:79], v[48:51]
	v_mfma_f32_16x16x32_bf16 v[48:51], v[220:223], v[72:75], v[52:55]
	v_mfma_f32_16x16x32_bf16 v[36:39], v[212:215], v[80:83], v[36:39]
	v_mfma_f32_16x16x32_bf16 v[32:35], v[220:223], v[80:83], v[32:35]
	v_mfma_f32_16x16x32_bf16 v[20:23], v[212:215], v[160:163], v[20:23]
	v_mfma_f32_16x16x32_bf16 v[16:19], v[220:223], v[160:163], v[16:19]
	v_mfma_f32_16x16x32_bf16 v[4:7], v[212:215], v[192:195], v[4:7]
	v_mfma_f32_16x16x32_bf16 v[0:3], v[220:223], v[192:195], v[0:3]
	v_mfma_f32_16x16x32_bf16 v[56:59], v[236:239], v[76:79], v[48:51]
	v_mfma_f32_16x16x32_bf16 v[36:39], v[216:219], v[84:87], v[36:39]
	v_mfma_f32_16x16x32_bf16 v[32:35], v[236:239], v[84:87], v[32:35]
	v_mfma_f32_16x16x32_bf16 v[20:23], v[216:219], v[164:167], v[20:23]
	v_mfma_f32_16x16x32_bf16 v[16:19], v[236:239], v[164:167], v[16:19]
	v_mfma_f32_16x16x32_bf16 v[4:7], v[216:219], v[196:199], v[4:7]
	v_mfma_f32_16x16x32_bf16 v[0:3], v[236:239], v[196:199], v[0:3]
	s_add_i32 s58, s58, 2
	s_add_u32 s8, s8, 0x100
	s_addc_u32 s9, s9, 0
	s_add_u32 s56, s56, 0x100
	s_addc_u32 s57, s57, 0
	s_cmp_gt_u32 s58, 13
	s_barrier
.LBB0_678:
	s_add_u32 s2, s8, 0xfffc0080
	s_addc_u32 s3, s9, -1
	ds_read_b128 v[48:51], v206
	ds_read_b128 v[52:55], v206 offset:1024
	ds_read_b128 v[60:63], v206 offset:2048
	ds_read_b128 v[68:71], v206 offset:3072
	s_cmp_eq_u32 s58, 12
	s_cselect_b32 s29, s1, s3
	s_cselect_b32 s28, s7, s2
	s_cselect_b32 s3, s21, s57
	s_cselect_b32 s2, s23, s56
	s_add_i32 m0, s41, 0xc000
	ds_read_b128 v[72:75], v207
	ds_read_b128 v[76:79], v207 offset:1024
	ds_read_b128 v[80:83], v207 offset:2048
	ds_read_b128 v[84:87], v207 offset:3072
	ds_read_b128 v[160:163], v207 offset:4096
	ds_read_b128 v[164:167], v207 offset:5120
	ds_read_b128 v[192:195], v207 offset:6144
	global_load_lds_dwordx4 v188, s[8:9]
	s_add_i32 m0, s41, 0xe000
	ds_read_b128 v[196:199], v207 offset:7168
	global_load_lds_dwordx4 v190, s[8:9]
	s_waitcnt lgkmcnt(8)
	s_barrier
	s_waitcnt lgkmcnt(0)
	v_mfma_f32_16x16x32_bf16 v[156:159], v[48:51], v[72:75], v[156:159]
	v_mfma_f32_16x16x32_bf16 v[152:155], v[60:63], v[72:75], v[152:155]
	v_mfma_f32_16x16x32_bf16 v[140:143], v[48:51], v[80:83], v[140:143]
	v_mfma_f32_16x16x32_bf16 v[136:139], v[60:63], v[80:83], v[136:139]
	v_mfma_f32_16x16x32_bf16 v[124:127], v[48:51], v[160:163], v[124:127]
	v_mfma_f32_16x16x32_bf16 v[120:123], v[60:63], v[160:163], v[120:123]
	v_mfma_f32_16x16x32_bf16 v[108:111], v[48:51], v[192:195], v[108:111]
	v_mfma_f32_16x16x32_bf16 v[104:107], v[60:63], v[192:195], v[104:107]
	v_mfma_f32_16x16x32_bf16 v[156:159], v[52:55], v[76:79], v[156:159]
	v_mfma_f32_16x16x32_bf16 v[152:155], v[68:71], v[76:79], v[152:155]
	v_mfma_f32_16x16x32_bf16 v[140:143], v[52:55], v[84:87], v[140:143]
	v_mfma_f32_16x16x32_bf16 v[136:139], v[68:71], v[84:87], v[136:139]
	v_mfma_f32_16x16x32_bf16 v[124:127], v[52:55], v[164:167], v[124:127]
	v_mfma_f32_16x16x32_bf16 v[120:123], v[68:71], v[164:167], v[120:123]
	v_mfma_f32_16x16x32_bf16 v[108:111], v[52:55], v[196:199], v[108:111]
	v_mfma_f32_16x16x32_bf16 v[104:107], v[68:71], v[196:199], v[104:107]
	s_barrier
	s_add_i32 s59, s40, 0x10000
	s_add_u32 s98, s2, 0x80
	s_addc_u32 s99, s3, 0
	s_mov_b32 m0, s59
	ds_read_b128 v[200:203], v206 offset:16384
	ds_read_b128 v[208:211], v206 offset:17408
	ds_read_b128 v[212:215], v206 offset:18432
	global_load_lds_dwordx4 v182, s[2:3]
	s_add_i32 m0, s59, 0x2000
	ds_read_b128 v[216:219], v206 offset:19456
	global_load_lds_dwordx4 v186, s[2:3]
	s_barrier
	s_waitcnt lgkmcnt(0)
	v_mfma_f32_16x16x32_bf16 v[148:151], v[200:203], v[72:75], v[148:151]
	v_mfma_f32_16x16x32_bf16 v[72:75], v[212:215], v[72:75], v[144:147]
	v_mfma_f32_16x16x32_bf16 v[148:151], v[208:211], v[76:79], v[148:151]
	v_mfma_f32_16x16x32_bf16 v[72:75], v[216:219], v[76:79], v[72:75]
	v_mfma_f32_16x16x32_bf16 v[76:79], v[200:203], v[80:83], v[132:135]
	v_mfma_f32_16x16x32_bf16 v[80:83], v[212:215], v[80:83], v[128:131]
	v_mfma_f32_16x16x32_bf16 v[112:115], v[212:215], v[160:163], v[112:115]
	v_mfma_f32_16x16x32_bf16 v[100:103], v[200:203], v[192:195], v[100:103]
	v_mfma_f32_16x16x32_bf16 v[96:99], v[212:215], v[192:195], v[96:99]
	v_mfma_f32_16x16x32_bf16 v[76:79], v[208:211], v[84:87], v[76:79]
	v_mfma_f32_16x16x32_bf16 v[80:83], v[216:219], v[84:87], v[80:83]
	v_mfma_f32_16x16x32_bf16 v[84:87], v[200:203], v[160:163], v[116:119]
	v_mfma_f32_16x16x32_bf16 v[112:115], v[216:219], v[164:167], v[112:115]
	v_mfma_f32_16x16x32_bf16 v[100:103], v[208:211], v[196:199], v[100:103]
	v_mfma_f32_16x16x32_bf16 v[96:99], v[216:219], v[196:199], v[96:99]
	v_mfma_f32_16x16x32_bf16 v[84:87], v[208:211], v[164:167], v[84:87]
	s_mov_b32 m0, s41
	s_add_u32 s100, s28, 0x80
	s_addc_u32 s101, s29, 0
	s_barrier
	ds_read_b128 v[116:119], v207 offset:16384
	ds_read_b128 v[128:131], v207 offset:17408
	ds_read_b128 v[132:135], v207 offset:18432
	ds_read_b128 v[144:147], v207 offset:19456
	ds_read_b128 v[160:163], v207 offset:20480
	ds_read_b128 v[164:167], v207 offset:21504
	ds_read_b128 v[192:195], v207 offset:22528
	global_load_lds_dwordx4 v180, s[28:29]
	s_mov_b32 m0, s42
	ds_read_b128 v[196:199], v207 offset:23552
	global_load_lds_dwordx4 v184, s[28:29]
	s_barrier
	s_waitcnt lgkmcnt(0)
	v_mfma_f32_16x16x32_bf16 v[92:95], v[48:51], v[116:119], v[92:95]
	v_mfma_f32_16x16x32_bf16 v[88:91], v[60:63], v[116:119], v[88:91]
	v_mfma_f32_16x16x32_bf16 v[44:47], v[48:51], v[132:135], v[44:47]
	v_mfma_f32_16x16x32_bf16 v[40:43], v[60:63], v[132:135], v[40:43]
	v_mfma_f32_16x16x32_bf16 v[28:31], v[48:51], v[160:163], v[28:31]
	v_mfma_f32_16x16x32_bf16 v[24:27], v[60:63], v[160:163], v[24:27]
	v_mfma_f32_16x16x32_bf16 v[12:15], v[48:51], v[192:195], v[12:15]
	v_mfma_f32_16x16x32_bf16 v[8:11], v[60:63], v[192:195], v[8:11]
	v_mfma_f32_16x16x32_bf16 v[92:95], v[52:55], v[128:131], v[92:95]
	v_mfma_f32_16x16x32_bf16 v[88:91], v[68:71], v[128:131], v[88:91]
	v_mfma_f32_16x16x32_bf16 v[44:47], v[52:55], v[144:147], v[44:47]
	v_mfma_f32_16x16x32_bf16 v[40:43], v[68:71], v[144:147], v[40:43]
	v_mfma_f32_16x16x32_bf16 v[28:31], v[52:55], v[164:167], v[28:31]
	v_mfma_f32_16x16x32_bf16 v[24:27], v[68:71], v[164:167], v[24:27]
	v_mfma_f32_16x16x32_bf16 v[12:15], v[52:55], v[196:199], v[12:15]
	v_mfma_f32_16x16x32_bf16 v[8:11], v[68:71], v[196:199], v[8:11]
	s_barrier
	s_add_i32 s59, s40, 0x14000
	s_mov_b32 m0, s59
	s_add_u32 s60, s2, 0x40000
	s_addc_u32 s61, s3, 0
	global_load_lds_dwordx4 v182, s[60:61]
	s_add_i32 m0, s59, 0x2000
	s_nop 0
	global_load_lds_dwordx4 v186, s[60:61]
	s_waitcnt vmcnt(6)
	s_barrier
	v_mfma_f32_16x16x32_bf16 v[36:39], v[200:203], v[132:135], v[36:39]
	v_mfma_f32_16x16x32_bf16 v[32:35], v[212:215], v[132:135], v[32:35]
	v_mfma_f32_16x16x32_bf16 v[20:23], v[200:203], v[160:163], v[20:23]
	v_mfma_f32_16x16x32_bf16 v[16:19], v[212:215], v[160:163], v[16:19]
	v_mfma_f32_16x16x32_bf16 v[4:7], v[200:203], v[192:195], v[4:7]
	v_mfma_f32_16x16x32_bf16 v[0:3], v[212:215], v[192:195], v[0:3]
	v_mfma_f32_16x16x32_bf16 v[48:51], v[200:203], v[116:119], v[64:67]
	v_mfma_f32_16x16x32_bf16 v[52:55], v[212:215], v[116:119], v[56:59]
	v_mfma_f32_16x16x32_bf16 v[36:39], v[208:211], v[144:147], v[36:39]
	v_mfma_f32_16x16x32_bf16 v[32:35], v[216:219], v[144:147], v[32:35]
	v_mfma_f32_16x16x32_bf16 v[20:23], v[208:211], v[164:167], v[20:23]
	v_mfma_f32_16x16x32_bf16 v[16:19], v[216:219], v[164:167], v[16:19]
	v_mfma_f32_16x16x32_bf16 v[4:7], v[208:211], v[196:199], v[4:7]
	v_mfma_f32_16x16x32_bf16 v[0:3], v[216:219], v[196:199], v[0:3]
	v_mfma_f32_16x16x32_bf16 v[48:51], v[208:211], v[128:131], v[48:51]
	v_mfma_f32_16x16x32_bf16 v[52:55], v[216:219], v[128:131], v[52:55]
	s_barrier
	ds_read_b128 v[56:59], v206 offset:32768
	ds_read_b128 v[60:63], v206 offset:33792
	ds_read_b128 v[64:67], v206 offset:34816
	ds_read_b128 v[68:71], v206 offset:35840
	s_add_u32 s28, s28, 0x40000
	s_addc_u32 s29, s29, 0
	s_mov_b32 m0, s43
	ds_read_b128 v[116:119], v207 offset:32768
	ds_read_b128 v[128:131], v207 offset:33792
	ds_read_b128 v[160:163], v207 offset:34816
	ds_read_b128 v[164:167], v207 offset:35840
	ds_read_b128 v[192:195], v207 offset:36864
	ds_read_b128 v[196:199], v207 offset:37888
	ds_read_b128 v[200:203], v207 offset:38912
	global_load_lds_dwordx4 v180, s[28:29]
	s_mov_b32 m0, s44
	ds_read_b128 v[208:211], v207 offset:39936
	global_load_lds_dwordx4 v184, s[28:29]
	s_waitcnt lgkmcnt(8)
	s_barrier
	s_waitcnt lgkmcnt(0)
	v_mfma_f32_16x16x32_bf16 v[132:135], v[56:59], v[116:119], v[156:159]
	v_mfma_f32_16x16x32_bf16 v[156:159], v[60:63], v[128:131], v[132:135]
	v_mfma_f32_16x16x32_bf16 v[132:135], v[64:67], v[116:119], v[152:155]
	v_mfma_f32_16x16x32_bf16 v[152:155], v[68:71], v[128:131], v[132:135]
	v_mfma_f32_16x16x32_bf16 v[132:135], v[56:59], v[160:163], v[140:143]
	v_mfma_f32_16x16x32_bf16 v[140:143], v[60:63], v[164:167], v[132:135]
	v_mfma_f32_16x16x32_bf16 v[132:135], v[64:67], v[160:163], v[136:139]
	v_mfma_f32_16x16x32_bf16 v[124:127], v[56:59], v[192:195], v[124:127]
	v_mfma_f32_16x16x32_bf16 v[120:123], v[64:67], v[192:195], v[120:123]
	v_mfma_f32_16x16x32_bf16 v[108:111], v[56:59], v[200:203], v[108:111]
	v_mfma_f32_16x16x32_bf16 v[104:107], v[64:67], v[200:203], v[104:107]
	v_mfma_f32_16x16x32_bf16 v[136:139], v[68:71], v[164:167], v[132:135]
	v_mfma_f32_16x16x32_bf16 v[124:127], v[60:63], v[196:199], v[124:127]
	v_mfma_f32_16x16x32_bf16 v[120:123], v[68:71], v[196:199], v[120:123]
	v_mfma_f32_16x16x32_bf16 v[108:111], v[60:63], v[208:211], v[108:111]
	v_mfma_f32_16x16x32_bf16 v[104:107], v[68:71], v[208:211], v[104:107]
	s_barrier
	s_add_i32 s29, s40, 0x18000
	ds_read_b128 v[212:215], v206 offset:49152
	ds_read_b128 v[216:219], v206 offset:50176
	ds_read_b128 v[220:223], v206 offset:51200
	s_mov_b32 m0, s29
	ds_read_b128 v[236:239], v206 offset:52224
	global_load_lds_dwordx4 v182, s[98:99]
	s_add_i32 m0, s29, 0x2000
	s_nop 0
	global_load_lds_dwordx4 v186, s[98:99]
	s_barrier
	s_waitcnt lgkmcnt(0)
	v_mfma_f32_16x16x32_bf16 v[72:75], v[220:223], v[116:119], v[72:75]
	v_mfma_f32_16x16x32_bf16 v[132:135], v[212:215], v[116:119], v[148:151]
	v_mfma_f32_16x16x32_bf16 v[144:147], v[236:239], v[128:131], v[72:75]
	v_mfma_f32_16x16x32_bf16 v[72:75], v[212:215], v[160:163], v[76:79]
	v_mfma_f32_16x16x32_bf16 v[148:151], v[216:219], v[128:131], v[132:135]
	v_mfma_f32_16x16x32_bf16 v[132:135], v[216:219], v[164:167], v[72:75]
	v_mfma_f32_16x16x32_bf16 v[72:75], v[220:223], v[160:163], v[80:83]
	v_mfma_f32_16x16x32_bf16 v[128:131], v[236:239], v[164:167], v[72:75]
	v_mfma_f32_16x16x32_bf16 v[72:75], v[212:215], v[192:195], v[84:87]
	v_mfma_f32_16x16x32_bf16 v[116:119], v[216:219], v[196:199], v[72:75]
	v_mfma_f32_16x16x32_bf16 v[72:75], v[220:223], v[192:195], v[112:115]
	v_mfma_f32_16x16x32_bf16 v[112:115], v[236:239], v[196:199], v[72:75]
	v_mfma_f32_16x16x32_bf16 v[72:75], v[212:215], v[200:203], v[100:103]
	v_mfma_f32_16x16x32_bf16 v[100:103], v[216:219], v[208:211], v[72:75]
	v_mfma_f32_16x16x32_bf16 v[72:75], v[220:223], v[200:203], v[96:99]
	v_mfma_f32_16x16x32_bf16 v[96:99], v[236:239], v[208:211], v[72:75]
	s_mov_b32 m0, s53
	s_barrier
	s_nop 2
	ds_read_b128 v[72:75], v207 offset:49152
	ds_read_b128 v[76:79], v207 offset:50176
	ds_read_b128 v[80:83], v207 offset:51200
	ds_read_b128 v[84:87], v207 offset:52224
	ds_read_b128 v[160:163], v207 offset:53248
	ds_read_b128 v[164:167], v207 offset:54272
	ds_read_b128 v[192:195], v207 offset:55296
	global_load_lds_dwordx4 v180, s[100:101]
	s_mov_b32 m0, s54
	ds_read_b128 v[196:199], v207 offset:56320
	global_load_lds_dwordx4 v184, s[100:101]
	s_barrier
	s_waitcnt lgkmcnt(0)
	v_mfma_f32_16x16x32_bf16 v[92:95], v[56:59], v[72:75], v[92:95]
	v_mfma_f32_16x16x32_bf16 v[88:91], v[64:67], v[72:75], v[88:91]
	v_mfma_f32_16x16x32_bf16 v[44:47], v[56:59], v[80:83], v[44:47]
	v_mfma_f32_16x16x32_bf16 v[40:43], v[64:67], v[80:83], v[40:43]
	v_mfma_f32_16x16x32_bf16 v[28:31], v[56:59], v[160:163], v[28:31]
	v_mfma_f32_16x16x32_bf16 v[24:27], v[64:67], v[160:163], v[24:27]
	v_mfma_f32_16x16x32_bf16 v[12:15], v[56:59], v[192:195], v[12:15]
	v_mfma_f32_16x16x32_bf16 v[8:11], v[64:67], v[192:195], v[8:11]
	v_mfma_f32_16x16x32_bf16 v[92:95], v[60:63], v[76:79], v[92:95]
	v_mfma_f32_16x16x32_bf16 v[88:91], v[68:71], v[76:79], v[88:91]
	v_mfma_f32_16x16x32_bf16 v[44:47], v[60:63], v[84:87], v[44:47]
	v_mfma_f32_16x16x32_bf16 v[40:43], v[68:71], v[84:87], v[40:43]
	v_mfma_f32_16x16x32_bf16 v[28:31], v[60:63], v[164:167], v[28:31]
	v_mfma_f32_16x16x32_bf16 v[24:27], v[68:71], v[164:167], v[24:27]
	v_mfma_f32_16x16x32_bf16 v[12:15], v[60:63], v[196:199], v[12:15]
	v_mfma_f32_16x16x32_bf16 v[8:11], v[68:71], v[196:199], v[8:11]
	s_barrier
	s_add_i32 s28, s40, 0x1c000
	s_mov_b32 m0, s28
	s_add_u32 s2, s2, 0x40080
	s_addc_u32 s3, s3, 0
	global_load_lds_dwordx4 v182, s[2:3]
	s_add_i32 m0, s28, 0x2000
	s_nop 0
	global_load_lds_dwordx4 v186, s[2:3]
	s_waitcnt vmcnt(6)
	s_barrier
	v_mfma_f32_16x16x32_bf16 v[48:51], v[212:215], v[72:75], v[48:51]
	v_mfma_f32_16x16x32_bf16 v[64:67], v[216:219], v[76:79], v[48:51]
	v_mfma_f32_16x16x32_bf16 v[48:51], v[220:223], v[72:75], v[52:55]
	v_mfma_f32_16x16x32_bf16 v[36:39], v[212:215], v[80:83], v[36:39]
	v_mfma_f32_16x16x32_bf16 v[32:35], v[220:223], v[80:83], v[32:35]
	v_mfma_f32_16x16x32_bf16 v[20:23], v[212:215], v[160:163], v[20:23]
	v_mfma_f32_16x16x32_bf16 v[16:19], v[220:223], v[160:163], v[16:19]
	v_mfma_f32_16x16x32_bf16 v[4:7], v[212:215], v[192:195], v[4:7]
	v_mfma_f32_16x16x32_bf16 v[0:3], v[220:223], v[192:195], v[0:3]
	v_mfma_f32_16x16x32_bf16 v[56:59], v[236:239], v[76:79], v[48:51]
	v_mfma_f32_16x16x32_bf16 v[36:39], v[216:219], v[84:87], v[36:39]
	v_mfma_f32_16x16x32_bf16 v[32:35], v[236:239], v[84:87], v[32:35]
	v_mfma_f32_16x16x32_bf16 v[20:23], v[216:219], v[164:167], v[20:23]
	v_mfma_f32_16x16x32_bf16 v[16:19], v[236:239], v[164:167], v[16:19]
	v_mfma_f32_16x16x32_bf16 v[4:7], v[216:219], v[196:199], v[4:7]
	v_mfma_f32_16x16x32_bf16 v[0:3], v[236:239], v[196:199], v[0:3]
	s_add_i32 s58, s58, 2
	s_add_u32 s8, s8, 0x100
	s_addc_u32 s9, s9, 0
	s_add_u32 s56, s56, 0x100
	s_addc_u32 s57, s57, 0
	s_cmp_gt_u32 s58, 13
	s_barrier
	s_cbranch_scc0 .LBB0_678
	s_lshl_b32 s1, s0, 8
	s_add_i32 s2, s1, s51
	s_lshl_b32 s1, s6, 8
	v_mov_b32_e32 v160, v205
	v_mov_b32_e32 v208, v204
	s_or_b32 s1, s1, s52
	s_nop 0
	v_lshl_add_u32 v192, v208, 3, s1
	s_add_i32 s1, s0, -16
	s_lshr_b32 s1, s1, 3
	s_add_i32 s1, s1, 1
	s_cmp_gt_i32 s0, 15
	s_cselect_b32 s3, s1, 0
	s_mul_i32 s96, s3, 0x1800
	s_lshl_b64 s[0:1], s[96:97], 2
	s_add_u32 s0, s45, s0
	v_ashrrev_i32_e32 v193, 31, v192
	s_addc_u32 s1, s46, s1
	v_lshlrev_b64 v[196:197], 2, v[192:193]
	s_lshl_b32 s96, s3, 10
	v_lshl_add_u64 v[48:49], s[0:1], 0, v[196:197]
	s_lshl_b64 s[0:1], s[96:97], 2
	s_add_u32 s0, s49, s0
	s_addc_u32 s1, s50, s1
	v_lshl_add_u64 v[52:53], s[0:1], 0, v[196:197]
	global_load_dwordx4 v[80:83], v[48:49], off offset:16
	global_load_dwordx4 v[84:87], v[48:49], off
	global_load_dwordx4 v[72:75], v[52:53], off offset:16
	global_load_dwordx4 v[76:79], v[52:53], off
	global_load_dwordx4 v[60:63], v[48:49], off offset:528
	global_load_dwordx4 v[68:71], v[48:49], off offset:512
	s_nop 0
	global_load_dwordx4 v[48:51], v[52:53], off offset:528
	s_nop 0
	global_load_dwordx4 v[52:55], v[52:53], off offset:512
	v_add_u32_e32 v194, s2, v160
	v_ashrrev_i32_e32 v195, 31, v194
	v_lshlrev_b64 v[160:161], 10, v[194:195]
	v_lshl_add_u64 v[198:199], v[160:161], 0, v[192:193]
	v_cndmask_b32_e64 v160, 0, 1, s[74:75]
	v_cmp_gt_i32_e64 s[0:1], s71, v194
	v_cmp_ne_u32_e64 s[6:7], 1, v160
	s_andn2_b64 vcc, exec, s[74:75]
	s_mov_b64 s[2:3], -1
	s_cbranch_vccnz .LBB0_681
	v_lshl_add_u64 v[160:161], v[198:199], 1, s[14:15]
	v_mov_b32_e32 v222, v160
	v_mov_b32_e32 v223, v161
	global_load_dwordx4 v[210:213], v[222:223], off
	global_load_dwordx4 v[214:217], v[222:223], off offset:256
	s_mov_b64 s[80:81], 0x8000
	v_lshl_add_u64 v[222:223], v[222:223], 0, s[80:81]
	global_load_dwordx4 v[218:221], v[222:223], off
	global_load_dwordx4 v[236:239], v[222:223], off offset:256
	s_mov_b64 s[2:3], 0
	s_waitcnt vmcnt(3)
	v_lshlrev_b32_e32 v164, 16, v210
	v_and_b32_e32 v165, 0xffff0000, v210
	v_lshlrev_b32_e32 v166, 16, v211
	v_and_b32_e32 v167, 0xffff0000, v211
	v_lshlrev_b32_e32 v160, 16, v212
	v_and_b32_e32 v161, 0xffff0000, v212
	v_lshlrev_b32_e32 v162, 16, v213
	v_and_b32_e32 v163, 0xffff0000, v213
	s_mov_b64 s[80:81], 0x8000
	v_lshl_add_u64 v[222:223], v[222:223], 0, s[80:81]
	global_load_dwordx4 v[210:213], v[222:223], off

.LBB0_875:
	s_add_u32 s16, s25, 0x2f82000
	s_addc_u32 s17, s24, 0
	s_add_u32 s18, s25, 0x7182000
	v_readlane_b32 s1, v254, 53
	s_addc_u32 s19, s24, 0
	s_mul_i32 s1, s1, 0x10800
	s_add_u32 s20, s13, s1
	s_addc_u32 s21, s7, 0
	s_lshl_b32 s1, s12, 2
	s_add_u32 s1, s25, s1
	s_addc_u32 s7, s24, 0
	s_add_u32 s22, s1, 0x2efe000
	s_addc_u32 s23, s7, 0
	s_lshl_b32 s1, s6, 2
	s_add_u32 s1, s25, s1
	s_addc_u32 s6, s24, 0
	v_bfe_u32 v236, v12, 4, 2
	s_add_u32 s58, s1, 0x2f3d000
	v_and_b32_e32 v235, 15, v12
	v_lshlrev_b32_e32 v15, 4, v236
	v_lshlrev_b32_e32 v12, 2, v12
	s_addc_u32 s59, s6, 0
	v_lshl_or_b32 v15, v235, 6, v15
	s_lshl_b32 s1, s14, 13
	v_and_b32_e32 v12, 32, v12
	v_bitop3_b32 v16, v15, s1, v12 bitop3:0xde
	s_lshl_b32 s1, s15, 5
	s_and_b32 s61, s1, 0x60
	s_add_i32 m0, s54, 0x18000
	v_lshl_add_u64 v[6:7], v[6:7], 0, s[78:79]
	s_lshl_b32 s60, s14, 6
	s_lshl_b32 s1, s61, 7
	s_waitcnt vmcnt(4)
	s_barrier
	global_load_lds_dwordx4 v[6:7], off
	v_lshl_add_u64 v[4:5], v[4:5], 0, s[78:79]
	s_add_i32 m0, s54, 0x1a000
	s_add_i32 s62, s54, 0x8000
	s_add_i32 s63, s54, 0xa000
	global_load_lds_dwordx4 v[4:5], off
	v_lshl_add_u64 v[2:3], v[2:3], 0, s[78:79]
	s_mov_b32 m0, s62
	s_add_u32 s6, s2, 0x40080
	global_load_lds_dwordx4 v[2:3], off
	v_lshl_add_u64 v[0:1], v[0:1], 0, s[78:79]
	s_mov_b32 m0, s63
	s_addc_u32 s7, s3, 0
	global_load_lds_dwordx4 v[0:1], off
	s_add_i32 m0, s54, 0x1c000
	v_lshl_add_u64 v[0:1], s[6:7], 0, v[168:169]
	global_load_lds_dwordx4 v[0:1], off
	v_lshl_add_u64 v[0:1], s[6:7], 0, v[184:185]
	s_add_i32 m0, s54, 0x1e000
	s_ashr_i32 s64, s45, 31
	global_load_lds_dwordx4 v[0:1], off
	s_add_u32 s24, s20, 0x2c00
	s_addc_u32 s25, s21, 0
	v_lshlrev_b32_e32 v0, 14, v8
	s_add_u32 s26, s20, 0x5800
	v_and_b32_e32 v0, 0xffff8000, v0
	s_addc_u32 s27, s21, 0
	v_lshl_add_u32 v0, v9, 11, v0
	v_and_b32_e32 v1, 1, v8
	s_add_u32 s28, s20, 0x8400
	v_lshl_or_b32 v0, v1, 6, v0
	s_addc_u32 s29, s21, 0
	v_lshl_add_u32 v186, v10, 1, v0
	v_lshlrev_b32_e32 v0, 14, v11
	s_add_u32 s30, s20, 0xb000
	v_and_b32_e32 v0, 0xffff8000, v0
	s_waitcnt vmcnt(6)
	s_addc_u32 s31, s21, 0
	v_lshl_add_u32 v0, v13, 11, v0
	v_and_b32_e32 v1, 1, v11
	s_add_u32 s34, s20, 0xdc00
	v_lshl_or_b32 v0, v1, 6, v0
	v_bitop3_b32 v237, s1, v15, v12 bitop3:0xf6
	v_add_u32_e32 v237, 0x10000, v237
	s_addc_u32 s35, s21, 0
	v_mov_b32_e32 v187, v169
	v_lshl_add_u32 v188, v14, 1, v0
	v_mov_b32_e32 v189, v169
	s_mov_b32 s65, 0
	s_mov_b32 s83, 0
	v_add_u32_e32 v238, 0, v16
	s_lshl_b32 s66, s61, 2
	s_barrier
	s_branch .LBB0_877

.LBB0_879:
	s_ashr_i32 s39, s38, 31
	v_cmp_lt_i64_e32 vcc, s[12:13], v[178:179]
	s_lshl_b64 s[12:13], s[38:39], 19
	s_add_u32 s40, s49, s12
	s_addc_u32 s41, s50, s13
	s_lshl_b32 s84, s82, 18
	s_add_u32 s40, s40, s84
	s_addc_u32 s41, s41, 0
	s_and_b64 s[12:13], vcc, exec
	s_cselect_b32 s1, s41, s11
	s_cselect_b32 s9, s40, s10
	s_ashr_i32 s37, s36, 31
	s_lshl_b64 s[12:13], s[36:37], 19
	s_add_u32 s42, s51, s12
	s_addc_u32 s43, s52, s13
	s_and_b64 s[12:13], vcc, exec
	s_cselect_b32 s14, s43, s3
	s_cselect_b32 s15, s42, s2
	s_add_u32 s10, s10, 0x40080
	s_addc_u32 s11, s11, 0
	s_add_u32 s37, s2, 0x100
	s_addc_u32 s39, s3, 0
	s_mov_b32 s67, -2
	s_cmp_lg_u32 s83, 0
	s_cbranch_scc1 .Lup_half_peel
	s_add_u32 s2, s10, 0xfffc0080
	s_addc_u32 s3, s11, -1
	ds_read_b128 v[48:51], v237
	ds_read_b128 v[52:55], v237 offset:1024
	ds_read_b128 v[104:107], v237 offset:2048
	ds_read_b128 v[108:111], v237 offset:3072
	s_cmp_eq_u32 s67, 12
	s_cselect_b32 s13, s1, s3
	s_cselect_b32 s12, s9, s2
	s_cselect_b32 s3, s14, s39
	s_cselect_b32 s2, s15, s37
	s_add_i32 m0, s54, 0xc000
	ds_read_b128 v[112:115], v238
	ds_read_b128 v[116:119], v238 offset:1024
	ds_read_b128 v[120:123], v238 offset:2048
	ds_read_b128 v[156:159], v238 offset:3072
	ds_read_b128 v[160:163], v238 offset:4096
	ds_read_b128 v[164:167], v238 offset:5120
	ds_read_b128 v[190:193], v238 offset:6144
	global_load_lds_dwordx4 v186, s[10:11]
	s_add_i32 m0, s54, 0xe000
	ds_read_b128 v[194:197], v238 offset:7168
	global_load_lds_dwordx4 v188, s[10:11]
	s_waitcnt lgkmcnt(8)
	s_barrier
	s_waitcnt lgkmcnt(0)
	v_mfma_f32_16x16x32_bf16 v[152:155], v[48:51], v[112:115], 0
	v_mfma_f32_16x16x32_bf16 v[68:71], v[104:107], v[112:115], 0
	v_mfma_f32_16x16x32_bf16 v[148:151], v[48:51], v[120:123], 0
	v_mfma_f32_16x16x32_bf16 v[64:67], v[104:107], v[120:123], 0
	v_mfma_f32_16x16x32_bf16 v[136:139], v[48:51], v[160:163], 0
	v_mfma_f32_16x16x32_bf16 v[44:47], v[104:107], v[160:163], 0
	v_mfma_f32_16x16x32_bf16 v[128:131], v[48:51], v[190:193], 0
	v_mfma_f32_16x16x32_bf16 v[40:43], v[104:107], v[190:193], 0
	v_mfma_f32_16x16x32_bf16 v[152:155], v[52:55], v[116:119], v[152:155]
	v_mfma_f32_16x16x32_bf16 v[68:71], v[108:111], v[116:119], v[68:71]
	v_mfma_f32_16x16x32_bf16 v[148:151], v[52:55], v[156:159], v[148:151]
	v_mfma_f32_16x16x32_bf16 v[64:67], v[108:111], v[156:159], v[64:67]
	v_mfma_f32_16x16x32_bf16 v[136:139], v[52:55], v[164:167], v[136:139]
	v_mfma_f32_16x16x32_bf16 v[44:47], v[108:111], v[164:167], v[44:47]
	v_mfma_f32_16x16x32_bf16 v[128:131], v[52:55], v[194:197], v[128:131]
	v_mfma_f32_16x16x32_bf16 v[40:43], v[108:111], v[194:197], v[40:43]
	s_barrier
	s_add_i32 s68, s53, 0x10000
	s_add_u32 s98, s2, 0x80
	s_addc_u32 s99, s3, 0
	s_mov_b32 m0, s68
	ds_read_b128 v[198:201], v237 offset:16384
	ds_read_b128 v[202:205], v237 offset:17408
	ds_read_b128 v[206:209], v237 offset:18432
	global_load_lds_dwordx4 v168, s[2:3]
	s_add_i32 m0, s68, 0x2000
	ds_read_b128 v[210:213], v237 offset:19456
	global_load_lds_dwordx4 v184, s[2:3]
	s_barrier
	s_waitcnt lgkmcnt(0)
	v_mfma_f32_16x16x32_bf16 v[144:147], v[198:201], v[112:115], 0
	v_mfma_f32_16x16x32_bf16 v[60:63], v[206:209], v[112:115], 0
	v_mfma_f32_16x16x32_bf16 v[56:59], v[206:209], v[120:123], 0
	v_mfma_f32_16x16x32_bf16 v[36:39], v[206:209], v[160:163], 0
	v_mfma_f32_16x16x32_bf16 v[32:35], v[206:209], v[190:193], 0
	v_mfma_f32_16x16x32_bf16 v[144:147], v[202:205], v[116:119], v[144:147]
	v_mfma_f32_16x16x32_bf16 v[60:63], v[210:213], v[116:119], v[60:63]
	v_mfma_f32_16x16x32_bf16 v[112:115], v[198:201], v[120:123], 0
	v_mfma_f32_16x16x32_bf16 v[56:59], v[210:213], v[156:159], v[56:59]
	v_mfma_f32_16x16x32_bf16 v[116:119], v[198:201], v[160:163], 0
	v_mfma_f32_16x16x32_bf16 v[36:39], v[210:213], v[164:167], v[36:39]
	v_mfma_f32_16x16x32_bf16 v[120:123], v[198:201], v[190:193], 0
	v_mfma_f32_16x16x32_bf16 v[32:35], v[210:213], v[194:197], v[32:35]
	v_mfma_f32_16x16x32_bf16 v[112:115], v[202:205], v[156:159], v[112:115]
	v_mfma_f32_16x16x32_bf16 v[116:119], v[202:205], v[164:167], v[116:119]
	v_mfma_f32_16x16x32_bf16 v[120:123], v[202:205], v[194:197], v[120:123]
	s_mov_b32 m0, s54
	s_add_u32 s100, s12, 0x80
	s_addc_u32 s101, s13, 0
	s_barrier
	ds_read_b128 v[124:127], v238 offset:16384
	ds_read_b128 v[132:135], v238 offset:17408
	ds_read_b128 v[140:143], v238 offset:18432
	ds_read_b128 v[156:159], v238 offset:19456
	ds_read_b128 v[160:163], v238 offset:20480
	ds_read_b128 v[164:167], v238 offset:21504
	ds_read_b128 v[190:193], v238 offset:22528
	global_load_lds_dwordx4 v180, s[12:13]
	s_mov_b32 m0, s55
	ds_read_b128 v[194:197], v238 offset:23552
	global_load_lds_dwordx4 v182, s[12:13]
	s_barrier
	s_waitcnt lgkmcnt(0)
	v_mfma_f32_16x16x32_bf16 v[100:103], v[48:51], v[124:127], 0
	v_mfma_f32_16x16x32_bf16 v[28:31], v[104:107], v[124:127], 0
	v_mfma_f32_16x16x32_bf16 v[96:99], v[48:51], v[140:143], 0
	v_mfma_f32_16x16x32_bf16 v[24:27], v[104:107], v[140:143], 0
	v_mfma_f32_16x16x32_bf16 v[84:87], v[48:51], v[160:163], 0
	v_mfma_f32_16x16x32_bf16 v[12:15], v[104:107], v[160:163], 0
	v_mfma_f32_16x16x32_bf16 v[8:11], v[104:107], v[190:193], 0
	v_mfma_f32_16x16x32_bf16 v[100:103], v[52:55], v[132:135], v[100:103]
	v_mfma_f32_16x16x32_bf16 v[28:31], v[108:111], v[132:135], v[28:31]
	v_mfma_f32_16x16x32_bf16 v[96:99], v[52:55], v[156:159], v[96:99]
	v_mfma_f32_16x16x32_bf16 v[24:27], v[108:111], v[156:159], v[24:27]
	v_mfma_f32_16x16x32_bf16 v[84:87], v[52:55], v[164:167], v[84:87]
	v_mfma_f32_16x16x32_bf16 v[12:15], v[108:111], v[164:167], v[12:15]
	v_mfma_f32_16x16x32_bf16 v[48:51], v[48:51], v[190:193], 0
	v_mfma_f32_16x16x32_bf16 v[8:11], v[108:111], v[194:197], v[8:11]
	v_mfma_f32_16x16x32_bf16 v[48:51], v[52:55], v[194:197], v[48:51]
	s_barrier
	s_add_i32 s70, s53, 0x14000
	s_mov_b32 m0, s70
	s_add_u32 s68, s2, 0x40000
	s_addc_u32 s69, s3, 0
	global_load_lds_dwordx4 v168, s[68:69]
	s_add_i32 m0, s70, 0x2000
	s_nop 0
	global_load_lds_dwordx4 v184, s[68:69]
	s_waitcnt vmcnt(6)
	s_barrier
	v_mfma_f32_16x16x32_bf16 v[76:79], v[198:201], v[140:143], 0
	v_mfma_f32_16x16x32_bf16 v[20:23], v[206:209], v[124:127], 0
	v_mfma_f32_16x16x32_bf16 v[88:91], v[202:205], v[156:159], v[76:79]
	v_mfma_f32_16x16x32_bf16 v[16:19], v[206:209], v[140:143], 0
	v_mfma_f32_16x16x32_bf16 v[76:79], v[198:201], v[160:163], 0
	v_mfma_f32_16x16x32_bf16 v[4:7], v[206:209], v[160:163], 0
	v_mfma_f32_16x16x32_bf16 v[72:75], v[198:201], v[190:193], 0
	v_mfma_f32_16x16x32_bf16 v[0:3], v[206:209], v[190:193], 0
	v_mfma_f32_16x16x32_bf16 v[52:55], v[198:201], v[124:127], 0
	v_mfma_f32_16x16x32_bf16 v[20:23], v[210:213], v[132:135], v[20:23]
	v_mfma_f32_16x16x32_bf16 v[16:19], v[210:213], v[156:159], v[16:19]
	v_mfma_f32_16x16x32_bf16 v[80:83], v[202:205], v[164:167], v[76:79]
	v_mfma_f32_16x16x32_bf16 v[4:7], v[210:213], v[164:167], v[4:7]
	v_mfma_f32_16x16x32_bf16 v[72:75], v[202:205], v[194:197], v[72:75]
	v_mfma_f32_16x16x32_bf16 v[0:3], v[210:213], v[194:197], v[0:3]
	v_mfma_f32_16x16x32_bf16 v[52:55], v[202:205], v[132:135], v[52:55]
	s_barrier
	ds_read_b128 v[76:79], v237 offset:32768
	ds_read_b128 v[92:95], v237 offset:33792
	ds_read_b128 v[104:107], v237 offset:34816
	ds_read_b128 v[108:111], v237 offset:35840
	s_add_u32 s12, s12, 0x40000
	s_addc_u32 s13, s13, 0
	s_mov_b32 m0, s56
	ds_read_b128 v[124:127], v238 offset:32768
	ds_read_b128 v[132:135], v238 offset:33792
	ds_read_b128 v[156:159], v238 offset:34816
	ds_read_b128 v[160:163], v238 offset:35840
	ds_read_b128 v[164:167], v238 offset:36864
	ds_read_b128 v[190:193], v238 offset:37888
	ds_read_b128 v[194:197], v238 offset:38912
	global_load_lds_dwordx4 v180, s[12:13]
	s_mov_b32 m0, s57
	ds_read_b128 v[198:201], v238 offset:39936
	global_load_lds_dwordx4 v182, s[12:13]
	s_waitcnt lgkmcnt(8)
	s_barrier
	s_waitcnt lgkmcnt(0)
	v_mfma_f32_16x16x32_bf16 v[140:143], v[76:79], v[124:127], v[152:155]
	v_mfma_f32_16x16x32_bf16 v[152:155], v[92:95], v[132:135], v[140:143]
	v_mfma_f32_16x16x32_bf16 v[68:71], v[104:107], v[124:127], v[68:71]
	v_mfma_f32_16x16x32_bf16 v[140:143], v[76:79], v[156:159], v[148:151]
	v_mfma_f32_16x16x32_bf16 v[64:67], v[104:107], v[156:159], v[64:67]
	v_mfma_f32_16x16x32_bf16 v[136:139], v[76:79], v[164:167], v[136:139]
	v_mfma_f32_16x16x32_bf16 v[44:47], v[104:107], v[164:167], v[44:47]
	v_mfma_f32_16x16x32_bf16 v[128:131], v[76:79], v[194:197], v[128:131]
	v_mfma_f32_16x16x32_bf16 v[40:43], v[104:107], v[194:197], v[40:43]
	v_mfma_f32_16x16x32_bf16 v[68:71], v[108:111], v[132:135], v[68:71]
	v_mfma_f32_16x16x32_bf16 v[148:151], v[92:95], v[160:163], v[140:143]
	v_mfma_f32_16x16x32_bf16 v[64:67], v[108:111], v[160:163], v[64:67]
	v_mfma_f32_16x16x32_bf16 v[136:139], v[92:95], v[190:193], v[136:139]
	v_mfma_f32_16x16x32_bf16 v[44:47], v[108:111], v[190:193], v[44:47]
	v_mfma_f32_16x16x32_bf16 v[128:131], v[92:95], v[198:201], v[128:131]
	v_mfma_f32_16x16x32_bf16 v[40:43], v[108:111], v[198:201], v[40:43]
	s_barrier
	s_add_i32 s13, s53, 0x18000
	ds_read_b128 v[202:205], v237 offset:49152
	ds_read_b128 v[206:209], v237 offset:50176
	ds_read_b128 v[210:213], v237 offset:51200
	s_mov_b32 m0, s13
	ds_read_b128 v[214:217], v237 offset:52224
	global_load_lds_dwordx4 v168, s[98:99]
	s_add_i32 m0, s13, 0x2000
	s_nop 0
	global_load_lds_dwordx4 v184, s[98:99]
	s_barrier
	s_waitcnt lgkmcnt(0)
	v_mfma_f32_16x16x32_bf16 v[140:143], v[202:205], v[124:127], v[144:147]
	v_mfma_f32_16x16x32_bf16 v[112:115], v[202:205], v[156:159], v[112:115]
	v_mfma_f32_16x16x32_bf16 v[144:147], v[206:209], v[132:135], v[140:143]
	v_mfma_f32_16x16x32_bf16 v[60:63], v[210:213], v[124:127], v[60:63]
	v_mfma_f32_16x16x32_bf16 v[140:143], v[206:209], v[160:163], v[112:115]
	v_mfma_f32_16x16x32_bf16 v[112:115], v[202:205], v[164:167], v[116:119]
	v_mfma_f32_16x16x32_bf16 v[60:63], v[214:217], v[132:135], v[60:63]
	v_mfma_f32_16x16x32_bf16 v[56:59], v[210:213], v[156:159], v[56:59]
	v_mfma_f32_16x16x32_bf16 v[132:135], v[206:209], v[190:193], v[112:115]
	v_mfma_f32_16x16x32_bf16 v[36:39], v[210:213], v[164:167], v[36:39]
	v_mfma_f32_16x16x32_bf16 v[112:115], v[202:205], v[194:197], v[120:123]
	v_mfma_f32_16x16x32_bf16 v[32:35], v[210:213], v[194:197], v[32:35]
	v_mfma_f32_16x16x32_bf16 v[56:59], v[214:217], v[160:163], v[56:59]
	v_mfma_f32_16x16x32_bf16 v[36:39], v[214:217], v[190:193], v[36:39]
	v_mfma_f32_16x16x32_bf16 v[124:127], v[206:209], v[198:201], v[112:115]
	v_mfma_f32_16x16x32_bf16 v[32:35], v[214:217], v[198:201], v[32:35]
	s_mov_b32 m0, s62
	s_barrier
	ds_read_b128 v[112:115], v238 offset:49152
	ds_read_b128 v[116:119], v238 offset:50176
	ds_read_b128 v[120:123], v238 offset:51200
	ds_read_b128 v[156:159], v238 offset:52224
	ds_read_b128 v[160:163], v238 offset:53248
	ds_read_b128 v[164:167], v238 offset:54272
	ds_read_b128 v[190:193], v238 offset:55296
	global_load_lds_dwordx4 v180, s[100:101]
	s_mov_b32 m0, s63
	ds_read_b128 v[194:197], v238 offset:56320
	global_load_lds_dwordx4 v182, s[100:101]
	s_barrier
	s_waitcnt lgkmcnt(0)
	v_mfma_f32_16x16x32_bf16 v[100:103], v[76:79], v[112:115], v[100:103]
	v_mfma_f32_16x16x32_bf16 v[28:31], v[104:107], v[112:115], v[28:31]
	v_mfma_f32_16x16x32_bf16 v[96:99], v[76:79], v[120:123], v[96:99]
	v_mfma_f32_16x16x32_bf16 v[24:27], v[104:107], v[120:123], v[24:27]
	v_mfma_f32_16x16x32_bf16 v[84:87], v[76:79], v[160:163], v[84:87]
	v_mfma_f32_16x16x32_bf16 v[12:15], v[104:107], v[160:163], v[12:15]
	v_mfma_f32_16x16x32_bf16 v[48:51], v[76:79], v[190:193], v[48:51]
	v_mfma_f32_16x16x32_bf16 v[8:11], v[104:107], v[190:193], v[8:11]
	v_mfma_f32_16x16x32_bf16 v[100:103], v[92:95], v[116:119], v[100:103]
	v_mfma_f32_16x16x32_bf16 v[28:31], v[108:111], v[116:119], v[28:31]
	v_mfma_f32_16x16x32_bf16 v[96:99], v[92:95], v[156:159], v[96:99]
	v_mfma_f32_16x16x32_bf16 v[24:27], v[108:111], v[156:159], v[24:27]
	v_mfma_f32_16x16x32_bf16 v[84:87], v[92:95], v[164:167], v[84:87]
	v_mfma_f32_16x16x32_bf16 v[12:15], v[108:111], v[164:167], v[12:15]
	v_mfma_f32_16x16x32_bf16 v[76:79], v[92:95], v[194:197], v[48:51]
	v_mfma_f32_16x16x32_bf16 v[8:11], v[108:111], v[194:197], v[8:11]
	s_barrier
	s_add_i32 s12, s53, 0x1c000
	s_mov_b32 m0, s12
	s_add_u32 s2, s2, 0x40080
	s_addc_u32 s3, s3, 0
	global_load_lds_dwordx4 v168, s[2:3]
	s_add_i32 m0, s12, 0x2000
	s_nop 0
	global_load_lds_dwordx4 v184, s[2:3]
	s_waitcnt vmcnt(6)
	s_barrier
	v_mfma_f32_16x16x32_bf16 v[48:51], v[202:205], v[112:115], v[52:55]
	v_mfma_f32_16x16x32_bf16 v[92:95], v[206:209], v[116:119], v[48:51]
	v_mfma_f32_16x16x32_bf16 v[48:51], v[202:205], v[120:123], v[88:91]
	v_mfma_f32_16x16x32_bf16 v[88:91], v[206:209], v[156:159], v[48:51]
	v_mfma_f32_16x16x32_bf16 v[48:51], v[202:205], v[160:163], v[80:83]
	v_mfma_f32_16x16x32_bf16 v[20:23], v[210:213], v[112:115], v[20:23]
	v_mfma_f32_16x16x32_bf16 v[16:19], v[210:213], v[120:123], v[16:19]
	v_mfma_f32_16x16x32_bf16 v[80:83], v[206:209], v[164:167], v[48:51]
	v_mfma_f32_16x16x32_bf16 v[4:7], v[210:213], v[160:163], v[4:7]
	v_mfma_f32_16x16x32_bf16 v[48:51], v[202:205], v[190:193], v[72:75]
	v_mfma_f32_16x16x32_bf16 v[0:3], v[210:213], v[190:193], v[0:3]
	v_mfma_f32_16x16x32_bf16 v[20:23], v[214:217], v[116:119], v[20:23]
	v_mfma_f32_16x16x32_bf16 v[16:19], v[214:217], v[156:159], v[16:19]
	v_mfma_f32_16x16x32_bf16 v[4:7], v[214:217], v[164:167], v[4:7]
	v_mfma_f32_16x16x32_bf16 v[72:75], v[206:209], v[194:197], v[48:51]
	v_mfma_f32_16x16x32_bf16 v[0:3], v[214:217], v[194:197], v[0:3]
	s_add_i32 s67, s67, 2
	s_add_u32 s10, s10, 0x100
	s_addc_u32 s11, s11, 0
	s_add_u32 s37, s37, 0x100
	s_addc_u32 s39, s39, 0
	s_cmp_gt_u32 s67, 13
	s_barrier
.LBB0_880:
	s_add_u32 s2, s10, 0xfffc0080
	s_addc_u32 s3, s11, -1
	ds_read_b128 v[48:51], v237
	ds_read_b128 v[52:55], v237 offset:1024
	ds_read_b128 v[104:107], v237 offset:2048
	ds_read_b128 v[108:111], v237 offset:3072
	s_cmp_eq_u32 s67, 12
	s_cselect_b32 s13, s1, s3
	s_cselect_b32 s12, s9, s2
	s_cselect_b32 s3, s14, s39
	s_cselect_b32 s2, s15, s37
	s_add_i32 m0, s54, 0xc000
	ds_read_b128 v[112:115], v238
	ds_read_b128 v[116:119], v238 offset:1024
	ds_read_b128 v[120:123], v238 offset:2048
	ds_read_b128 v[156:159], v238 offset:3072
	ds_read_b128 v[160:163], v238 offset:4096
	ds_read_b128 v[164:167], v238 offset:5120
	ds_read_b128 v[190:193], v238 offset:6144
	global_load_lds_dwordx4 v186, s[10:11]
	s_add_i32 m0, s54, 0xe000
	ds_read_b128 v[194:197], v238 offset:7168
	global_load_lds_dwordx4 v188, s[10:11]
	s_waitcnt lgkmcnt(8)
	s_barrier
	s_waitcnt lgkmcnt(0)
	v_mfma_f32_16x16x32_bf16 v[152:155], v[48:51], v[112:115], v[152:155]
	v_mfma_f32_16x16x32_bf16 v[68:71], v[104:107], v[112:115], v[68:71]
	v_mfma_f32_16x16x32_bf16 v[148:151], v[48:51], v[120:123], v[148:151]
	v_mfma_f32_16x16x32_bf16 v[64:67], v[104:107], v[120:123], v[64:67]
	v_mfma_f32_16x16x32_bf16 v[136:139], v[48:51], v[160:163], v[136:139]
	v_mfma_f32_16x16x32_bf16 v[44:47], v[104:107], v[160:163], v[44:47]
	v_mfma_f32_16x16x32_bf16 v[128:131], v[48:51], v[190:193], v[128:131]
	v_mfma_f32_16x16x32_bf16 v[40:43], v[104:107], v[190:193], v[40:43]
	v_mfma_f32_16x16x32_bf16 v[152:155], v[52:55], v[116:119], v[152:155]
	v_mfma_f32_16x16x32_bf16 v[68:71], v[108:111], v[116:119], v[68:71]
	v_mfma_f32_16x16x32_bf16 v[148:151], v[52:55], v[156:159], v[148:151]
	v_mfma_f32_16x16x32_bf16 v[64:67], v[108:111], v[156:159], v[64:67]
	v_mfma_f32_16x16x32_bf16 v[136:139], v[52:55], v[164:167], v[136:139]
	v_mfma_f32_16x16x32_bf16 v[44:47], v[108:111], v[164:167], v[44:47]
	v_mfma_f32_16x16x32_bf16 v[128:131], v[52:55], v[194:197], v[128:131]
	v_mfma_f32_16x16x32_bf16 v[40:43], v[108:111], v[194:197], v[40:43]
	s_barrier
	s_add_i32 s68, s53, 0x10000
	s_add_u32 s98, s2, 0x80
	s_addc_u32 s99, s3, 0
	s_mov_b32 m0, s68
	ds_read_b128 v[198:201], v237 offset:16384
	ds_read_b128 v[202:205], v237 offset:17408
	ds_read_b128 v[206:209], v237 offset:18432
	global_load_lds_dwordx4 v168, s[2:3]
	s_add_i32 m0, s68, 0x2000
	ds_read_b128 v[210:213], v237 offset:19456
	global_load_lds_dwordx4 v184, s[2:3]
	s_barrier
	s_waitcnt lgkmcnt(0)
	v_mfma_f32_16x16x32_bf16 v[144:147], v[198:201], v[112:115], v[144:147]
	v_mfma_f32_16x16x32_bf16 v[60:63], v[206:209], v[112:115], v[60:63]
	v_mfma_f32_16x16x32_bf16 v[56:59], v[206:209], v[120:123], v[56:59]
	v_mfma_f32_16x16x32_bf16 v[36:39], v[206:209], v[160:163], v[36:39]
	v_mfma_f32_16x16x32_bf16 v[32:35], v[206:209], v[190:193], v[32:35]
	v_mfma_f32_16x16x32_bf16 v[144:147], v[202:205], v[116:119], v[144:147]
	v_mfma_f32_16x16x32_bf16 v[60:63], v[210:213], v[116:119], v[60:63]
	v_mfma_f32_16x16x32_bf16 v[112:115], v[198:201], v[120:123], v[140:143]
	v_mfma_f32_16x16x32_bf16 v[56:59], v[210:213], v[156:159], v[56:59]
	v_mfma_f32_16x16x32_bf16 v[116:119], v[198:201], v[160:163], v[132:135]
	v_mfma_f32_16x16x32_bf16 v[36:39], v[210:213], v[164:167], v[36:39]
	v_mfma_f32_16x16x32_bf16 v[120:123], v[198:201], v[190:193], v[124:127]
	v_mfma_f32_16x16x32_bf16 v[32:35], v[210:213], v[194:197], v[32:35]
	v_mfma_f32_16x16x32_bf16 v[112:115], v[202:205], v[156:159], v[112:115]
	v_mfma_f32_16x16x32_bf16 v[116:119], v[202:205], v[164:167], v[116:119]
	v_mfma_f32_16x16x32_bf16 v[120:123], v[202:205], v[194:197], v[120:123]
	s_mov_b32 m0, s54
	s_add_u32 s100, s12, 0x80
	s_addc_u32 s101, s13, 0
	s_barrier
	ds_read_b128 v[124:127], v238 offset:16384
	ds_read_b128 v[132:135], v238 offset:17408
	ds_read_b128 v[140:143], v238 offset:18432
	ds_read_b128 v[156:159], v238 offset:19456
	ds_read_b128 v[160:163], v238 offset:20480
	ds_read_b128 v[164:167], v238 offset:21504
	ds_read_b128 v[190:193], v238 offset:22528
	global_load_lds_dwordx4 v180, s[12:13]
	s_mov_b32 m0, s55
	ds_read_b128 v[194:197], v238 offset:23552
	global_load_lds_dwordx4 v182, s[12:13]
	s_barrier
	s_waitcnt lgkmcnt(0)
	v_mfma_f32_16x16x32_bf16 v[100:103], v[48:51], v[124:127], v[100:103]
	v_mfma_f32_16x16x32_bf16 v[28:31], v[104:107], v[124:127], v[28:31]
	v_mfma_f32_16x16x32_bf16 v[96:99], v[48:51], v[140:143], v[96:99]
	v_mfma_f32_16x16x32_bf16 v[24:27], v[104:107], v[140:143], v[24:27]
	v_mfma_f32_16x16x32_bf16 v[84:87], v[48:51], v[160:163], v[84:87]
	v_mfma_f32_16x16x32_bf16 v[12:15], v[104:107], v[160:163], v[12:15]
	v_mfma_f32_16x16x32_bf16 v[8:11], v[104:107], v[190:193], v[8:11]
	v_mfma_f32_16x16x32_bf16 v[100:103], v[52:55], v[132:135], v[100:103]
	v_mfma_f32_16x16x32_bf16 v[28:31], v[108:111], v[132:135], v[28:31]
	v_mfma_f32_16x16x32_bf16 v[96:99], v[52:55], v[156:159], v[96:99]
	v_mfma_f32_16x16x32_bf16 v[24:27], v[108:111], v[156:159], v[24:27]
	v_mfma_f32_16x16x32_bf16 v[84:87], v[52:55], v[164:167], v[84:87]
	v_mfma_f32_16x16x32_bf16 v[12:15], v[108:111], v[164:167], v[12:15]
	v_mfma_f32_16x16x32_bf16 v[48:51], v[48:51], v[190:193], v[76:79]
	v_mfma_f32_16x16x32_bf16 v[8:11], v[108:111], v[194:197], v[8:11]
	v_mfma_f32_16x16x32_bf16 v[48:51], v[52:55], v[194:197], v[48:51]
	s_barrier
	s_add_i32 s70, s53, 0x14000
	s_mov_b32 m0, s70
	s_add_u32 s68, s2, 0x40000
	s_addc_u32 s69, s3, 0
	global_load_lds_dwordx4 v168, s[68:69]
	s_add_i32 m0, s70, 0x2000
	s_nop 0
	global_load_lds_dwordx4 v184, s[68:69]
	s_waitcnt vmcnt(6)
	s_barrier
	v_mfma_f32_16x16x32_bf16 v[76:79], v[198:201], v[140:143], v[88:91]
	v_mfma_f32_16x16x32_bf16 v[20:23], v[206:209], v[124:127], v[20:23]
	v_mfma_f32_16x16x32_bf16 v[88:91], v[202:205], v[156:159], v[76:79]
	v_mfma_f32_16x16x32_bf16 v[16:19], v[206:209], v[140:143], v[16:19]
	v_mfma_f32_16x16x32_bf16 v[76:79], v[198:201], v[160:163], v[80:83]
	v_mfma_f32_16x16x32_bf16 v[4:7], v[206:209], v[160:163], v[4:7]
	v_mfma_f32_16x16x32_bf16 v[72:75], v[198:201], v[190:193], v[72:75]
	v_mfma_f32_16x16x32_bf16 v[0:3], v[206:209], v[190:193], v[0:3]
	v_mfma_f32_16x16x32_bf16 v[52:55], v[198:201], v[124:127], v[92:95]
	v_mfma_f32_16x16x32_bf16 v[20:23], v[210:213], v[132:135], v[20:23]
	v_mfma_f32_16x16x32_bf16 v[16:19], v[210:213], v[156:159], v[16:19]
	v_mfma_f32_16x16x32_bf16 v[80:83], v[202:205], v[164:167], v[76:79]
	v_mfma_f32_16x16x32_bf16 v[4:7], v[210:213], v[164:167], v[4:7]
	v_mfma_f32_16x16x32_bf16 v[72:75], v[202:205], v[194:197], v[72:75]
	v_mfma_f32_16x16x32_bf16 v[0:3], v[210:213], v[194:197], v[0:3]
	v_mfma_f32_16x16x32_bf16 v[52:55], v[202:205], v[132:135], v[52:55]
	s_barrier
	ds_read_b128 v[76:79], v237 offset:32768
	ds_read_b128 v[92:95], v237 offset:33792
	ds_read_b128 v[104:107], v237 offset:34816
	ds_read_b128 v[108:111], v237 offset:35840
	s_add_u32 s12, s12, 0x40000
	s_addc_u32 s13, s13, 0
	s_mov_b32 m0, s56
	ds_read_b128 v[124:127], v238 offset:32768
	ds_read_b128 v[132:135], v238 offset:33792
	ds_read_b128 v[156:159], v238 offset:34816
	ds_read_b128 v[160:163], v238 offset:35840
	ds_read_b128 v[164:167], v238 offset:36864
	ds_read_b128 v[190:193], v238 offset:37888
	ds_read_b128 v[194:197], v238 offset:38912
	global_load_lds_dwordx4 v180, s[12:13]
	s_mov_b32 m0, s57
	ds_read_b128 v[198:201], v238 offset:39936
	global_load_lds_dwordx4 v182, s[12:13]
	s_waitcnt lgkmcnt(8)
	s_barrier
	s_waitcnt lgkmcnt(0)
	v_mfma_f32_16x16x32_bf16 v[140:143], v[76:79], v[124:127], v[152:155]
	v_mfma_f32_16x16x32_bf16 v[152:155], v[92:95], v[132:135], v[140:143]
	v_mfma_f32_16x16x32_bf16 v[68:71], v[104:107], v[124:127], v[68:71]
	v_mfma_f32_16x16x32_bf16 v[140:143], v[76:79], v[156:159], v[148:151]
	v_mfma_f32_16x16x32_bf16 v[64:67], v[104:107], v[156:159], v[64:67]
	v_mfma_f32_16x16x32_bf16 v[136:139], v[76:79], v[164:167], v[136:139]
	v_mfma_f32_16x16x32_bf16 v[44:47], v[104:107], v[164:167], v[44:47]
	v_mfma_f32_16x16x32_bf16 v[128:131], v[76:79], v[194:197], v[128:131]
	v_mfma_f32_16x16x32_bf16 v[40:43], v[104:107], v[194:197], v[40:43]
	v_mfma_f32_16x16x32_bf16 v[68:71], v[108:111], v[132:135], v[68:71]
	v_mfma_f32_16x16x32_bf16 v[148:151], v[92:95], v[160:163], v[140:143]
	v_mfma_f32_16x16x32_bf16 v[64:67], v[108:111], v[160:163], v[64:67]
	v_mfma_f32_16x16x32_bf16 v[136:139], v[92:95], v[190:193], v[136:139]
	v_mfma_f32_16x16x32_bf16 v[44:47], v[108:111], v[190:193], v[44:47]
	v_mfma_f32_16x16x32_bf16 v[128:131], v[92:95], v[198:201], v[128:131]
	v_mfma_f32_16x16x32_bf16 v[40:43], v[108:111], v[198:201], v[40:43]
	s_barrier
	s_add_i32 s13, s53, 0x18000
	ds_read_b128 v[202:205], v237 offset:49152
	ds_read_b128 v[206:209], v237 offset:50176
	ds_read_b128 v[210:213], v237 offset:51200
	s_mov_b32 m0, s13
	ds_read_b128 v[214:217], v237 offset:52224
	global_load_lds_dwordx4 v168, s[98:99]
	s_add_i32 m0, s13, 0x2000
	s_nop 0
	global_load_lds_dwordx4 v184, s[98:99]
	s_barrier
	s_waitcnt lgkmcnt(0)
	v_mfma_f32_16x16x32_bf16 v[140:143], v[202:205], v[124:127], v[144:147]
	v_mfma_f32_16x16x32_bf16 v[112:115], v[202:205], v[156:159], v[112:115]
	v_mfma_f32_16x16x32_bf16 v[144:147], v[206:209], v[132:135], v[140:143]
	v_mfma_f32_16x16x32_bf16 v[60:63], v[210:213], v[124:127], v[60:63]
	v_mfma_f32_16x16x32_bf16 v[140:143], v[206:209], v[160:163], v[112:115]
	v_mfma_f32_16x16x32_bf16 v[112:115], v[202:205], v[164:167], v[116:119]
	v_mfma_f32_16x16x32_bf16 v[60:63], v[214:217], v[132:135], v[60:63]
	v_mfma_f32_16x16x32_bf16 v[56:59], v[210:213], v[156:159], v[56:59]
	v_mfma_f32_16x16x32_bf16 v[132:135], v[206:209], v[190:193], v[112:115]
	v_mfma_f32_16x16x32_bf16 v[36:39], v[210:213], v[164:167], v[36:39]
	v_mfma_f32_16x16x32_bf16 v[112:115], v[202:205], v[194:197], v[120:123]
	v_mfma_f32_16x16x32_bf16 v[32:35], v[210:213], v[194:197], v[32:35]
	v_mfma_f32_16x16x32_bf16 v[56:59], v[214:217], v[160:163], v[56:59]
	v_mfma_f32_16x16x32_bf16 v[36:39], v[214:217], v[190:193], v[36:39]
	v_mfma_f32_16x16x32_bf16 v[124:127], v[206:209], v[198:201], v[112:115]
	v_mfma_f32_16x16x32_bf16 v[32:35], v[214:217], v[198:201], v[32:35]
	s_mov_b32 m0, s62
	s_barrier
	ds_read_b128 v[112:115], v238 offset:49152
	ds_read_b128 v[116:119], v238 offset:50176
	ds_read_b128 v[120:123], v238 offset:51200
	ds_read_b128 v[156:159], v238 offset:52224
	ds_read_b128 v[160:163], v238 offset:53248
	ds_read_b128 v[164:167], v238 offset:54272
	ds_read_b128 v[190:193], v238 offset:55296
	global_load_lds_dwordx4 v180, s[100:101]
	s_mov_b32 m0, s63
	ds_read_b128 v[194:197], v238 offset:56320
	global_load_lds_dwordx4 v182, s[100:101]
	s_barrier
	s_waitcnt lgkmcnt(0)
	v_mfma_f32_16x16x32_bf16 v[100:103], v[76:79], v[112:115], v[100:103]
	v_mfma_f32_16x16x32_bf16 v[28:31], v[104:107], v[112:115], v[28:31]
	v_mfma_f32_16x16x32_bf16 v[96:99], v[76:79], v[120:123], v[96:99]
	v_mfma_f32_16x16x32_bf16 v[24:27], v[104:107], v[120:123], v[24:27]
	v_mfma_f32_16x16x32_bf16 v[84:87], v[76:79], v[160:163], v[84:87]
	v_mfma_f32_16x16x32_bf16 v[12:15], v[104:107], v[160:163], v[12:15]
	v_mfma_f32_16x16x32_bf16 v[48:51], v[76:79], v[190:193], v[48:51]
	v_mfma_f32_16x16x32_bf16 v[8:11], v[104:107], v[190:193], v[8:11]
	v_mfma_f32_16x16x32_bf16 v[100:103], v[92:95], v[116:119], v[100:103]
	v_mfma_f32_16x16x32_bf16 v[28:31], v[108:111], v[116:119], v[28:31]
	v_mfma_f32_16x16x32_bf16 v[96:99], v[92:95], v[156:159], v[96:99]
	v_mfma_f32_16x16x32_bf16 v[24:27], v[108:111], v[156:159], v[24:27]
	v_mfma_f32_16x16x32_bf16 v[84:87], v[92:95], v[164:167], v[84:87]
	v_mfma_f32_16x16x32_bf16 v[12:15], v[108:111], v[164:167], v[12:15]
	v_mfma_f32_16x16x32_bf16 v[76:79], v[92:95], v[194:197], v[48:51]
	v_mfma_f32_16x16x32_bf16 v[8:11], v[108:111], v[194:197], v[8:11]
	s_barrier
	s_add_i32 s12, s53, 0x1c000
	s_mov_b32 m0, s12
	s_add_u32 s2, s2, 0x40080
	s_addc_u32 s3, s3, 0
	global_load_lds_dwordx4 v168, s[2:3]
	s_add_i32 m0, s12, 0x2000
	s_nop 0
	global_load_lds_dwordx4 v184, s[2:3]
	s_waitcnt vmcnt(6)
	s_barrier
	v_mfma_f32_16x16x32_bf16 v[48:51], v[202:205], v[112:115], v[52:55]
	v_mfma_f32_16x16x32_bf16 v[92:95], v[206:209], v[116:119], v[48:51]
	v_mfma_f32_16x16x32_bf16 v[48:51], v[202:205], v[120:123], v[88:91]
	v_mfma_f32_16x16x32_bf16 v[88:91], v[206:209], v[156:159], v[48:51]
	v_mfma_f32_16x16x32_bf16 v[48:51], v[202:205], v[160:163], v[80:83]
	v_mfma_f32_16x16x32_bf16 v[20:23], v[210:213], v[112:115], v[20:23]
	v_mfma_f32_16x16x32_bf16 v[16:19], v[210:213], v[120:123], v[16:19]
	v_mfma_f32_16x16x32_bf16 v[80:83], v[206:209], v[164:167], v[48:51]
	v_mfma_f32_16x16x32_bf16 v[4:7], v[210:213], v[160:163], v[4:7]
	v_mfma_f32_16x16x32_bf16 v[48:51], v[202:205], v[190:193], v[72:75]
	v_mfma_f32_16x16x32_bf16 v[0:3], v[210:213], v[190:193], v[0:3]
	v_mfma_f32_16x16x32_bf16 v[20:23], v[214:217], v[116:119], v[20:23]
	v_mfma_f32_16x16x32_bf16 v[16:19], v[214:217], v[156:159], v[16:19]
	v_mfma_f32_16x16x32_bf16 v[4:7], v[214:217], v[164:167], v[4:7]
	v_mfma_f32_16x16x32_bf16 v[72:75], v[206:209], v[194:197], v[48:51]
	v_mfma_f32_16x16x32_bf16 v[0:3], v[214:217], v[194:197], v[0:3]
	s_add_i32 s67, s67, 2
	s_add_u32 s10, s10, 0x100
	s_addc_u32 s11, s11, 0
	s_add_u32 s37, s37, 0x100
	s_addc_u32 s39, s39, 0
	s_cmp_gt_u32 s67, 13
	s_barrier
	s_cbranch_scc0 .LBB0_880

.Lup_half_peel:
	s_add_u32 s2, s10, 0xfffc0080
	s_addc_u32 s3, s11, -1
	ds_read_b128 v[48:51], v237
	ds_read_b128 v[52:55], v237 offset:1024
	ds_read_b128 v[104:107], v237 offset:2048
	ds_read_b128 v[108:111], v237 offset:3072
	s_cmp_eq_u32 s67, 12
	s_cselect_b32 s13, s1, s3
	s_cselect_b32 s12, s9, s2
	s_cselect_b32 s3, s14, s39
	s_cselect_b32 s2, s15, s37
	s_add_i32 m0, s54, 0xc000
	ds_read_b128 v[112:115], v238
	ds_read_b128 v[116:119], v238 offset:1024
	ds_read_b128 v[120:123], v238 offset:2048
	ds_read_b128 v[156:159], v238 offset:3072
	ds_read_b128 v[160:163], v238 offset:4096
	ds_read_b128 v[164:167], v238 offset:5120
	ds_read_b128 v[190:193], v238 offset:6144
	global_load_lds_dwordx4 v186, s[10:11]
	s_add_i32 m0, s54, 0xe000
	ds_read_b128 v[194:197], v238 offset:7168
	global_load_lds_dwordx4 v188, s[10:11]
	s_waitcnt lgkmcnt(8)
	s_barrier
	s_waitcnt lgkmcnt(0)
	v_mfma_f32_16x16x32_bf16 v[152:155], v[48:51], v[112:115], 0
	v_mfma_f32_16x16x32_bf16 v[68:71], v[104:107], v[112:115], 0
	v_mfma_f32_16x16x32_bf16 v[148:151], v[48:51], v[120:123], 0
	v_mfma_f32_16x16x32_bf16 v[64:67], v[104:107], v[120:123], 0
	v_mfma_f32_16x16x32_bf16 v[136:139], v[48:51], v[160:163], 0
	v_mfma_f32_16x16x32_bf16 v[44:47], v[104:107], v[160:163], 0
	v_mfma_f32_16x16x32_bf16 v[128:131], v[48:51], v[190:193], 0
	v_mfma_f32_16x16x32_bf16 v[40:43], v[104:107], v[190:193], 0
	v_mfma_f32_16x16x32_bf16 v[152:155], v[52:55], v[116:119], v[152:155]
	v_mfma_f32_16x16x32_bf16 v[68:71], v[108:111], v[116:119], v[68:71]
	v_mfma_f32_16x16x32_bf16 v[148:151], v[52:55], v[156:159], v[148:151]
	v_mfma_f32_16x16x32_bf16 v[64:67], v[108:111], v[156:159], v[64:67]
	v_mfma_f32_16x16x32_bf16 v[136:139], v[52:55], v[164:167], v[136:139]
	v_mfma_f32_16x16x32_bf16 v[44:47], v[108:111], v[164:167], v[44:47]
	v_mfma_f32_16x16x32_bf16 v[128:131], v[52:55], v[194:197], v[128:131]
	v_mfma_f32_16x16x32_bf16 v[40:43], v[108:111], v[194:197], v[40:43]
	s_barrier
	s_add_i32 s68, s53, 0x10000
	s_add_u32 s98, s2, 0x80
	s_addc_u32 s99, s3, 0
	s_mov_b32 m0, s68
	ds_read_b128 v[198:201], v237 offset:16384
	ds_read_b128 v[202:205], v237 offset:17408
	ds_read_b128 v[206:209], v237 offset:18432
	global_load_lds_dwordx4 v168, s[2:3]
	s_add_i32 m0, s68, 0x2000
	ds_read_b128 v[210:213], v237 offset:19456
	global_load_lds_dwordx4 v184, s[2:3]
	s_barrier
	s_waitcnt lgkmcnt(0)
	v_mfma_f32_16x16x32_bf16 v[144:147], v[198:201], v[112:115], 0
	v_mfma_f32_16x16x32_bf16 v[60:63], v[206:209], v[112:115], 0
	v_mfma_f32_16x16x32_bf16 v[56:59], v[206:209], v[120:123], 0
	v_mfma_f32_16x16x32_bf16 v[36:39], v[206:209], v[160:163], 0
	v_mfma_f32_16x16x32_bf16 v[32:35], v[206:209], v[190:193], 0
	v_mfma_f32_16x16x32_bf16 v[144:147], v[202:205], v[116:119], v[144:147]
	v_mfma_f32_16x16x32_bf16 v[60:63], v[210:213], v[116:119], v[60:63]
	v_mfma_f32_16x16x32_bf16 v[112:115], v[198:201], v[120:123], 0
	v_mfma_f32_16x16x32_bf16 v[56:59], v[210:213], v[156:159], v[56:59]
	v_mfma_f32_16x16x32_bf16 v[116:119], v[198:201], v[160:163], 0
	v_mfma_f32_16x16x32_bf16 v[36:39], v[210:213], v[164:167], v[36:39]
	v_mfma_f32_16x16x32_bf16 v[120:123], v[198:201], v[190:193], 0
	v_mfma_f32_16x16x32_bf16 v[32:35], v[210:213], v[194:197], v[32:35]
	v_mfma_f32_16x16x32_bf16 v[112:115], v[202:205], v[156:159], v[112:115]
	v_mfma_f32_16x16x32_bf16 v[116:119], v[202:205], v[164:167], v[116:119]
	v_mfma_f32_16x16x32_bf16 v[120:123], v[202:205], v[194:197], v[120:123]
	s_mov_b32 m0, s54
	s_add_u32 s100, s12, 0x80
	s_addc_u32 s101, s13, 0
	s_barrier
	ds_read_b128 v[124:127], v238 offset:16384
	ds_read_b128 v[132:135], v238 offset:17408
	ds_read_b128 v[140:143], v238 offset:18432
	ds_read_b128 v[156:159], v238 offset:19456
	ds_read_b128 v[160:163], v238 offset:20480
	ds_read_b128 v[164:167], v238 offset:21504
	ds_read_b128 v[190:193], v238 offset:22528
	global_load_lds_dwordx4 v180, s[12:13]
	s_mov_b32 m0, s55
	ds_read_b128 v[194:197], v238 offset:23552
	global_load_lds_dwordx4 v182, s[12:13]
	s_barrier
	s_waitcnt lgkmcnt(0)
	s_barrier
	s_add_i32 s70, s53, 0x14000
	s_mov_b32 m0, s70
	s_add_u32 s68, s2, 0x40000
	s_addc_u32 s69, s3, 0
	global_load_lds_dwordx4 v168, s[68:69]
	s_add_i32 m0, s70, 0x2000
	s_nop 0
	global_load_lds_dwordx4 v184, s[68:69]
	s_waitcnt vmcnt(6)
	s_barrier
	s_barrier
	ds_read_b128 v[76:79], v237 offset:32768
	ds_read_b128 v[92:95], v237 offset:33792
	ds_read_b128 v[104:107], v237 offset:34816
	ds_read_b128 v[108:111], v237 offset:35840
	s_add_u32 s12, s12, 0x40000
	s_addc_u32 s13, s13, 0
	s_mov_b32 m0, s56
	ds_read_b128 v[124:127], v238 offset:32768
	ds_read_b128 v[132:135], v238 offset:33792
	ds_read_b128 v[156:159], v238 offset:34816
	ds_read_b128 v[160:163], v238 offset:35840
	ds_read_b128 v[164:167], v238 offset:36864
	ds_read_b128 v[190:193], v238 offset:37888
	ds_read_b128 v[194:197], v238 offset:38912
	global_load_lds_dwordx4 v180, s[12:13]
	s_mov_b32 m0, s57
	ds_read_b128 v[198:201], v238 offset:39936
	global_load_lds_dwordx4 v182, s[12:13]
	s_waitcnt lgkmcnt(8)
	s_barrier
	s_waitcnt lgkmcnt(0)
	v_mfma_f32_16x16x32_bf16 v[140:143], v[76:79], v[124:127], v[152:155]
	v_mfma_f32_16x16x32_bf16 v[152:155], v[92:95], v[132:135], v[140:143]
	v_mfma_f32_16x16x32_bf16 v[68:71], v[104:107], v[124:127], v[68:71]
	v_mfma_f32_16x16x32_bf16 v[140:143], v[76:79], v[156:159], v[148:151]
	v_mfma_f32_16x16x32_bf16 v[64:67], v[104:107], v[156:159], v[64:67]
	v_mfma_f32_16x16x32_bf16 v[136:139], v[76:79], v[164:167], v[136:139]
	v_mfma_f32_16x16x32_bf16 v[44:47], v[104:107], v[164:167], v[44:47]
	v_mfma_f32_16x16x32_bf16 v[128:131], v[76:79], v[194:197], v[128:131]
	v_mfma_f32_16x16x32_bf16 v[40:43], v[104:107], v[194:197], v[40:43]
	v_mfma_f32_16x16x32_bf16 v[68:71], v[108:111], v[132:135], v[68:71]
	v_mfma_f32_16x16x32_bf16 v[148:151], v[92:95], v[160:163], v[140:143]
	v_mfma_f32_16x16x32_bf16 v[64:67], v[108:111], v[160:163], v[64:67]
	v_mfma_f32_16x16x32_bf16 v[136:139], v[92:95], v[190:193], v[136:139]
	v_mfma_f32_16x16x32_bf16 v[44:47], v[108:111], v[190:193], v[44:47]
	v_mfma_f32_16x16x32_bf16 v[128:131], v[92:95], v[198:201], v[128:131]
	v_mfma_f32_16x16x32_bf16 v[40:43], v[108:111], v[198:201], v[40:43]
	s_barrier
	s_add_i32 s13, s53, 0x18000
	ds_read_b128 v[202:205], v237 offset:49152
	ds_read_b128 v[206:209], v237 offset:50176
	ds_read_b128 v[210:213], v237 offset:51200
	s_mov_b32 m0, s13
	ds_read_b128 v[214:217], v237 offset:52224
	global_load_lds_dwordx4 v168, s[98:99]
	s_add_i32 m0, s13, 0x2000
	s_nop 0
	global_load_lds_dwordx4 v184, s[98:99]
	s_barrier
	s_waitcnt lgkmcnt(0)
	v_mfma_f32_16x16x32_bf16 v[140:143], v[202:205], v[124:127], v[144:147]
	v_mfma_f32_16x16x32_bf16 v[112:115], v[202:205], v[156:159], v[112:115]
	v_mfma_f32_16x16x32_bf16 v[144:147], v[206:209], v[132:135], v[140:143]
	v_mfma_f32_16x16x32_bf16 v[60:63], v[210:213], v[124:127], v[60:63]
	v_mfma_f32_16x16x32_bf16 v[140:143], v[206:209], v[160:163], v[112:115]
	v_mfma_f32_16x16x32_bf16 v[112:115], v[202:205], v[164:167], v[116:119]
	v_mfma_f32_16x16x32_bf16 v[60:63], v[214:217], v[132:135], v[60:63]
	v_mfma_f32_16x16x32_bf16 v[56:59], v[210:213], v[156:159], v[56:59]
	v_mfma_f32_16x16x32_bf16 v[132:135], v[206:209], v[190:193], v[112:115]
	v_mfma_f32_16x16x32_bf16 v[36:39], v[210:213], v[164:167], v[36:39]
	v_mfma_f32_16x16x32_bf16 v[112:115], v[202:205], v[194:197], v[120:123]
	v_mfma_f32_16x16x32_bf16 v[32:35], v[210:213], v[194:197], v[32:35]
	v_mfma_f32_16x16x32_bf16 v[56:59], v[214:217], v[160:163], v[56:59]
	v_mfma_f32_16x16x32_bf16 v[36:39], v[214:217], v[190:193], v[36:39]
	v_mfma_f32_16x16x32_bf16 v[124:127], v[206:209], v[198:201], v[112:115]
	v_mfma_f32_16x16x32_bf16 v[32:35], v[214:217], v[198:201], v[32:35]
	s_mov_b32 m0, s62
	s_barrier
	ds_read_b128 v[112:115], v238 offset:49152
	ds_read_b128 v[116:119], v238 offset:50176
	ds_read_b128 v[120:123], v238 offset:51200
	ds_read_b128 v[156:159], v238 offset:52224
	ds_read_b128 v[160:163], v238 offset:53248
	ds_read_b128 v[164:167], v238 offset:54272
	ds_read_b128 v[190:193], v238 offset:55296
	global_load_lds_dwordx4 v180, s[100:101]
	s_mov_b32 m0, s63
	ds_read_b128 v[194:197], v238 offset:56320
	global_load_lds_dwordx4 v182, s[100:101]
	s_barrier
	s_waitcnt lgkmcnt(0)
	s_barrier
	s_add_i32 s12, s53, 0x1c000
	s_mov_b32 m0, s12
	s_add_u32 s2, s2, 0x40080
	s_addc_u32 s3, s3, 0
	global_load_lds_dwordx4 v168, s[2:3]
	s_add_i32 m0, s12, 0x2000
	s_nop 0
	global_load_lds_dwordx4 v184, s[2:3]
	s_waitcnt vmcnt(6)
	s_barrier
	s_add_i32 s67, s67, 2
	s_add_u32 s10, s10, 0x100
	s_addc_u32 s11, s11, 0
	s_add_u32 s37, s37, 0x100
	s_addc_u32 s39, s39, 0
	s_cmp_gt_u32 s67, 13
	s_barrier
.Lup_half_loop:
	s_add_u32 s2, s10, 0xfffc0080
	s_addc_u32 s3, s11, -1
	ds_read_b128 v[48:51], v237
	ds_read_b128 v[52:55], v237 offset:1024
	ds_read_b128 v[104:107], v237 offset:2048
	ds_read_b128 v[108:111], v237 offset:3072
	s_cmp_eq_u32 s67, 12
	s_cselect_b32 s13, s1, s3
	s_cselect_b32 s12, s9, s2
	s_cselect_b32 s3, s14, s39
	s_cselect_b32 s2, s15, s37
	s_add_i32 m0, s54, 0xc000
	ds_read_b128 v[112:115], v238
	ds_read_b128 v[116:119], v238 offset:1024
	ds_read_b128 v[120:123], v238 offset:2048
	ds_read_b128 v[156:159], v238 offset:3072
	ds_read_b128 v[160:163], v238 offset:4096
	ds_read_b128 v[164:167], v238 offset:5120
	ds_read_b128 v[190:193], v238 offset:6144
	global_load_lds_dwordx4 v186, s[10:11]
	s_add_i32 m0, s54, 0xe000
	ds_read_b128 v[194:197], v238 offset:7168
	global_load_lds_dwordx4 v188, s[10:11]
	s_waitcnt lgkmcnt(8)
	s_barrier
	s_waitcnt lgkmcnt(0)
	v_mfma_f32_16x16x32_bf16 v[152:155], v[48:51], v[112:115], v[152:155]
	v_mfma_f32_16x16x32_bf16 v[68:71], v[104:107], v[112:115], v[68:71]
	v_mfma_f32_16x16x32_bf16 v[148:151], v[48:51], v[120:123], v[148:151]
	v_mfma_f32_16x16x32_bf16 v[64:67], v[104:107], v[120:123], v[64:67]
	v_mfma_f32_16x16x32_bf16 v[136:139], v[48:51], v[160:163], v[136:139]
	v_mfma_f32_16x16x32_bf16 v[44:47], v[104:107], v[160:163], v[44:47]
	v_mfma_f32_16x16x32_bf16 v[128:131], v[48:51], v[190:193], v[128:131]
	v_mfma_f32_16x16x32_bf16 v[40:43], v[104:107], v[190:193], v[40:43]
	v_mfma_f32_16x16x32_bf16 v[152:155], v[52:55], v[116:119], v[152:155]
	v_mfma_f32_16x16x32_bf16 v[68:71], v[108:111], v[116:119], v[68:71]
	v_mfma_f32_16x16x32_bf16 v[148:151], v[52:55], v[156:159], v[148:151]
	v_mfma_f32_16x16x32_bf16 v[64:67], v[108:111], v[156:159], v[64:67]
	v_mfma_f32_16x16x32_bf16 v[136:139], v[52:55], v[164:167], v[136:139]
	v_mfma_f32_16x16x32_bf16 v[44:47], v[108:111], v[164:167], v[44:47]
	v_mfma_f32_16x16x32_bf16 v[128:131], v[52:55], v[194:197], v[128:131]
	v_mfma_f32_16x16x32_bf16 v[40:43], v[108:111], v[194:197], v[40:43]
	s_barrier
	s_add_i32 s68, s53, 0x10000
	s_add_u32 s98, s2, 0x80
	s_addc_u32 s99, s3, 0
	s_mov_b32 m0, s68
	ds_read_b128 v[198:201], v237 offset:16384
	ds_read_b128 v[202:205], v237 offset:17408
	ds_read_b128 v[206:209], v237 offset:18432
	global_load_lds_dwordx4 v168, s[2:3]
	s_add_i32 m0, s68, 0x2000
	ds_read_b128 v[210:213], v237 offset:19456
	global_load_lds_dwordx4 v184, s[2:3]
	s_barrier
	s_waitcnt lgkmcnt(0)
	v_mfma_f32_16x16x32_bf16 v[144:147], v[198:201], v[112:115], v[144:147]
	v_mfma_f32_16x16x32_bf16 v[60:63], v[206:209], v[112:115], v[60:63]
	v_mfma_f32_16x16x32_bf16 v[56:59], v[206:209], v[120:123], v[56:59]
	v_mfma_f32_16x16x32_bf16 v[36:39], v[206:209], v[160:163], v[36:39]
	v_mfma_f32_16x16x32_bf16 v[32:35], v[206:209], v[190:193], v[32:35]
	v_mfma_f32_16x16x32_bf16 v[144:147], v[202:205], v[116:119], v[144:147]
	v_mfma_f32_16x16x32_bf16 v[60:63], v[210:213], v[116:119], v[60:63]
	v_mfma_f32_16x16x32_bf16 v[112:115], v[198:201], v[120:123], v[140:143]
	v_mfma_f32_16x16x32_bf16 v[56:59], v[210:213], v[156:159], v[56:59]
	v_mfma_f32_16x16x32_bf16 v[116:119], v[198:201], v[160:163], v[132:135]
	v_mfma_f32_16x16x32_bf16 v[36:39], v[210:213], v[164:167], v[36:39]
	v_mfma_f32_16x16x32_bf16 v[120:123], v[198:201], v[190:193], v[124:127]
	v_mfma_f32_16x16x32_bf16 v[32:35], v[210:213], v[194:197], v[32:35]
	v_mfma_f32_16x16x32_bf16 v[112:115], v[202:205], v[156:159], v[112:115]
	v_mfma_f32_16x16x32_bf16 v[116:119], v[202:205], v[164:167], v[116:119]
	v_mfma_f32_16x16x32_bf16 v[120:123], v[202:205], v[194:197], v[120:123]
	s_mov_b32 m0, s54
	s_add_u32 s100, s12, 0x80
	s_addc_u32 s101, s13, 0
	s_barrier
	ds_read_b128 v[124:127], v238 offset:16384
	ds_read_b128 v[132:135], v238 offset:17408
	ds_read_b128 v[140:143], v238 offset:18432
	ds_read_b128 v[156:159], v238 offset:19456
	ds_read_b128 v[160:163], v238 offset:20480
	ds_read_b128 v[164:167], v238 offset:21504
	ds_read_b128 v[190:193], v238 offset:22528
	global_load_lds_dwordx4 v180, s[12:13]
	s_mov_b32 m0, s55
	ds_read_b128 v[194:197], v238 offset:23552
	global_load_lds_dwordx4 v182, s[12:13]
	s_barrier
	s_waitcnt lgkmcnt(0)
	s_barrier
	s_add_i32 s70, s53, 0x14000
	s_mov_b32 m0, s70
	s_add_u32 s68, s2, 0x40000
	s_addc_u32 s69, s3, 0
	global_load_lds_dwordx4 v168, s[68:69]
	s_add_i32 m0, s70, 0x2000
	s_nop 0
	global_load_lds_dwordx4 v184, s[68:69]
	s_waitcnt vmcnt(6)
	s_barrier
	s_barrier
	ds_read_b128 v[76:79], v237 offset:32768
	ds_read_b128 v[92:95], v237 offset:33792
	ds_read_b128 v[104:107], v237 offset:34816
	ds_read_b128 v[108:111], v237 offset:35840
	s_add_u32 s12, s12, 0x40000
	s_addc_u32 s13, s13, 0
	s_mov_b32 m0, s56
	ds_read_b128 v[124:127], v238 offset:32768
	ds_read_b128 v[132:135], v238 offset:33792
	ds_read_b128 v[156:159], v238 offset:34816
	ds_read_b128 v[160:163], v238 offset:35840
	ds_read_b128 v[164:167], v238 offset:36864
	ds_read_b128 v[190:193], v238 offset:37888
	ds_read_b128 v[194:197], v238 offset:38912
	global_load_lds_dwordx4 v180, s[12:13]
	s_mov_b32 m0, s57
	ds_read_b128 v[198:201], v238 offset:39936
	global_load_lds_dwordx4 v182, s[12:13]
	s_waitcnt lgkmcnt(8)
	s_barrier
	s_waitcnt lgkmcnt(0)
	v_mfma_f32_16x16x32_bf16 v[140:143], v[76:79], v[124:127], v[152:155]
	v_mfma_f32_16x16x32_bf16 v[152:155], v[92:95], v[132:135], v[140:143]
	v_mfma_f32_16x16x32_bf16 v[68:71], v[104:107], v[124:127], v[68:71]
	v_mfma_f32_16x16x32_bf16 v[140:143], v[76:79], v[156:159], v[148:151]
	v_mfma_f32_16x16x32_bf16 v[64:67], v[104:107], v[156:159], v[64:67]
	v_mfma_f32_16x16x32_bf16 v[136:139], v[76:79], v[164:167], v[136:139]
	v_mfma_f32_16x16x32_bf16 v[44:47], v[104:107], v[164:167], v[44:47]
	v_mfma_f32_16x16x32_bf16 v[128:131], v[76:79], v[194:197], v[128:131]
	v_mfma_f32_16x16x32_bf16 v[40:43], v[104:107], v[194:197], v[40:43]
	v_mfma_f32_16x16x32_bf16 v[68:71], v[108:111], v[132:135], v[68:71]
	v_mfma_f32_16x16x32_bf16 v[148:151], v[92:95], v[160:163], v[140:143]
	v_mfma_f32_16x16x32_bf16 v[64:67], v[108:111], v[160:163], v[64:67]
	v_mfma_f32_16x16x32_bf16 v[136:139], v[92:95], v[190:193], v[136:139]
	v_mfma_f32_16x16x32_bf16 v[44:47], v[108:111], v[190:193], v[44:47]
	v_mfma_f32_16x16x32_bf16 v[128:131], v[92:95], v[198:201], v[128:131]
	v_mfma_f32_16x16x32_bf16 v[40:43], v[108:111], v[198:201], v[40:43]
	s_barrier
	s_add_i32 s13, s53, 0x18000
	ds_read_b128 v[202:205], v237 offset:49152
	ds_read_b128 v[206:209], v237 offset:50176
	ds_read_b128 v[210:213], v237 offset:51200
	s_mov_b32 m0, s13
	ds_read_b128 v[214:217], v237 offset:52224
	global_load_lds_dwordx4 v168, s[98:99]
	s_add_i32 m0, s13, 0x2000
	s_nop 0
	global_load_lds_dwordx4 v184, s[98:99]
	s_barrier
	s_waitcnt lgkmcnt(0)
	v_mfma_f32_16x16x32_bf16 v[140:143], v[202:205], v[124:127], v[144:147]
	v_mfma_f32_16x16x32_bf16 v[112:115], v[202:205], v[156:159], v[112:115]
	v_mfma_f32_16x16x32_bf16 v[144:147], v[206:209], v[132:135], v[140:143]
	v_mfma_f32_16x16x32_bf16 v[60:63], v[210:213], v[124:127], v[60:63]
	v_mfma_f32_16x16x32_bf16 v[140:143], v[206:209], v[160:163], v[112:115]
	v_mfma_f32_16x16x32_bf16 v[112:115], v[202:205], v[164:167], v[116:119]
	v_mfma_f32_16x16x32_bf16 v[60:63], v[214:217], v[132:135], v[60:63]
	v_mfma_f32_16x16x32_bf16 v[56:59], v[210:213], v[156:159], v[56:59]
	v_mfma_f32_16x16x32_bf16 v[132:135], v[206:209], v[190:193], v[112:115]
	v_mfma_f32_16x16x32_bf16 v[36:39], v[210:213], v[164:167], v[36:39]
	v_mfma_f32_16x16x32_bf16 v[112:115], v[202:205], v[194:197], v[120:123]
	v_mfma_f32_16x16x32_bf16 v[32:35], v[210:213], v[194:197], v[32:35]
	v_mfma_f32_16x16x32_bf16 v[56:59], v[214:217], v[160:163], v[56:59]
	v_mfma_f32_16x16x32_bf16 v[36:39], v[214:217], v[190:193], v[36:39]
	v_mfma_f32_16x16x32_bf16 v[124:127], v[206:209], v[198:201], v[112:115]
	v_mfma_f32_16x16x32_bf16 v[32:35], v[214:217], v[198:201], v[32:35]
	s_mov_b32 m0, s62
	s_barrier
	ds_read_b128 v[112:115], v238 offset:49152
	ds_read_b128 v[116:119], v238 offset:50176
	ds_read_b128 v[120:123], v238 offset:51200
	ds_read_b128 v[156:159], v238 offset:52224
	ds_read_b128 v[160:163], v238 offset:53248
	ds_read_b128 v[164:167], v238 offset:54272
	ds_read_b128 v[190:193], v238 offset:55296
	global_load_lds_dwordx4 v180, s[100:101]
	s_mov_b32 m0, s63
	ds_read_b128 v[194:197], v238 offset:56320
	global_load_lds_dwordx4 v182, s[100:101]
	s_barrier
	s_waitcnt lgkmcnt(0)
	s_barrier
	s_add_i32 s12, s53, 0x1c000
	s_mov_b32 m0, s12
	s_add_u32 s2, s2, 0x40080
	s_addc_u32 s3, s3, 0
	global_load_lds_dwordx4 v168, s[2:3]
	s_add_i32 m0, s12, 0x2000
	s_nop 0
	global_load_lds_dwordx4 v184, s[2:3]
	s_waitcnt vmcnt(6)
	s_barrier
	s_add_i32 s67, s67, 2
	s_add_u32 s10, s10, 0x100
	s_addc_u32 s11, s11, 0
	s_add_u32 s37, s37, 0x100
	s_addc_u32 s39, s39, 0
	s_cmp_gt_u32 s67, 13
	s_barrier
	s_cbranch_scc0 .Lup_half_loop
	s_branch .Lup_epi

.LBB0_1039:
	s_add_u32 s16, s46, 0xde82000
	v_readlane_b32 s6, v254, 53
	s_addc_u32 s17, s45, 0
	s_mul_i32 s6, s6, 0x1e000
	s_add_u32 s6, s46, s6
	s_addc_u32 s7, s45, 0
	s_add_u32 s41, s6, 0x2ec7000
	s_addc_u32 s42, s7, 0
	s_add_u32 s18, s46, 0xc582000
	s_addc_u32 s19, s45, 0
	s_add_u32 s43, s46, 0x2f33000
	s_addc_u32 s44, s45, 0
	v_bfe_u32 v192, v12, 4, 2
	s_add_u32 s20, s46, 0x2f16000
	v_and_b32_e32 v193, 15, v12
	v_lshlrev_b32_e32 v17, 4, v192
	v_lshlrev_b32_e32 v12, 2, v12
	s_addc_u32 s21, s45, 0
	s_lshl_b32 s45, s0, 6
	v_lshl_or_b32 v17, v193, 6, v17
	s_lshl_b32 s0, s0, 13
	v_and_b32_e32 v12, 32, v12
	v_bitop3_b32 v18, v17, s0, v12 bitop3:0xde
	s_lshl_b32 s0, s1, 5
	s_and_b32 s46, s0, 0x60
	s_add_i32 m0, s37, 0x18000
	v_lshl_add_u64 v[6:7], v[6:7], 0, s[78:79]
	s_lshl_b32 s0, s46, 7
	s_waitcnt vmcnt(4)
	s_barrier
	global_load_lds_dwordx4 v[6:7], off
	v_lshl_add_u64 v[4:5], v[4:5], 0, s[78:79]
	s_add_i32 m0, s37, 0x1a000
	s_add_i32 s47, s37, 0x8000
	s_add_i32 s49, s37, 0xa000
	v_bitop3_b32 v194, s0, v17, v12 bitop3:0xf6
	v_add_u32_e32 v194, 0x10000, v194
	global_load_lds_dwordx4 v[4:5], off
	v_lshl_add_u64 v[2:3], v[2:3], 0, s[78:79]
	s_mov_b32 m0, s47
	s_add_u32 s0, s2, 0xb0080
	global_load_lds_dwordx4 v[2:3], off
	v_lshl_add_u64 v[0:1], v[0:1], 0, s[78:79]
	s_mov_b32 m0, s49
	s_addc_u32 s1, s3, 0
	global_load_lds_dwordx4 v[0:1], off
	s_add_i32 m0, s37, 0x1c000
	v_lshl_add_u64 v[0:1], s[0:1], 0, v[168:169]
	global_load_lds_dwordx4 v[0:1], off
	v_lshl_add_u64 v[0:1], s[0:1], 0, v[164:165]
	s_add_i32 m0, s37, 0x1e000
	s_movk_i32 s6, 0xb00
	global_load_lds_dwordx4 v[0:1], off
	v_lshrrev_b32_e32 v1, 1, v8
	v_mul_lo_u32 v0, v10, s6
	s_mov_b32 s7, 0xb000
	v_mad_u64_u32 v[0:1], s[0:1], v1, s7, v[0:1]
	v_or_b32_e32 v0, v0, v9
	v_add_lshl_u32 v0, v0, v11, 1
	v_mov_b32_e32 v1, v169
	s_mov_b64 s[8:9], 0xb0080
	v_lshl_add_u64 v[166:167], v[0:1], 0, s[8:9]
	v_lshrrev_b32_e32 v1, 1, v13
	v_mul_lo_u32 v0, v15, s6
	v_mad_u64_u32 v[0:1], s[0:1], v1, s7, v[0:1]
	s_waitcnt vmcnt(6)
	v_or_b32_e32 v0, v0, v14
	v_add_lshl_u32 v0, v0, v16, 1
	v_mov_b32_e32 v1, v169
	s_ashr_i32 s50, s29, 31
	v_lshl_add_u64 v[180:181], v[0:1], 0, s[8:9]
	s_mov_b32 s51, 0
	v_add_u32_e32 v195, 0, v18
	s_barrier
	s_branch .LBB0_1042

.LBB0_1048:
	s_add_u32 s56, s2, 0x100
	s_addc_u32 s57, s3, 0
	s_mov_b32 s58, -2
	s_add_u32 s2, s24, 0x100
	s_addc_u32 s3, s25, 0
	ds_read_b128 v[40:43], v194
	ds_read_b128 v[44:47], v194 offset:1024
	ds_read_b128 v[48:51], v194 offset:2048
	ds_read_b128 v[52:55], v194 offset:3072
	s_cmp_eq_u32 s58, 40
	s_cselect_b32 s27, s1, s3
	s_cselect_b32 s26, s0, s2
	s_cselect_b32 s9, s23, s57
	s_cselect_b32 s8, s22, s56
	s_add_i32 m0, s37, 0xc000
	ds_read_b128 v[56:59], v195
	ds_read_b128 v[60:63], v195 offset:1024
	ds_read_b128 v[72:75], v195 offset:2048
	ds_read_b128 v[84:87], v195 offset:3072
	ds_read_b128 v[182:185], v195 offset:4096
	ds_read_b128 v[186:189], v195 offset:5120
	ds_read_b128 v[196:199], v195 offset:6144
	global_load_lds_dwordx4 v166, s[24:25]
	s_add_i32 m0, s37, 0xe000
	ds_read_b128 v[200:203], v195 offset:7168
	global_load_lds_dwordx4 v180, s[24:25]
	s_waitcnt lgkmcnt(8)
	s_barrier
	s_waitcnt lgkmcnt(0)
	v_mfma_f32_16x16x32_bf16 v[156:159], v[40:43], v[56:59], 0
	v_mfma_f32_16x16x32_bf16 v[152:155], v[48:51], v[56:59], 0
	v_mfma_f32_16x16x32_bf16 v[140:143], v[40:43], v[72:75], 0
	v_mfma_f32_16x16x32_bf16 v[136:139], v[48:51], v[72:75], 0
	v_mfma_f32_16x16x32_bf16 v[124:127], v[40:43], v[182:185], 0
	v_mfma_f32_16x16x32_bf16 v[120:123], v[48:51], v[182:185], 0
	v_mfma_f32_16x16x32_bf16 v[108:111], v[40:43], v[196:199], 0
	v_mfma_f32_16x16x32_bf16 v[104:107], v[48:51], v[196:199], 0
	v_mfma_f32_16x16x32_bf16 v[156:159], v[44:47], v[60:63], v[156:159]
	v_mfma_f32_16x16x32_bf16 v[152:155], v[52:55], v[60:63], v[152:155]
	v_mfma_f32_16x16x32_bf16 v[140:143], v[44:47], v[84:87], v[140:143]
	v_mfma_f32_16x16x32_bf16 v[136:139], v[52:55], v[84:87], v[136:139]
	v_mfma_f32_16x16x32_bf16 v[124:127], v[44:47], v[186:189], v[124:127]
	v_mfma_f32_16x16x32_bf16 v[120:123], v[52:55], v[186:189], v[120:123]
	v_mfma_f32_16x16x32_bf16 v[108:111], v[44:47], v[200:203], v[108:111]
	v_mfma_f32_16x16x32_bf16 v[104:107], v[52:55], v[200:203], v[104:107]
	s_barrier
	s_add_i32 s24, s36, 0x10000
	ds_read_b128 v[204:207], v194 offset:16384
	ds_read_b128 v[208:211], v194 offset:17408
	ds_read_b128 v[212:215], v194 offset:18432
	ds_read_b128 v[216:219], v194 offset:19456
	s_mov_b32 m0, s24
	s_add_u32 s98, s8, 0x80
	s_addc_u32 s99, s9, 0
	global_load_lds_dwordx4 v168, s[8:9]
	s_add_i32 m0, s24, 0x2000
	s_nop 0
	global_load_lds_dwordx4 v164, s[8:9]
	s_barrier
	s_waitcnt lgkmcnt(0)
	v_mfma_f32_16x16x32_bf16 v[148:151], v[204:207], v[56:59], 0
	v_mfma_f32_16x16x32_bf16 v[56:59], v[212:215], v[56:59], 0
	v_mfma_f32_16x16x32_bf16 v[148:151], v[208:211], v[60:63], v[148:151]
	v_mfma_f32_16x16x32_bf16 v[56:59], v[216:219], v[60:63], v[56:59]
	v_mfma_f32_16x16x32_bf16 v[60:63], v[204:207], v[72:75], 0
	v_mfma_f32_16x16x32_bf16 v[72:75], v[212:215], v[72:75], 0
	v_mfma_f32_16x16x32_bf16 v[112:115], v[212:215], v[182:185], 0
	v_mfma_f32_16x16x32_bf16 v[100:103], v[204:207], v[196:199], 0
	v_mfma_f32_16x16x32_bf16 v[96:99], v[212:215], v[196:199], 0
	v_mfma_f32_16x16x32_bf16 v[60:63], v[208:211], v[84:87], v[60:63]
	v_mfma_f32_16x16x32_bf16 v[72:75], v[216:219], v[84:87], v[72:75]
	v_mfma_f32_16x16x32_bf16 v[84:87], v[204:207], v[182:185], 0
	v_mfma_f32_16x16x32_bf16 v[112:115], v[216:219], v[186:189], v[112:115]
	v_mfma_f32_16x16x32_bf16 v[100:103], v[208:211], v[200:203], v[100:103]
	v_mfma_f32_16x16x32_bf16 v[96:99], v[216:219], v[200:203], v[96:99]
	v_mfma_f32_16x16x32_bf16 v[84:87], v[208:211], v[186:189], v[84:87]
	s_mov_b32 m0, s37
	s_add_u32 s100, s26, 0x80
	s_addc_u32 s101, s27, 0
	s_barrier
	ds_read_b128 v[116:119], v195 offset:16384
	ds_read_b128 v[128:131], v195 offset:17408
	ds_read_b128 v[132:135], v195 offset:18432
	ds_read_b128 v[144:147], v195 offset:19456
	ds_read_b128 v[182:185], v195 offset:20480
	ds_read_b128 v[186:189], v195 offset:21504
	ds_read_b128 v[196:199], v195 offset:22528
	global_load_lds_dwordx4 v160, s[26:27]
	s_mov_b32 m0, s38
	ds_read_b128 v[200:203], v195 offset:23552
	global_load_lds_dwordx4 v162, s[26:27]
	s_barrier
	s_waitcnt lgkmcnt(0)
	v_mfma_f32_16x16x32_bf16 v[92:95], v[40:43], v[116:119], 0
	v_mfma_f32_16x16x32_bf16 v[88:91], v[48:51], v[116:119], 0
	v_mfma_f32_16x16x32_bf16 v[68:71], v[40:43], v[132:135], 0
	v_mfma_f32_16x16x32_bf16 v[64:67], v[48:51], v[132:135], 0
	v_mfma_f32_16x16x32_bf16 v[28:31], v[40:43], v[182:185], 0
	v_mfma_f32_16x16x32_bf16 v[24:27], v[48:51], v[182:185], 0
	v_mfma_f32_16x16x32_bf16 v[12:15], v[40:43], v[196:199], 0
	v_mfma_f32_16x16x32_bf16 v[8:11], v[48:51], v[196:199], 0
	v_mfma_f32_16x16x32_bf16 v[92:95], v[44:47], v[128:131], v[92:95]
	v_mfma_f32_16x16x32_bf16 v[88:91], v[52:55], v[128:131], v[88:91]
	v_mfma_f32_16x16x32_bf16 v[68:71], v[44:47], v[144:147], v[68:71]
	v_mfma_f32_16x16x32_bf16 v[64:67], v[52:55], v[144:147], v[64:67]
	v_mfma_f32_16x16x32_bf16 v[28:31], v[44:47], v[186:189], v[28:31]
	v_mfma_f32_16x16x32_bf16 v[24:27], v[52:55], v[186:189], v[24:27]
	v_mfma_f32_16x16x32_bf16 v[12:15], v[44:47], v[200:203], v[12:15]
	v_mfma_f32_16x16x32_bf16 v[8:11], v[52:55], v[200:203], v[8:11]
	s_barrier
	s_add_i32 s59, s36, 0x14000
	s_mov_b32 m0, s59
	s_add_u32 s24, s8, 0xb0000
	s_addc_u32 s25, s9, 0
	global_load_lds_dwordx4 v168, s[24:25]
	s_add_i32 m0, s59, 0x2000
	s_nop 0
	global_load_lds_dwordx4 v164, s[24:25]
	s_waitcnt vmcnt(6)
	s_barrier
	v_mfma_f32_16x16x32_bf16 v[36:39], v[204:207], v[132:135], 0
	v_mfma_f32_16x16x32_bf16 v[32:35], v[212:215], v[132:135], 0
	v_mfma_f32_16x16x32_bf16 v[20:23], v[204:207], v[182:185], 0
	v_mfma_f32_16x16x32_bf16 v[16:19], v[212:215], v[182:185], 0
	v_mfma_f32_16x16x32_bf16 v[4:7], v[204:207], v[196:199], 0
	v_mfma_f32_16x16x32_bf16 v[0:3], v[212:215], v[196:199], 0
	v_mfma_f32_16x16x32_bf16 v[40:43], v[204:207], v[116:119], 0
	v_mfma_f32_16x16x32_bf16 v[44:47], v[212:215], v[116:119], 0
	v_mfma_f32_16x16x32_bf16 v[36:39], v[208:211], v[144:147], v[36:39]
	v_mfma_f32_16x16x32_bf16 v[32:35], v[216:219], v[144:147], v[32:35]
	v_mfma_f32_16x16x32_bf16 v[20:23], v[208:211], v[186:189], v[20:23]
	v_mfma_f32_16x16x32_bf16 v[16:19], v[216:219], v[186:189], v[16:19]
	v_mfma_f32_16x16x32_bf16 v[4:7], v[208:211], v[200:203], v[4:7]
	v_mfma_f32_16x16x32_bf16 v[0:3], v[216:219], v[200:203], v[0:3]
	v_mfma_f32_16x16x32_bf16 v[40:43], v[208:211], v[128:131], v[40:43]
	v_mfma_f32_16x16x32_bf16 v[44:47], v[216:219], v[128:131], v[44:47]
	s_barrier
	ds_read_b128 v[48:51], v194 offset:32768
	ds_read_b128 v[52:55], v194 offset:33792
	ds_read_b128 v[76:79], v194 offset:34816
	ds_read_b128 v[80:83], v194 offset:35840
	s_add_u32 s24, s26, 0xb0000
	s_addc_u32 s25, s27, 0
	s_mov_b32 m0, s39
	ds_read_b128 v[116:119], v195 offset:32768
	ds_read_b128 v[128:131], v195 offset:33792
	ds_read_b128 v[182:185], v195 offset:34816
	ds_read_b128 v[186:189], v195 offset:35840
	ds_read_b128 v[196:199], v195 offset:36864
	ds_read_b128 v[200:203], v195 offset:37888
	ds_read_b128 v[204:207], v195 offset:38912
	global_load_lds_dwordx4 v160, s[24:25]
	s_mov_b32 m0, s40
	ds_read_b128 v[208:211], v195 offset:39936
	global_load_lds_dwordx4 v162, s[24:25]
	s_waitcnt lgkmcnt(8)
	s_barrier
	s_waitcnt lgkmcnt(0)
	v_mfma_f32_16x16x32_bf16 v[132:135], v[48:51], v[116:119], v[156:159]
	v_mfma_f32_16x16x32_bf16 v[156:159], v[52:55], v[128:131], v[132:135]
	v_mfma_f32_16x16x32_bf16 v[132:135], v[76:79], v[116:119], v[152:155]
	v_mfma_f32_16x16x32_bf16 v[152:155], v[80:83], v[128:131], v[132:135]
	v_mfma_f32_16x16x32_bf16 v[132:135], v[48:51], v[182:185], v[140:143]
	v_mfma_f32_16x16x32_bf16 v[140:143], v[52:55], v[186:189], v[132:135]
	v_mfma_f32_16x16x32_bf16 v[132:135], v[76:79], v[182:185], v[136:139]
	v_mfma_f32_16x16x32_bf16 v[124:127], v[48:51], v[196:199], v[124:127]
	v_mfma_f32_16x16x32_bf16 v[120:123], v[76:79], v[196:199], v[120:123]
	v_mfma_f32_16x16x32_bf16 v[108:111], v[48:51], v[204:207], v[108:111]
	v_mfma_f32_16x16x32_bf16 v[104:107], v[76:79], v[204:207], v[104:107]
	v_mfma_f32_16x16x32_bf16 v[136:139], v[80:83], v[186:189], v[132:135]
	v_mfma_f32_16x16x32_bf16 v[124:127], v[52:55], v[200:203], v[124:127]
	v_mfma_f32_16x16x32_bf16 v[120:123], v[80:83], v[200:203], v[120:123]
	v_mfma_f32_16x16x32_bf16 v[108:111], v[52:55], v[208:211], v[108:111]
	v_mfma_f32_16x16x32_bf16 v[104:107], v[80:83], v[208:211], v[104:107]
	s_barrier
	s_add_i32 s25, s36, 0x18000
	ds_read_b128 v[212:215], v194 offset:49152
	ds_read_b128 v[216:219], v194 offset:50176
	ds_read_b128 v[220:223], v194 offset:51200
	s_mov_b32 m0, s25
	ds_read_b128 v[236:239], v194 offset:52224
	global_load_lds_dwordx4 v168, s[98:99]
	s_add_i32 m0, s25, 0x2000
	s_nop 0
	global_load_lds_dwordx4 v164, s[98:99]
	s_barrier
	s_waitcnt lgkmcnt(0)
	v_mfma_f32_16x16x32_bf16 v[56:59], v[220:223], v[116:119], v[56:59]
	v_mfma_f32_16x16x32_bf16 v[132:135], v[212:215], v[116:119], v[148:151]
	v_mfma_f32_16x16x32_bf16 v[144:147], v[236:239], v[128:131], v[56:59]
	v_mfma_f32_16x16x32_bf16 v[56:59], v[212:215], v[182:185], v[60:63]
	v_mfma_f32_16x16x32_bf16 v[148:151], v[216:219], v[128:131], v[132:135]
	v_mfma_f32_16x16x32_bf16 v[132:135], v[216:219], v[186:189], v[56:59]
	v_mfma_f32_16x16x32_bf16 v[56:59], v[220:223], v[182:185], v[72:75]
	v_mfma_f32_16x16x32_bf16 v[128:131], v[236:239], v[186:189], v[56:59]
	v_mfma_f32_16x16x32_bf16 v[56:59], v[212:215], v[196:199], v[84:87]
	v_mfma_f32_16x16x32_bf16 v[116:119], v[216:219], v[200:203], v[56:59]
	v_mfma_f32_16x16x32_bf16 v[56:59], v[220:223], v[196:199], v[112:115]
	v_mfma_f32_16x16x32_bf16 v[112:115], v[236:239], v[200:203], v[56:59]
	v_mfma_f32_16x16x32_bf16 v[56:59], v[212:215], v[204:207], v[100:103]
	v_mfma_f32_16x16x32_bf16 v[100:103], v[216:219], v[208:211], v[56:59]
	v_mfma_f32_16x16x32_bf16 v[56:59], v[220:223], v[204:207], v[96:99]
	v_mfma_f32_16x16x32_bf16 v[96:99], v[236:239], v[208:211], v[56:59]
	s_mov_b32 m0, s47
	s_barrier
	s_nop 2
	ds_read_b128 v[56:59], v195 offset:49152
	ds_read_b128 v[60:63], v195 offset:50176
	ds_read_b128 v[72:75], v195 offset:51200
	ds_read_b128 v[84:87], v195 offset:52224
	ds_read_b128 v[182:185], v195 offset:53248
	ds_read_b128 v[186:189], v195 offset:54272
	ds_read_b128 v[196:199], v195 offset:55296
	global_load_lds_dwordx4 v160, s[100:101]
	s_mov_b32 m0, s49
	ds_read_b128 v[200:203], v195 offset:56320
	global_load_lds_dwordx4 v162, s[100:101]
	s_barrier
	s_waitcnt lgkmcnt(0)
	v_mfma_f32_16x16x32_bf16 v[92:95], v[48:51], v[56:59], v[92:95]
	v_mfma_f32_16x16x32_bf16 v[88:91], v[76:79], v[56:59], v[88:91]
	v_mfma_f32_16x16x32_bf16 v[68:71], v[48:51], v[72:75], v[68:71]
	v_mfma_f32_16x16x32_bf16 v[64:67], v[76:79], v[72:75], v[64:67]
	v_mfma_f32_16x16x32_bf16 v[28:31], v[48:51], v[182:185], v[28:31]
	v_mfma_f32_16x16x32_bf16 v[24:27], v[76:79], v[182:185], v[24:27]
	v_mfma_f32_16x16x32_bf16 v[12:15], v[48:51], v[196:199], v[12:15]
	v_mfma_f32_16x16x32_bf16 v[8:11], v[76:79], v[196:199], v[8:11]
	v_mfma_f32_16x16x32_bf16 v[92:95], v[52:55], v[60:63], v[92:95]
	v_mfma_f32_16x16x32_bf16 v[88:91], v[80:83], v[60:63], v[88:91]
	v_mfma_f32_16x16x32_bf16 v[68:71], v[52:55], v[84:87], v[68:71]
	v_mfma_f32_16x16x32_bf16 v[64:67], v[80:83], v[84:87], v[64:67]
	v_mfma_f32_16x16x32_bf16 v[28:31], v[52:55], v[186:189], v[28:31]
	v_mfma_f32_16x16x32_bf16 v[24:27], v[80:83], v[186:189], v[24:27]
	v_mfma_f32_16x16x32_bf16 v[12:15], v[52:55], v[200:203], v[12:15]
	v_mfma_f32_16x16x32_bf16 v[8:11], v[80:83], v[200:203], v[8:11]
	s_barrier
	s_add_i32 s24, s36, 0x1c000
	s_mov_b32 m0, s24
	s_add_u32 s8, s8, 0xb0080
	s_addc_u32 s9, s9, 0
	global_load_lds_dwordx4 v168, s[8:9]
	s_add_i32 m0, s24, 0x2000
	s_nop 0
	global_load_lds_dwordx4 v164, s[8:9]
	s_waitcnt vmcnt(6)
	s_barrier
	v_mfma_f32_16x16x32_bf16 v[40:43], v[212:215], v[56:59], v[40:43]
	v_mfma_f32_16x16x32_bf16 v[80:83], v[216:219], v[60:63], v[40:43]
	v_mfma_f32_16x16x32_bf16 v[40:43], v[220:223], v[56:59], v[44:47]
	v_mfma_f32_16x16x32_bf16 v[36:39], v[212:215], v[72:75], v[36:39]
	v_mfma_f32_16x16x32_bf16 v[32:35], v[220:223], v[72:75], v[32:35]
	v_mfma_f32_16x16x32_bf16 v[20:23], v[212:215], v[182:185], v[20:23]
	v_mfma_f32_16x16x32_bf16 v[16:19], v[220:223], v[182:185], v[16:19]
	v_mfma_f32_16x16x32_bf16 v[4:7], v[212:215], v[196:199], v[4:7]
	v_mfma_f32_16x16x32_bf16 v[0:3], v[220:223], v[196:199], v[0:3]
	v_mfma_f32_16x16x32_bf16 v[76:79], v[236:239], v[60:63], v[40:43]
	v_mfma_f32_16x16x32_bf16 v[36:39], v[216:219], v[84:87], v[36:39]
	v_mfma_f32_16x16x32_bf16 v[32:35], v[236:239], v[84:87], v[32:35]
	v_mfma_f32_16x16x32_bf16 v[20:23], v[216:219], v[186:189], v[20:23]
	v_mfma_f32_16x16x32_bf16 v[16:19], v[236:239], v[186:189], v[16:19]
	v_mfma_f32_16x16x32_bf16 v[4:7], v[216:219], v[200:203], v[4:7]
	v_mfma_f32_16x16x32_bf16 v[0:3], v[236:239], v[200:203], v[0:3]
	s_add_i32 s58, s58, 2
	s_add_u32 s56, s56, 0x100
	s_addc_u32 s57, s57, 0
	s_cmp_gt_u32 s58, 41
	s_mov_b64 s[24:25], s[2:3]
	s_barrier
.LBB0_1049:
	s_add_u32 s2, s24, 0x100
	s_addc_u32 s3, s25, 0
	ds_read_b128 v[40:43], v194
	ds_read_b128 v[44:47], v194 offset:1024
	ds_read_b128 v[48:51], v194 offset:2048
	ds_read_b128 v[52:55], v194 offset:3072
	s_cmp_eq_u32 s58, 40
	s_cselect_b32 s27, s1, s3
	s_cselect_b32 s26, s0, s2
	s_cselect_b32 s9, s23, s57
	s_cselect_b32 s8, s22, s56
	s_add_i32 m0, s37, 0xc000
	ds_read_b128 v[56:59], v195
	ds_read_b128 v[60:63], v195 offset:1024
	ds_read_b128 v[72:75], v195 offset:2048
	ds_read_b128 v[84:87], v195 offset:3072
	ds_read_b128 v[182:185], v195 offset:4096
	ds_read_b128 v[186:189], v195 offset:5120
	ds_read_b128 v[196:199], v195 offset:6144
	global_load_lds_dwordx4 v166, s[24:25]
	s_add_i32 m0, s37, 0xe000
	ds_read_b128 v[200:203], v195 offset:7168
	global_load_lds_dwordx4 v180, s[24:25]
	s_waitcnt lgkmcnt(8)
	s_barrier
	s_waitcnt lgkmcnt(0)
	v_mfma_f32_16x16x32_bf16 v[156:159], v[40:43], v[56:59], v[156:159]
	v_mfma_f32_16x16x32_bf16 v[152:155], v[48:51], v[56:59], v[152:155]
	v_mfma_f32_16x16x32_bf16 v[140:143], v[40:43], v[72:75], v[140:143]
	v_mfma_f32_16x16x32_bf16 v[136:139], v[48:51], v[72:75], v[136:139]
	v_mfma_f32_16x16x32_bf16 v[124:127], v[40:43], v[182:185], v[124:127]
	v_mfma_f32_16x16x32_bf16 v[120:123], v[48:51], v[182:185], v[120:123]
	v_mfma_f32_16x16x32_bf16 v[108:111], v[40:43], v[196:199], v[108:111]
	v_mfma_f32_16x16x32_bf16 v[104:107], v[48:51], v[196:199], v[104:107]
	v_mfma_f32_16x16x32_bf16 v[156:159], v[44:47], v[60:63], v[156:159]
	v_mfma_f32_16x16x32_bf16 v[152:155], v[52:55], v[60:63], v[152:155]
	v_mfma_f32_16x16x32_bf16 v[140:143], v[44:47], v[84:87], v[140:143]
	v_mfma_f32_16x16x32_bf16 v[136:139], v[52:55], v[84:87], v[136:139]
	v_mfma_f32_16x16x32_bf16 v[124:127], v[44:47], v[186:189], v[124:127]
	v_mfma_f32_16x16x32_bf16 v[120:123], v[52:55], v[186:189], v[120:123]
	v_mfma_f32_16x16x32_bf16 v[108:111], v[44:47], v[200:203], v[108:111]
	v_mfma_f32_16x16x32_bf16 v[104:107], v[52:55], v[200:203], v[104:107]
	s_barrier
	s_add_i32 s24, s36, 0x10000
	ds_read_b128 v[204:207], v194 offset:16384
	ds_read_b128 v[208:211], v194 offset:17408
	ds_read_b128 v[212:215], v194 offset:18432
	ds_read_b128 v[216:219], v194 offset:19456
	s_mov_b32 m0, s24
	s_add_u32 s98, s8, 0x80
	s_addc_u32 s99, s9, 0
	global_load_lds_dwordx4 v168, s[8:9]
	s_add_i32 m0, s24, 0x2000
	s_nop 0
	global_load_lds_dwordx4 v164, s[8:9]
	s_barrier
	s_waitcnt lgkmcnt(0)
	v_mfma_f32_16x16x32_bf16 v[148:151], v[204:207], v[56:59], v[148:151]
	v_mfma_f32_16x16x32_bf16 v[56:59], v[212:215], v[56:59], v[144:147]
	v_mfma_f32_16x16x32_bf16 v[148:151], v[208:211], v[60:63], v[148:151]
	v_mfma_f32_16x16x32_bf16 v[56:59], v[216:219], v[60:63], v[56:59]
	v_mfma_f32_16x16x32_bf16 v[60:63], v[204:207], v[72:75], v[132:135]
	v_mfma_f32_16x16x32_bf16 v[72:75], v[212:215], v[72:75], v[128:131]
	v_mfma_f32_16x16x32_bf16 v[112:115], v[212:215], v[182:185], v[112:115]
	v_mfma_f32_16x16x32_bf16 v[100:103], v[204:207], v[196:199], v[100:103]
	v_mfma_f32_16x16x32_bf16 v[96:99], v[212:215], v[196:199], v[96:99]
	v_mfma_f32_16x16x32_bf16 v[60:63], v[208:211], v[84:87], v[60:63]
	v_mfma_f32_16x16x32_bf16 v[72:75], v[216:219], v[84:87], v[72:75]
	v_mfma_f32_16x16x32_bf16 v[84:87], v[204:207], v[182:185], v[116:119]
	v_mfma_f32_16x16x32_bf16 v[112:115], v[216:219], v[186:189], v[112:115]
	v_mfma_f32_16x16x32_bf16 v[100:103], v[208:211], v[200:203], v[100:103]
	v_mfma_f32_16x16x32_bf16 v[96:99], v[216:219], v[200:203], v[96:99]
	v_mfma_f32_16x16x32_bf16 v[84:87], v[208:211], v[186:189], v[84:87]
	s_mov_b32 m0, s37
	s_add_u32 s100, s26, 0x80
	s_addc_u32 s101, s27, 0
	s_barrier
	ds_read_b128 v[116:119], v195 offset:16384
	ds_read_b128 v[128:131], v195 offset:17408
	ds_read_b128 v[132:135], v195 offset:18432
	ds_read_b128 v[144:147], v195 offset:19456
	ds_read_b128 v[182:185], v195 offset:20480
	ds_read_b128 v[186:189], v195 offset:21504
	ds_read_b128 v[196:199], v195 offset:22528
	global_load_lds_dwordx4 v160, s[26:27]
	s_mov_b32 m0, s38
	ds_read_b128 v[200:203], v195 offset:23552
	global_load_lds_dwordx4 v162, s[26:27]
	s_barrier
	s_waitcnt lgkmcnt(0)
	v_mfma_f32_16x16x32_bf16 v[92:95], v[40:43], v[116:119], v[92:95]
	v_mfma_f32_16x16x32_bf16 v[88:91], v[48:51], v[116:119], v[88:91]
	v_mfma_f32_16x16x32_bf16 v[68:71], v[40:43], v[132:135], v[68:71]
	v_mfma_f32_16x16x32_bf16 v[64:67], v[48:51], v[132:135], v[64:67]
	v_mfma_f32_16x16x32_bf16 v[28:31], v[40:43], v[182:185], v[28:31]
	v_mfma_f32_16x16x32_bf16 v[24:27], v[48:51], v[182:185], v[24:27]
	v_mfma_f32_16x16x32_bf16 v[12:15], v[40:43], v[196:199], v[12:15]
	v_mfma_f32_16x16x32_bf16 v[8:11], v[48:51], v[196:199], v[8:11]
	v_mfma_f32_16x16x32_bf16 v[92:95], v[44:47], v[128:131], v[92:95]
	v_mfma_f32_16x16x32_bf16 v[88:91], v[52:55], v[128:131], v[88:91]
	v_mfma_f32_16x16x32_bf16 v[68:71], v[44:47], v[144:147], v[68:71]
	v_mfma_f32_16x16x32_bf16 v[64:67], v[52:55], v[144:147], v[64:67]
	v_mfma_f32_16x16x32_bf16 v[28:31], v[44:47], v[186:189], v[28:31]
	v_mfma_f32_16x16x32_bf16 v[24:27], v[52:55], v[186:189], v[24:27]
	v_mfma_f32_16x16x32_bf16 v[12:15], v[44:47], v[200:203], v[12:15]
	v_mfma_f32_16x16x32_bf16 v[8:11], v[52:55], v[200:203], v[8:11]
	s_barrier
	s_add_i32 s59, s36, 0x14000
	s_mov_b32 m0, s59
	s_add_u32 s24, s8, 0xb0000
	s_addc_u32 s25, s9, 0
	global_load_lds_dwordx4 v168, s[24:25]
	s_add_i32 m0, s59, 0x2000
	s_nop 0
	global_load_lds_dwordx4 v164, s[24:25]
	s_waitcnt vmcnt(6)
	s_barrier
	v_mfma_f32_16x16x32_bf16 v[36:39], v[204:207], v[132:135], v[36:39]
	v_mfma_f32_16x16x32_bf16 v[32:35], v[212:215], v[132:135], v[32:35]
	v_mfma_f32_16x16x32_bf16 v[20:23], v[204:207], v[182:185], v[20:23]
	v_mfma_f32_16x16x32_bf16 v[16:19], v[212:215], v[182:185], v[16:19]
	v_mfma_f32_16x16x32_bf16 v[4:7], v[204:207], v[196:199], v[4:7]
	v_mfma_f32_16x16x32_bf16 v[0:3], v[212:215], v[196:199], v[0:3]
	v_mfma_f32_16x16x32_bf16 v[40:43], v[204:207], v[116:119], v[80:83]
	v_mfma_f32_16x16x32_bf16 v[44:47], v[212:215], v[116:119], v[76:79]
	v_mfma_f32_16x16x32_bf16 v[36:39], v[208:211], v[144:147], v[36:39]
	v_mfma_f32_16x16x32_bf16 v[32:35], v[216:219], v[144:147], v[32:35]
	v_mfma_f32_16x16x32_bf16 v[20:23], v[208:211], v[186:189], v[20:23]
	v_mfma_f32_16x16x32_bf16 v[16:19], v[216:219], v[186:189], v[16:19]
	v_mfma_f32_16x16x32_bf16 v[4:7], v[208:211], v[200:203], v[4:7]
	v_mfma_f32_16x16x32_bf16 v[0:3], v[216:219], v[200:203], v[0:3]
	v_mfma_f32_16x16x32_bf16 v[40:43], v[208:211], v[128:131], v[40:43]
	v_mfma_f32_16x16x32_bf16 v[44:47], v[216:219], v[128:131], v[44:47]
	s_barrier
	ds_read_b128 v[48:51], v194 offset:32768
	ds_read_b128 v[52:55], v194 offset:33792
	ds_read_b128 v[76:79], v194 offset:34816
	ds_read_b128 v[80:83], v194 offset:35840
	s_add_u32 s24, s26, 0xb0000
	s_addc_u32 s25, s27, 0
	s_mov_b32 m0, s39
	ds_read_b128 v[116:119], v195 offset:32768
	ds_read_b128 v[128:131], v195 offset:33792
	ds_read_b128 v[182:185], v195 offset:34816
	ds_read_b128 v[186:189], v195 offset:35840
	ds_read_b128 v[196:199], v195 offset:36864
	ds_read_b128 v[200:203], v195 offset:37888
	ds_read_b128 v[204:207], v195 offset:38912
	global_load_lds_dwordx4 v160, s[24:25]
	s_mov_b32 m0, s40
	ds_read_b128 v[208:211], v195 offset:39936
	global_load_lds_dwordx4 v162, s[24:25]
	s_waitcnt lgkmcnt(8)
	s_barrier
	s_waitcnt lgkmcnt(0)
	v_mfma_f32_16x16x32_bf16 v[132:135], v[48:51], v[116:119], v[156:159]
	v_mfma_f32_16x16x32_bf16 v[156:159], v[52:55], v[128:131], v[132:135]
	v_mfma_f32_16x16x32_bf16 v[132:135], v[76:79], v[116:119], v[152:155]
	v_mfma_f32_16x16x32_bf16 v[152:155], v[80:83], v[128:131], v[132:135]
	v_mfma_f32_16x16x32_bf16 v[132:135], v[48:51], v[182:185], v[140:143]
	v_mfma_f32_16x16x32_bf16 v[140:143], v[52:55], v[186:189], v[132:135]
	v_mfma_f32_16x16x32_bf16 v[132:135], v[76:79], v[182:185], v[136:139]
	v_mfma_f32_16x16x32_bf16 v[124:127], v[48:51], v[196:199], v[124:127]
	v_mfma_f32_16x16x32_bf16 v[120:123], v[76:79], v[196:199], v[120:123]
	v_mfma_f32_16x16x32_bf16 v[108:111], v[48:51], v[204:207], v[108:111]
	v_mfma_f32_16x16x32_bf16 v[104:107], v[76:79], v[204:207], v[104:107]
	v_mfma_f32_16x16x32_bf16 v[136:139], v[80:83], v[186:189], v[132:135]
	v_mfma_f32_16x16x32_bf16 v[124:127], v[52:55], v[200:203], v[124:127]
	v_mfma_f32_16x16x32_bf16 v[120:123], v[80:83], v[200:203], v[120:123]
	v_mfma_f32_16x16x32_bf16 v[108:111], v[52:55], v[208:211], v[108:111]
	v_mfma_f32_16x16x32_bf16 v[104:107], v[80:83], v[208:211], v[104:107]
	s_barrier
	s_add_i32 s25, s36, 0x18000
	ds_read_b128 v[212:215], v194 offset:49152
	ds_read_b128 v[216:219], v194 offset:50176
	ds_read_b128 v[220:223], v194 offset:51200
	s_mov_b32 m0, s25
	ds_read_b128 v[236:239], v194 offset:52224
	global_load_lds_dwordx4 v168, s[98:99]
	s_add_i32 m0, s25, 0x2000
	s_nop 0
	global_load_lds_dwordx4 v164, s[98:99]
	s_barrier
	s_waitcnt lgkmcnt(0)
	v_mfma_f32_16x16x32_bf16 v[56:59], v[220:223], v[116:119], v[56:59]
	v_mfma_f32_16x16x32_bf16 v[132:135], v[212:215], v[116:119], v[148:151]
	v_mfma_f32_16x16x32_bf16 v[144:147], v[236:239], v[128:131], v[56:59]
	v_mfma_f32_16x16x32_bf16 v[56:59], v[212:215], v[182:185], v[60:63]
	v_mfma_f32_16x16x32_bf16 v[148:151], v[216:219], v[128:131], v[132:135]
	v_mfma_f32_16x16x32_bf16 v[132:135], v[216:219], v[186:189], v[56:59]
	v_mfma_f32_16x16x32_bf16 v[56:59], v[220:223], v[182:185], v[72:75]
	v_mfma_f32_16x16x32_bf16 v[128:131], v[236:239], v[186:189], v[56:59]
	v_mfma_f32_16x16x32_bf16 v[56:59], v[212:215], v[196:199], v[84:87]
	v_mfma_f32_16x16x32_bf16 v[116:119], v[216:219], v[200:203], v[56:59]
	v_mfma_f32_16x16x32_bf16 v[56:59], v[220:223], v[196:199], v[112:115]
	v_mfma_f32_16x16x32_bf16 v[112:115], v[236:239], v[200:203], v[56:59]
	v_mfma_f32_16x16x32_bf16 v[56:59], v[212:215], v[204:207], v[100:103]
	v_mfma_f32_16x16x32_bf16 v[100:103], v[216:219], v[208:211], v[56:59]
	v_mfma_f32_16x16x32_bf16 v[56:59], v[220:223], v[204:207], v[96:99]
	v_mfma_f32_16x16x32_bf16 v[96:99], v[236:239], v[208:211], v[56:59]
	s_mov_b32 m0, s47
	s_barrier
	s_nop 2
	ds_read_b128 v[56:59], v195 offset:49152
	ds_read_b128 v[60:63], v195 offset:50176
	ds_read_b128 v[72:75], v195 offset:51200
	ds_read_b128 v[84:87], v195 offset:52224
	ds_read_b128 v[182:185], v195 offset:53248
	ds_read_b128 v[186:189], v195 offset:54272
	ds_read_b128 v[196:199], v195 offset:55296
	global_load_lds_dwordx4 v160, s[100:101]
	s_mov_b32 m0, s49
	ds_read_b128 v[200:203], v195 offset:56320
	global_load_lds_dwordx4 v162, s[100:101]
	s_barrier
	s_waitcnt lgkmcnt(0)
	v_mfma_f32_16x16x32_bf16 v[92:95], v[48:51], v[56:59], v[92:95]
	v_mfma_f32_16x16x32_bf16 v[88:91], v[76:79], v[56:59], v[88:91]
	v_mfma_f32_16x16x32_bf16 v[68:71], v[48:51], v[72:75], v[68:71]
	v_mfma_f32_16x16x32_bf16 v[64:67], v[76:79], v[72:75], v[64:67]
	v_mfma_f32_16x16x32_bf16 v[28:31], v[48:51], v[182:185], v[28:31]
	v_mfma_f32_16x16x32_bf16 v[24:27], v[76:79], v[182:185], v[24:27]
	v_mfma_f32_16x16x32_bf16 v[12:15], v[48:51], v[196:199], v[12:15]
	v_mfma_f32_16x16x32_bf16 v[8:11], v[76:79], v[196:199], v[8:11]
	v_mfma_f32_16x16x32_bf16 v[92:95], v[52:55], v[60:63], v[92:95]
	v_mfma_f32_16x16x32_bf16 v[88:91], v[80:83], v[60:63], v[88:91]
	v_mfma_f32_16x16x32_bf16 v[68:71], v[52:55], v[84:87], v[68:71]
	v_mfma_f32_16x16x32_bf16 v[64:67], v[80:83], v[84:87], v[64:67]
	v_mfma_f32_16x16x32_bf16 v[28:31], v[52:55], v[186:189], v[28:31]
	v_mfma_f32_16x16x32_bf16 v[24:27], v[80:83], v[186:189], v[24:27]
	v_mfma_f32_16x16x32_bf16 v[12:15], v[52:55], v[200:203], v[12:15]
	v_mfma_f32_16x16x32_bf16 v[8:11], v[80:83], v[200:203], v[8:11]
	s_barrier
	s_add_i32 s24, s36, 0x1c000
	s_mov_b32 m0, s24
	s_add_u32 s8, s8, 0xb0080
	s_addc_u32 s9, s9, 0
	global_load_lds_dwordx4 v168, s[8:9]
	s_add_i32 m0, s24, 0x2000
	s_nop 0
	global_load_lds_dwordx4 v164, s[8:9]
	s_waitcnt vmcnt(6)
	s_barrier
	v_mfma_f32_16x16x32_bf16 v[40:43], v[212:215], v[56:59], v[40:43]
	v_mfma_f32_16x16x32_bf16 v[80:83], v[216:219], v[60:63], v[40:43]
	v_mfma_f32_16x16x32_bf16 v[40:43], v[220:223], v[56:59], v[44:47]
	v_mfma_f32_16x16x32_bf16 v[36:39], v[212:215], v[72:75], v[36:39]
	v_mfma_f32_16x16x32_bf16 v[32:35], v[220:223], v[72:75], v[32:35]
	v_mfma_f32_16x16x32_bf16 v[20:23], v[212:215], v[182:185], v[20:23]
	v_mfma_f32_16x16x32_bf16 v[16:19], v[220:223], v[182:185], v[16:19]
	v_mfma_f32_16x16x32_bf16 v[4:7], v[212:215], v[196:199], v[4:7]
	v_mfma_f32_16x16x32_bf16 v[0:3], v[220:223], v[196:199], v[0:3]
	v_mfma_f32_16x16x32_bf16 v[76:79], v[236:239], v[60:63], v[40:43]
	v_mfma_f32_16x16x32_bf16 v[36:39], v[216:219], v[84:87], v[36:39]
	v_mfma_f32_16x16x32_bf16 v[32:35], v[236:239], v[84:87], v[32:35]
	v_mfma_f32_16x16x32_bf16 v[20:23], v[216:219], v[186:189], v[20:23]
	v_mfma_f32_16x16x32_bf16 v[16:19], v[236:239], v[186:189], v[16:19]
	v_mfma_f32_16x16x32_bf16 v[4:7], v[216:219], v[200:203], v[4:7]
	v_mfma_f32_16x16x32_bf16 v[0:3], v[236:239], v[200:203], v[0:3]
	s_add_i32 s58, s58, 2
	s_add_u32 s56, s56, 0x100
	s_addc_u32 s57, s57, 0
	s_cmp_gt_u32 s58, 41
	s_mov_b64 s[24:25], s[2:3]
	s_barrier
	s_cbranch_scc0 .LBB0_1049
	s_lshl_b32 s2, s55, 8
	v_mov_b32_e32 v186, v193
	v_mov_b32_e32 v196, v192
	s_or_b32 s2, s2, s46
	v_mov_b32_e32 v52, 0
	v_lshl_add_u32 v182, v196, 3, s2
	s_add_i32 s2, s54, -16
	s_lshr_b32 s2, s2, 3
	s_add_i32 s2, s2, 1
	s_cmp_gt_i32 s54, 15
	s_cselect_b32 s8, s2, 0
	s_mul_i32 s96, s8, 0x1800
	s_lshl_b64 s[2:3], s[96:97], 2
	s_add_u32 s2, s41, s2
	v_ashrrev_i32_e32 v183, 31, v182
	s_addc_u32 s3, s42, s3
	v_lshlrev_b64 v[40:41], 2, v[182:183]
	v_lshl_add_u64 v[42:43], s[2:3], 0, v[40:41]
	global_load_dwordx4 v[72:75], v[42:43], off
	s_lshl_b32 s96, s8, 10
	s_lshl_b64 s[2:3], s[96:97], 2
	s_add_u32 s2, s43, s2
	s_addc_u32 s3, s44, s3
	v_lshl_add_u64 v[184:185], s[2:3], 0, v[40:41]
	s_and_b64 vcc, exec, s[4:5]
	v_mov_b32_e32 v60, 0
	v_mov_b32_e32 v61, v52
	v_mov_b32_e32 v62, 0
	v_mov_b32_e32 v63, 0
	s_cbranch_vccnz .LBB0_1052
	global_load_dwordx4 v[60:63], v[184:185], off
